# K-loops: 8 of 16 LDS-DMA per two K-tiles use the SGPR-base form (vOff, s[base]) and their v_lshl_add_u64 address VALU is deleted
# speedup vs baseline: 1.0029x; 1.0029x over previous
; #define PG8_STAGE(bufoff, gbase, voff) do { _Pragma("unroll") for (int _i = 0; _i < 2; ++_i) \
;         __builtin_amdgcn_global_load_lds((const unsigned*)((const char*)(gbase) + (voff)[_i]), (PG8_LAS unsigned*)(lds + (bufoff) + ldsw + _i * 8192), 16, 0, 0); } while (0)
; #define PG8_LDA(dst, b, h) do { _Pragma("unroll") for (int m = 0; m < 4; ++m) _Pragma("unroll") for (int k = 0; k < 2; ++k) dst[m][k] = *(const PG8_LAS bf16x8*)(lds + PG8_SA(b, h) + aoff + m * 2048 + k * 1024); } while (0)
; #define PG8_LDB(dst, b, h) do { _Pragma("unroll") for (int n = 0; n < 2; ++n) _Pragma("unroll") for (int k = 0; k < 2; ++k) dst[n][k] = *(const PG8_LAS bf16x8*)(lds + PG8_SB(b, h) + boff + n * 2048 + k * 1024); } while (0)
; #define PG8_MMA(ai, bj, At, Bt) do { __builtin_amdgcn_s_setprio(1); _Pragma("unroll") for (int m = 0; m < 4; ++m) _Pragma("unroll") for (int n = 0; n < 2; ++n) _Pragma("unroll") for (int k = 0; k < 2; ++k) \
;         acc[ai][bj][m][n] = __builtin_amdgcn_mfma_f32_16x16x32_bf16(Bt[n][k], At[m][k], acc[ai][bj][m][n], 0, 0, 0); __builtin_amdgcn_s_setprio(0); } while (0)
; #define PG8_WAIT_V(n) asm volatile("s_waitcnt vmcnt(" #n ")" ::: "memory")
; #define PG8_WAIT_L(n) asm volatile("s_waitcnt lgkmcnt(" #n ")" ::: "memory")
; #define PG8_BAR __builtin_amdgcn_s_barrier()
; #define PG8_SCHED __builtin_amdgcn_sched_barrier(0)
; template <class Epi, class Sched, bool ALIGN_EPI = false, bool SP2 = false>
; __device__ __forceinline__ void gemm_phase(PG8_LAS unsigned char* lds, const Gemm g, const Sched& S, const Epi& E) {
;     ...
;             PG8_LDB(B0, 0, 0); PG8_LDB(B1, 0, 1); PG8_SCHED; PG8_LDA(At, 0, 0); PG8_STAGE(PG8_SA(1, 1), a1 + hstep, voffA);
;             PG8_WAIT_V(8); PG8_WAIT_L(0); PG8_BAR; PG8_MMA(0, 0, At, B0); PG8_MMA(0, 1, At, B1); PG8_BAR; PG8_SCHED;
;             PG8_LDA(At, 0, 1); PG8_STAGE(PG8_SB(0, 0), b2, voffB); PG8_STAGE(PG8_SB(0, 1), b2 + hstep, voffB); PG8_STAGE(PG8_SA(0, 0), a2, voffA);
;             PG8_WAIT_V(8); PG8_WAIT_L(0); PG8_BAR; PG8_MMA(1, 0, At, B0); PG8_MMA(1, 1, At, B1); PG8_BAR; PG8_SCHED;
.LBB0_234:
	ds_read_b128 v[144:147], v160
	ds_read_b128 v[164:167], v160 offset:1024
	ds_read_b128 v[168:171], v160 offset:2048
	ds_read_b128 v[172:175], v160 offset:3072
	ds_read_b128 v[176:179], v161
	ds_read_b128 v[180:183], v161 offset:1024
	ds_read_b128 v[184:187], v161 offset:2048
	ds_read_b128 v[188:191], v161 offset:3072
	s_add_u32 s6, s58, 0xfffc0080
	s_addc_u32 s7, s59, -1
	s_cmp_eq_u32 s85, 12
	s_cselect_b32 s11, s45, s7
	s_cselect_b32 s10, s81, s6
	s_cselect_b32 s7, s35, s84
	s_cselect_b32 s6, s82, s83
	s_add_i32 m0, s57, 0xc000
	ds_read_b128 v[192:195], v162
	ds_read_b128 v[196:199], v162 offset:1024
	ds_read_b128 v[200:203], v162 offset:2048
	ds_read_b128 v[204:207], v162 offset:3072
	ds_read_b128 v[208:211], v162 offset:4096
	ds_read_b128 v[212:215], v162 offset:5120
	ds_read_b128 v[216:219], v162 offset:6144
	ds_read_b128 v[222:225], v162 offset:7168
	global_load_lds_dwordx4 v136, s[58:59]
	s_add_i32 m0, s57, 0xe000
	s_nop 0
	global_load_lds_dwordx4 v138, s[58:59]
	s_waitcnt vmcnt(8)
	s_waitcnt lgkmcnt(0)
	s_barrier
	s_waitcnt lgkmcnt(0)
	v_mfma_f32_16x16x32_bf16 v[124:127], v[144:147], v[192:195], v[124:127]
	v_mfma_f32_16x16x32_bf16 v[120:123], v[168:171], v[192:195], v[120:123]
	v_mfma_f32_16x16x32_bf16 v[108:111], v[144:147], v[200:203], v[108:111]
	v_mfma_f32_16x16x32_bf16 v[104:107], v[168:171], v[200:203], v[104:107]
	v_mfma_f32_16x16x32_bf16 v[92:95], v[144:147], v[208:211], v[92:95]
	v_mfma_f32_16x16x32_bf16 v[88:91], v[168:171], v[208:211], v[88:91]
	v_mfma_f32_16x16x32_bf16 v[76:79], v[144:147], v[216:219], v[76:79]
	v_mfma_f32_16x16x32_bf16 v[72:75], v[168:171], v[216:219], v[72:75]
	v_mfma_f32_16x16x32_bf16 v[124:127], v[164:167], v[196:199], v[124:127]
	v_mfma_f32_16x16x32_bf16 v[120:123], v[172:175], v[196:199], v[120:123]
	v_mfma_f32_16x16x32_bf16 v[108:111], v[164:167], v[204:207], v[108:111]
	v_mfma_f32_16x16x32_bf16 v[104:107], v[172:175], v[204:207], v[104:107]
	v_mfma_f32_16x16x32_bf16 v[92:95], v[164:167], v[212:215], v[92:95]
	v_mfma_f32_16x16x32_bf16 v[88:91], v[172:175], v[212:215], v[88:91]
	v_mfma_f32_16x16x32_bf16 v[76:79], v[164:167], v[222:225], v[76:79]
	v_mfma_f32_16x16x32_bf16 v[72:75], v[172:175], v[222:225], v[72:75]
	v_mfma_f32_16x16x32_bf16 v[116:119], v[176:179], v[192:195], v[116:119]
	v_mfma_f32_16x16x32_bf16 v[112:115], v[184:187], v[192:195], v[112:115]
	v_mfma_f32_16x16x32_bf16 v[100:103], v[176:179], v[200:203], v[100:103]
	v_mfma_f32_16x16x32_bf16 v[96:99], v[184:187], v[200:203], v[96:99]
	v_mfma_f32_16x16x32_bf16 v[84:87], v[176:179], v[208:211], v[84:87]
	v_mfma_f32_16x16x32_bf16 v[80:83], v[184:187], v[208:211], v[80:83]
	v_mfma_f32_16x16x32_bf16 v[68:71], v[176:179], v[216:219], v[68:71]
	v_mfma_f32_16x16x32_bf16 v[64:67], v[184:187], v[216:219], v[64:67]
	v_mfma_f32_16x16x32_bf16 v[116:119], v[180:183], v[196:199], v[116:119]
	v_mfma_f32_16x16x32_bf16 v[112:115], v[188:191], v[196:199], v[112:115]
	v_mfma_f32_16x16x32_bf16 v[100:103], v[180:183], v[204:207], v[100:103]
	v_mfma_f32_16x16x32_bf16 v[96:99], v[188:191], v[204:207], v[96:99]
	v_mfma_f32_16x16x32_bf16 v[84:87], v[180:183], v[212:215], v[84:87]
	v_mfma_f32_16x16x32_bf16 v[80:83], v[188:191], v[212:215], v[80:83]
	v_mfma_f32_16x16x32_bf16 v[68:71], v[180:183], v[222:225], v[68:71]
	v_mfma_f32_16x16x32_bf16 v[64:67], v[188:191], v[222:225], v[64:67]
	s_barrier
	s_add_i32 s86, s77, s3
	v_lshl_add_u64 v[226:227], s[6:7], 0, v[132:133]
	s_mov_b32 m0, s86
	ds_read_b128 v[192:195], v162 offset:16384
	ds_read_b128 v[196:199], v162 offset:17408
	ds_read_b128 v[200:203], v162 offset:18432
	ds_read_b128 v[204:207], v162 offset:19456
	ds_read_b128 v[208:211], v162 offset:20480
	ds_read_b128 v[212:215], v162 offset:21504
	ds_read_b128 v[216:219], v162 offset:22528
	ds_read_b128 v[222:225], v162 offset:23552
	global_load_lds_dwordx4 v[226:227], off
	s_add_i32 m0, s86, 0x2000
	s_add_u32 s86, s6, 0x40000
	v_lshl_add_u64 v[228:229], s[6:7], 0, v[128:129]
	s_addc_u32 s87, s7, 0
	s_add_i32 s88, s78, s3
	global_load_lds_dwordx4 v[228:229], off
	s_mov_b32 m0, s88
	v_lshl_add_u64 v[232:233], s[10:11], 0, v[130:131]
	global_load_lds_dwordx4 v132, s[86:87]
	s_add_i32 m0, s88, 0x2000
	s_nop 0
	global_load_lds_dwordx4 v128, s[86:87]
	v_lshl_add_u64 v[230:231], s[10:11], 0, v[134:135]
	s_mov_b32 m0, s57
	s_nop 0
	global_load_lds_dwordx4 v[230:231], off
	s_mov_b32 m0, s61
	s_nop 0
	global_load_lds_dwordx4 v[232:233], off
	s_waitcnt vmcnt(8)
	s_waitcnt lgkmcnt(0)
	s_barrier
	s_waitcnt lgkmcnt(0)
	v_mfma_f32_16x16x32_bf16 v[60:63], v[144:147], v[192:195], v[60:63]
	v_mfma_f32_16x16x32_bf16 v[56:59], v[168:171], v[192:195], v[56:59]
	v_mfma_f32_16x16x32_bf16 v[44:47], v[144:147], v[200:203], v[44:47]
	v_mfma_f32_16x16x32_bf16 v[40:43], v[168:171], v[200:203], v[40:43]
	v_mfma_f32_16x16x32_bf16 v[28:31], v[144:147], v[208:211], v[28:31]
	v_mfma_f32_16x16x32_bf16 v[24:27], v[168:171], v[208:211], v[24:27]
	v_mfma_f32_16x16x32_bf16 v[12:15], v[144:147], v[216:219], v[12:15]
	v_mfma_f32_16x16x32_bf16 v[8:11], v[168:171], v[216:219], v[8:11]
	v_mfma_f32_16x16x32_bf16 v[60:63], v[164:167], v[196:199], v[60:63]
	v_mfma_f32_16x16x32_bf16 v[56:59], v[172:175], v[196:199], v[56:59]
	v_mfma_f32_16x16x32_bf16 v[44:47], v[164:167], v[204:207], v[44:47]
	v_mfma_f32_16x16x32_bf16 v[40:43], v[172:175], v[204:207], v[40:43]
	v_mfma_f32_16x16x32_bf16 v[28:31], v[164:167], v[212:215], v[28:31]
	v_mfma_f32_16x16x32_bf16 v[24:27], v[172:175], v[212:215], v[24:27]
	v_mfma_f32_16x16x32_bf16 v[12:15], v[164:167], v[222:225], v[12:15]
	v_mfma_f32_16x16x32_bf16 v[8:11], v[172:175], v[222:225], v[8:11]
	v_mfma_f32_16x16x32_bf16 v[52:55], v[176:179], v[192:195], v[52:55]
	v_mfma_f32_16x16x32_bf16 v[48:51], v[184:187], v[192:195], v[48:51]
	v_mfma_f32_16x16x32_bf16 v[36:39], v[176:179], v[200:203], v[36:39]
	v_mfma_f32_16x16x32_bf16 v[32:35], v[184:187], v[200:203], v[32:35]
	v_mfma_f32_16x16x32_bf16 v[20:23], v[176:179], v[208:211], v[20:23]
	v_mfma_f32_16x16x32_bf16 v[16:19], v[184:187], v[208:211], v[16:19]
	v_mfma_f32_16x16x32_bf16 v[4:7], v[176:179], v[216:219], v[4:7]
	v_mfma_f32_16x16x32_bf16 v[0:3], v[184:187], v[216:219], v[0:3]
	v_mfma_f32_16x16x32_bf16 v[52:55], v[180:183], v[196:199], v[52:55]
	v_mfma_f32_16x16x32_bf16 v[48:51], v[188:191], v[196:199], v[48:51]
	v_mfma_f32_16x16x32_bf16 v[36:39], v[180:183], v[204:207], v[36:39]
	v_mfma_f32_16x16x32_bf16 v[32:35], v[188:191], v[204:207], v[32:35]
	v_mfma_f32_16x16x32_bf16 v[20:23], v[180:183], v[212:215], v[20:23]
	v_mfma_f32_16x16x32_bf16 v[16:19], v[188:191], v[212:215], v[16:19]
	v_mfma_f32_16x16x32_bf16 v[4:7], v[180:183], v[222:225], v[4:7]
	v_mfma_f32_16x16x32_bf16 v[0:3], v[188:191], v[222:225], v[0:3]
	s_barrier
; #define PG8_STAGE(bufoff, gbase, voff) do { _Pragma("unroll") for (int _i = 0; _i < 2; ++_i) \
;         __builtin_amdgcn_global_load_lds((const unsigned*)((const char*)(gbase) + (voff)[_i]), (PG8_LAS unsigned*)(lds + (bufoff) + ldsw + _i * 8192), 16, 0, 0); } while (0)
; #define PG8_LDA(dst, b, h) do { _Pragma("unroll") for (int m = 0; m < 4; ++m) _Pragma("unroll") for (int k = 0; k < 2; ++k) dst[m][k] = *(const PG8_LAS bf16x8*)(lds + PG8_SA(b, h) + aoff + m * 2048 + k * 1024); } while (0)
; #define PG8_LDB(dst, b, h) do { _Pragma("unroll") for (int n = 0; n < 2; ++n) _Pragma("unroll") for (int k = 0; k < 2; ++k) dst[n][k] = *(const PG8_LAS bf16x8*)(lds + PG8_SB(b, h) + boff + n * 2048 + k * 1024); } while (0)
; #define PG8_MMA(ai, bj, At, Bt) do { __builtin_amdgcn_s_setprio(1); _Pragma("unroll") for (int m = 0; m < 4; ++m) _Pragma("unroll") for (int n = 0; n < 2; ++n) _Pragma("unroll") for (int k = 0; k < 2; ++k) \
;         acc[ai][bj][m][n] = __builtin_amdgcn_mfma_f32_16x16x32_bf16(Bt[n][k], At[m][k], acc[ai][bj][m][n], 0, 0, 0); __builtin_amdgcn_s_setprio(0); } while (0)
; #define PG8_WAIT_V(n) asm volatile("s_waitcnt vmcnt(" #n ")" ::: "memory")
; #define PG8_WAIT_L(n) asm volatile("s_waitcnt lgkmcnt(" #n ")" ::: "memory")
; #define PG8_BAR __builtin_amdgcn_s_barrier()
; #define PG8_SCHED __builtin_amdgcn_sched_barrier(0)
; template <class Epi, class Sched, bool ALIGN_EPI = false, bool SP2 = false>
; __device__ __forceinline__ void gemm_phase(PG8_LAS unsigned char* lds, const Gemm g, const Sched& S, const Epi& E) {
;     ...
;         for (int t = 0; t < nt; t += 2) {
;             const bool last = (t == nt - 2);
;     ...
;             PG8_LDB(B0, 1, 0); PG8_LDB(B1, 1, 1); PG8_SCHED; PG8_LDA(At, 1, 0); PG8_STAGE(PG8_SA(0, 1), a2 + hstep, voffA);
;             PG8_WAIT_V(8); PG8_WAIT_L(0); PG8_BAR; PG8_MMA(0, 0, At, B0); PG8_MMA(0, 1, At, B1); PG8_BAR; PG8_SCHED;
;             PG8_LDA(At, 1, 1); PG8_STAGE(PG8_SB(1, 0), b3, voffB); PG8_STAGE(PG8_SB(1, 1), b3 + hstep, voffB); PG8_STAGE(PG8_SA(1, 0), a3, voffA);
;             PG8_WAIT_V(8); PG8_WAIT_L(0); PG8_BAR; PG8_MMA(1, 0, At, B0); PG8_MMA(1, 1, At, B1); PG8_BAR; PG8_SCHED;
	s_add_i32 s86, 0, 0x18000
	v_add_u32_e32 v163, s86, v158
	s_add_i32 s87, 0, 0x1c000
	ds_read_b128 v[144:147], v163
	ds_read_b128 v[164:167], v163 offset:1024
	ds_read_b128 v[168:171], v163 offset:2048
	ds_read_b128 v[172:175], v163 offset:3072
	v_add_u32_e32 v163, s87, v158
	ds_read_b128 v[176:179], v163
	ds_read_b128 v[180:183], v163 offset:1024
	ds_read_b128 v[184:187], v163 offset:2048
	ds_read_b128 v[188:191], v163 offset:3072
	s_add_u32 s10, s10, 0x40000
	s_addc_u32 s11, s11, 0
	s_mov_b32 m0, s62
	ds_read_b128 v[192:195], v162 offset:32768
	ds_read_b128 v[196:199], v162 offset:33792
	ds_read_b128 v[200:203], v162 offset:34816
	ds_read_b128 v[204:207], v162 offset:35840
	ds_read_b128 v[208:211], v162 offset:36864
	ds_read_b128 v[212:215], v162 offset:37888
	ds_read_b128 v[216:219], v162 offset:38912
	ds_read_b128 v[222:225], v162 offset:39936
	global_load_lds_dwordx4 v134, s[10:11]
	s_mov_b32 m0, s63
	s_nop 0
	global_load_lds_dwordx4 v130, s[10:11]
	s_waitcnt vmcnt(8)
	s_waitcnt lgkmcnt(0)
	s_barrier
	s_waitcnt lgkmcnt(0)
	v_mfma_f32_16x16x32_bf16 v[124:127], v[144:147], v[192:195], v[124:127]
	v_mfma_f32_16x16x32_bf16 v[120:123], v[168:171], v[192:195], v[120:123]
	v_mfma_f32_16x16x32_bf16 v[108:111], v[144:147], v[200:203], v[108:111]
	v_mfma_f32_16x16x32_bf16 v[104:107], v[168:171], v[200:203], v[104:107]
	v_mfma_f32_16x16x32_bf16 v[92:95], v[144:147], v[208:211], v[92:95]
	v_mfma_f32_16x16x32_bf16 v[88:91], v[168:171], v[208:211], v[88:91]
	v_mfma_f32_16x16x32_bf16 v[76:79], v[144:147], v[216:219], v[76:79]
	v_mfma_f32_16x16x32_bf16 v[72:75], v[168:171], v[216:219], v[72:75]
	v_mfma_f32_16x16x32_bf16 v[124:127], v[164:167], v[196:199], v[124:127]
	v_mfma_f32_16x16x32_bf16 v[120:123], v[172:175], v[196:199], v[120:123]
	v_mfma_f32_16x16x32_bf16 v[108:111], v[164:167], v[204:207], v[108:111]
	v_mfma_f32_16x16x32_bf16 v[104:107], v[172:175], v[204:207], v[104:107]
	v_mfma_f32_16x16x32_bf16 v[92:95], v[164:167], v[212:215], v[92:95]
	v_mfma_f32_16x16x32_bf16 v[88:91], v[172:175], v[212:215], v[88:91]
	v_mfma_f32_16x16x32_bf16 v[76:79], v[164:167], v[222:225], v[76:79]
	v_mfma_f32_16x16x32_bf16 v[72:75], v[172:175], v[222:225], v[72:75]
	v_mfma_f32_16x16x32_bf16 v[116:119], v[176:179], v[192:195], v[116:119]
	v_mfma_f32_16x16x32_bf16 v[112:115], v[184:187], v[192:195], v[112:115]
	v_mfma_f32_16x16x32_bf16 v[100:103], v[176:179], v[200:203], v[100:103]
	v_mfma_f32_16x16x32_bf16 v[96:99], v[184:187], v[200:203], v[96:99]
	v_mfma_f32_16x16x32_bf16 v[84:87], v[176:179], v[208:211], v[84:87]
	v_mfma_f32_16x16x32_bf16 v[80:83], v[184:187], v[208:211], v[80:83]
	v_mfma_f32_16x16x32_bf16 v[68:71], v[176:179], v[216:219], v[68:71]
	v_mfma_f32_16x16x32_bf16 v[64:67], v[184:187], v[216:219], v[64:67]
	v_mfma_f32_16x16x32_bf16 v[116:119], v[180:183], v[196:199], v[116:119]
	v_mfma_f32_16x16x32_bf16 v[112:115], v[188:191], v[196:199], v[112:115]
	v_mfma_f32_16x16x32_bf16 v[100:103], v[180:183], v[204:207], v[100:103]
	v_mfma_f32_16x16x32_bf16 v[96:99], v[188:191], v[204:207], v[96:99]
	v_mfma_f32_16x16x32_bf16 v[84:87], v[180:183], v[212:215], v[84:87]
	v_mfma_f32_16x16x32_bf16 v[80:83], v[188:191], v[212:215], v[80:83]
	v_mfma_f32_16x16x32_bf16 v[68:71], v[180:183], v[222:225], v[68:71]
	v_mfma_f32_16x16x32_bf16 v[64:67], v[188:191], v[222:225], v[64:67]
	s_barrier
	s_add_i32 s10, s86, s3
	v_lshl_add_u64 v[226:227], v[226:227], 0, s[20:21]
	s_mov_b32 m0, s10
	ds_read_b128 v[192:195], v162 offset:49152
	ds_read_b128 v[196:199], v162 offset:50176
	ds_read_b128 v[200:203], v162 offset:51200
	ds_read_b128 v[204:207], v162 offset:52224
	ds_read_b128 v[208:211], v162 offset:53248
	ds_read_b128 v[212:215], v162 offset:54272
	ds_read_b128 v[216:219], v162 offset:55296
	ds_read_b128 v[222:225], v162 offset:56320
	global_load_lds_dwordx4 v[226:227], off
	s_add_i32 m0, s10, 0x2000
	s_add_u32 s6, s6, 0x40080
	v_lshl_add_u64 v[226:227], v[228:229], 0, s[20:21]
	s_addc_u32 s7, s7, 0
	s_add_i32 s10, s87, s3
	global_load_lds_dwordx4 v[226:227], off
	s_mov_b32 m0, s10
	s_nop 0
	global_load_lds_dwordx4 v132, s[6:7]
	s_add_i32 m0, s10, 0x2000
	s_nop 0
	global_load_lds_dwordx4 v128, s[6:7]
	v_lshl_add_u64 v[226:227], v[230:231], 0, s[20:21]
	s_mov_b32 m0, s65
	s_nop 0
	global_load_lds_dwordx4 v[226:227], off
	v_lshl_add_u64 v[226:227], v[232:233], 0, s[20:21]
	s_mov_b32 m0, s66
	s_nop 0
	global_load_lds_dwordx4 v[226:227], off
	s_waitcnt vmcnt(8)
	s_waitcnt lgkmcnt(0)
	s_barrier
	s_waitcnt lgkmcnt(0)
	v_mfma_f32_16x16x32_bf16 v[60:63], v[144:147], v[192:195], v[60:63]
	v_mfma_f32_16x16x32_bf16 v[56:59], v[168:171], v[192:195], v[56:59]
	v_mfma_f32_16x16x32_bf16 v[44:47], v[144:147], v[200:203], v[44:47]
	v_mfma_f32_16x16x32_bf16 v[40:43], v[168:171], v[200:203], v[40:43]
	v_mfma_f32_16x16x32_bf16 v[28:31], v[144:147], v[208:211], v[28:31]
	v_mfma_f32_16x16x32_bf16 v[24:27], v[168:171], v[208:211], v[24:27]
	v_mfma_f32_16x16x32_bf16 v[12:15], v[144:147], v[216:219], v[12:15]
	v_mfma_f32_16x16x32_bf16 v[8:11], v[168:171], v[216:219], v[8:11]
	v_mfma_f32_16x16x32_bf16 v[60:63], v[164:167], v[196:199], v[60:63]
	v_mfma_f32_16x16x32_bf16 v[56:59], v[172:175], v[196:199], v[56:59]
	v_mfma_f32_16x16x32_bf16 v[44:47], v[164:167], v[204:207], v[44:47]
	v_mfma_f32_16x16x32_bf16 v[40:43], v[172:175], v[204:207], v[40:43]
	v_mfma_f32_16x16x32_bf16 v[28:31], v[164:167], v[212:215], v[28:31]
	v_mfma_f32_16x16x32_bf16 v[24:27], v[172:175], v[212:215], v[24:27]
	v_mfma_f32_16x16x32_bf16 v[12:15], v[164:167], v[222:225], v[12:15]
	v_mfma_f32_16x16x32_bf16 v[8:11], v[172:175], v[222:225], v[8:11]
	v_mfma_f32_16x16x32_bf16 v[52:55], v[176:179], v[192:195], v[52:55]
	v_mfma_f32_16x16x32_bf16 v[48:51], v[184:187], v[192:195], v[48:51]
	v_mfma_f32_16x16x32_bf16 v[36:39], v[176:179], v[200:203], v[36:39]
	v_mfma_f32_16x16x32_bf16 v[32:35], v[184:187], v[200:203], v[32:35]
	v_mfma_f32_16x16x32_bf16 v[20:23], v[176:179], v[208:211], v[20:23]
	v_mfma_f32_16x16x32_bf16 v[16:19], v[184:187], v[208:211], v[16:19]
	v_mfma_f32_16x16x32_bf16 v[4:7], v[176:179], v[216:219], v[4:7]
	v_mfma_f32_16x16x32_bf16 v[0:3], v[184:187], v[216:219], v[0:3]
	v_mfma_f32_16x16x32_bf16 v[52:55], v[180:183], v[196:199], v[52:55]
	v_mfma_f32_16x16x32_bf16 v[48:51], v[188:191], v[196:199], v[48:51]
	v_mfma_f32_16x16x32_bf16 v[36:39], v[180:183], v[204:207], v[36:39]
	v_mfma_f32_16x16x32_bf16 v[32:35], v[188:191], v[204:207], v[32:35]
	v_mfma_f32_16x16x32_bf16 v[20:23], v[180:183], v[212:215], v[20:23]
	v_mfma_f32_16x16x32_bf16 v[16:19], v[188:191], v[212:215], v[16:19]
	v_mfma_f32_16x16x32_bf16 v[4:7], v[180:183], v[222:225], v[4:7]
	v_mfma_f32_16x16x32_bf16 v[0:3], v[188:191], v[222:225], v[0:3]
	s_barrier
	s_add_i32 s85, s85, 2
	s_add_u32 s58, s58, 0x100
	s_addc_u32 s59, s59, 0
	s_add_u32 s83, s83, 0x100
	s_addc_u32 s84, s84, 0
	s_cmp_gt_u32 s85, 13
	s_cbranch_scc0 .LBB0_234
	s_and_b64 vcc, exec, s[26:27]
	s_cbranch_vccz .LBB0_237
	s_barrier

; #define PG8_STAGE(bufoff, gbase, voff) do { _Pragma("unroll") for (int _i = 0; _i < 2; ++_i) \
;         __builtin_amdgcn_global_load_lds((const unsigned*)((const char*)(gbase) + (voff)[_i]), (PG8_LAS unsigned*)(lds + (bufoff) + ldsw + _i * 8192), 16, 0, 0); } while (0)
; #define PG8_LDA(dst, b, h) do { _Pragma("unroll") for (int m = 0; m < 4; ++m) _Pragma("unroll") for (int k = 0; k < 2; ++k) dst[m][k] = *(const PG8_LAS bf16x8*)(lds + PG8_SA(b, h) + aoff + m * 2048 + k * 1024); } while (0)
; #define PG8_LDB(dst, b, h) do { _Pragma("unroll") for (int n = 0; n < 2; ++n) _Pragma("unroll") for (int k = 0; k < 2; ++k) dst[n][k] = *(const PG8_LAS bf16x8*)(lds + PG8_SB(b, h) + boff + n * 2048 + k * 1024); } while (0)
; #define PG8_MMA(ai, bj, At, Bt) do { __builtin_amdgcn_s_setprio(1); _Pragma("unroll") for (int m = 0; m < 4; ++m) _Pragma("unroll") for (int n = 0; n < 2; ++n) _Pragma("unroll") for (int k = 0; k < 2; ++k) \
;         acc[ai][bj][m][n] = __builtin_amdgcn_mfma_f32_16x16x32_bf16(Bt[n][k], At[m][k], acc[ai][bj][m][n], 0, 0, 0); __builtin_amdgcn_s_setprio(0); } while (0)
; #define PG8_WAIT_V(n) asm volatile("s_waitcnt vmcnt(" #n ")" ::: "memory")
; #define PG8_WAIT_L(n) asm volatile("s_waitcnt lgkmcnt(" #n ")" ::: "memory")
; #define PG8_BAR __builtin_amdgcn_s_barrier()
; #define PG8_SCHED __builtin_amdgcn_sched_barrier(0)
; template <class Epi, class Sched, bool ALIGN_EPI = false, bool SP2 = false>
; __device__ __forceinline__ void gemm_phase(PG8_LAS unsigned char* lds, const Gemm g, const Sched& S, const Epi& E) {
;     ...
;             PG8_LDB(B0, 0, 0); PG8_LDB(B1, 0, 1); PG8_SCHED; PG8_LDA(At, 0, 0); PG8_STAGE(PG8_SA(1, 1), a1 + hstep, voffA);
;             PG8_WAIT_V(8); PG8_WAIT_L(0); PG8_BAR; PG8_MMA(0, 0, At, B0); PG8_MMA(0, 1, At, B1); PG8_BAR; PG8_SCHED;
;             PG8_LDA(At, 0, 1); PG8_STAGE(PG8_SB(0, 0), b2, voffB); PG8_STAGE(PG8_SB(0, 1), b2 + hstep, voffB); PG8_STAGE(PG8_SA(0, 0), a2, voffA);
;             PG8_WAIT_V(8); PG8_WAIT_L(0); PG8_BAR; PG8_MMA(1, 0, At, B0); PG8_MMA(1, 1, At, B1); PG8_BAR; PG8_SCHED;
.LBB0_480:
	ds_read_b128 v[88:91], v225
	ds_read_b128 v[92:95], v225 offset:1024
	ds_read_b128 v[96:99], v225 offset:2048
	ds_read_b128 v[104:107], v225 offset:3072
	ds_read_b128 v[144:147], v226
	ds_read_b128 v[148:151], v226 offset:1024
	ds_read_b128 v[152:155], v226 offset:2048
	ds_read_b128 v[156:159], v226 offset:3072
	s_add_u32 s6, s8, 0x3fff00
	s_addc_u32 s7, s9, 0
	s_cmp_eq_u32 s77, 12
	s_cselect_b32 s11, s47, s7
	s_cselect_b32 s10, s65, s6
	s_cselect_b32 s7, s35, s76
	s_cselect_b32 s6, s66, s67
	s_add_i32 m0, s33, 0xc000
	ds_read_b64_tr_b16 v[160:161], v249
	ds_read_b64_tr_b16 v[162:163], v249 offset:1024
	ds_read_b64_tr_b16 v[164:165], v249 offset:8192
	ds_read_b64_tr_b16 v[166:167], v249 offset:9216
	ds_read_b64_tr_b16 v[168:169], v250
	ds_read_b64_tr_b16 v[170:171], v250 offset:1024
	ds_read_b64_tr_b16 v[172:173], v250 offset:8192
	ds_read_b64_tr_b16 v[174:175], v250 offset:9216
	ds_read_b64_tr_b16 v[176:177], v251
	ds_read_b64_tr_b16 v[178:179], v251 offset:1024
	ds_read_b64_tr_b16 v[180:181], v251 offset:8192
	ds_read_b64_tr_b16 v[182:183], v251 offset:9216
	ds_read_b64_tr_b16 v[184:185], v254
	ds_read_b64_tr_b16 v[186:187], v254 offset:1024
	ds_read_b64_tr_b16 v[188:189], v254 offset:8192
	ds_read_b64_tr_b16 v[190:191], v254 offset:9216
	global_load_lds_dwordx4 v200, s[8:9]
	s_add_i32 m0, s33, 0xe000
	s_nop 0
	global_load_lds_dwordx4 v202, s[8:9]
	s_waitcnt vmcnt(8)
	s_waitcnt lgkmcnt(0)
	s_barrier
	s_waitcnt lgkmcnt(0)
	v_mfma_f32_16x16x32_bf16 v[140:143], v[88:91], v[160:163], v[140:143]
	v_mfma_f32_16x16x32_bf16 v[136:139], v[96:99], v[160:163], v[136:139]
	v_mfma_f32_16x16x32_bf16 v[124:127], v[88:91], v[168:171], v[124:127]
	v_mfma_f32_16x16x32_bf16 v[120:123], v[96:99], v[168:171], v[120:123]
	v_mfma_f32_16x16x32_bf16 v[108:111], v[88:91], v[176:179], v[108:111]
	v_mfma_f32_16x16x32_bf16 v[100:103], v[96:99], v[176:179], v[100:103]
	v_mfma_f32_16x16x32_bf16 v[76:79], v[88:91], v[184:187], v[76:79]
	v_mfma_f32_16x16x32_bf16 v[72:75], v[96:99], v[184:187], v[72:75]
	v_mfma_f32_16x16x32_bf16 v[140:143], v[92:95], v[164:167], v[140:143]
	v_mfma_f32_16x16x32_bf16 v[136:139], v[104:107], v[164:167], v[136:139]
	v_mfma_f32_16x16x32_bf16 v[124:127], v[92:95], v[172:175], v[124:127]
	v_mfma_f32_16x16x32_bf16 v[120:123], v[104:107], v[172:175], v[120:123]
	v_mfma_f32_16x16x32_bf16 v[108:111], v[92:95], v[180:183], v[108:111]
	v_mfma_f32_16x16x32_bf16 v[100:103], v[104:107], v[180:183], v[100:103]
	v_mfma_f32_16x16x32_bf16 v[76:79], v[92:95], v[188:191], v[76:79]
	v_mfma_f32_16x16x32_bf16 v[72:75], v[104:107], v[188:191], v[72:75]
	v_mfma_f32_16x16x32_bf16 v[132:135], v[144:147], v[160:163], v[132:135]
	v_mfma_f32_16x16x32_bf16 v[128:131], v[152:155], v[160:163], v[128:131]
	v_mfma_f32_16x16x32_bf16 v[116:119], v[144:147], v[168:171], v[116:119]
	v_mfma_f32_16x16x32_bf16 v[112:115], v[152:155], v[168:171], v[112:115]
	v_mfma_f32_16x16x32_bf16 v[84:87], v[144:147], v[176:179], v[84:87]
	v_mfma_f32_16x16x32_bf16 v[80:83], v[152:155], v[176:179], v[80:83]
	v_mfma_f32_16x16x32_bf16 v[68:71], v[144:147], v[184:187], v[68:71]
	v_mfma_f32_16x16x32_bf16 v[64:67], v[152:155], v[184:187], v[64:67]
	v_mfma_f32_16x16x32_bf16 v[132:135], v[148:151], v[164:167], v[132:135]
	v_mfma_f32_16x16x32_bf16 v[128:131], v[156:159], v[164:167], v[128:131]
	v_mfma_f32_16x16x32_bf16 v[116:119], v[148:151], v[172:175], v[116:119]
	v_mfma_f32_16x16x32_bf16 v[112:115], v[156:159], v[172:175], v[112:115]
	v_mfma_f32_16x16x32_bf16 v[84:87], v[148:151], v[180:183], v[84:87]
	v_mfma_f32_16x16x32_bf16 v[80:83], v[156:159], v[180:183], v[80:83]
	v_mfma_f32_16x16x32_bf16 v[68:71], v[148:151], v[188:191], v[68:71]
	v_mfma_f32_16x16x32_bf16 v[64:67], v[156:159], v[188:191], v[64:67]
	s_barrier
	s_add_i32 s78, s62, s3
	v_lshl_add_u64 v[208:209], s[6:7], 0, v[194:195]
	s_mov_b32 m0, s78
	ds_read_b64_tr_b16 v[160:161], v249 offset:16384
	ds_read_b64_tr_b16 v[162:163], v249 offset:17408
	ds_read_b64_tr_b16 v[164:165], v249 offset:24576
	ds_read_b64_tr_b16 v[166:167], v249 offset:25600
	ds_read_b64_tr_b16 v[168:169], v250 offset:16384
	ds_read_b64_tr_b16 v[170:171], v250 offset:17408
	ds_read_b64_tr_b16 v[172:173], v250 offset:24576
	ds_read_b64_tr_b16 v[174:175], v250 offset:25600
	ds_read_b64_tr_b16 v[176:177], v251 offset:16384
	ds_read_b64_tr_b16 v[178:179], v251 offset:17408
	ds_read_b64_tr_b16 v[180:181], v251 offset:24576
	ds_read_b64_tr_b16 v[182:183], v251 offset:25600
	ds_read_b64_tr_b16 v[184:185], v254 offset:16384
	ds_read_b64_tr_b16 v[186:187], v254 offset:17408
	ds_read_b64_tr_b16 v[188:189], v254 offset:24576
	ds_read_b64_tr_b16 v[190:191], v254 offset:25600
	global_load_lds_dwordx4 v[208:209], off
	s_add_i32 m0, s78, 0x2000
	s_add_u32 s78, s6, 0x40000
	v_lshl_add_u64 v[210:211], s[6:7], 0, v[198:199]
	s_addc_u32 s79, s7, 0
	s_add_i32 s80, s63, s3
	global_load_lds_dwordx4 v[210:211], off
	s_mov_b32 m0, s80
	v_lshl_add_u64 v[214:215], s[10:11], 0, v[196:197]
	global_load_lds_dwordx4 v194, s[78:79]
	s_add_i32 m0, s80, 0x2000
	s_nop 0
	global_load_lds_dwordx4 v198, s[78:79]
	v_lshl_add_u64 v[212:213], s[10:11], 0, v[192:193]
	s_mov_b32 m0, s33
	s_nop 0
	global_load_lds_dwordx4 v[212:213], off
	s_mov_b32 m0, s53
	s_nop 0
	global_load_lds_dwordx4 v[214:215], off
	s_waitcnt vmcnt(8)
	s_waitcnt lgkmcnt(0)
	s_barrier
; #define PG8_STAGE(bufoff, gbase, voff) do { _Pragma("unroll") for (int _i = 0; _i < 2; ++_i) \
;         __builtin_amdgcn_global_load_lds((const unsigned*)((const char*)(gbase) + (voff)[_i]), (PG8_LAS unsigned*)(lds + (bufoff) + ldsw + _i * 8192), 16, 0, 0); } while (0)
; #define PG8_LDA(dst, b, h) do { _Pragma("unroll") for (int m = 0; m < 4; ++m) _Pragma("unroll") for (int k = 0; k < 2; ++k) dst[m][k] = *(const PG8_LAS bf16x8*)(lds + PG8_SA(b, h) + aoff + m * 2048 + k * 1024); } while (0)
; #define PG8_LDB(dst, b, h) do { _Pragma("unroll") for (int n = 0; n < 2; ++n) _Pragma("unroll") for (int k = 0; k < 2; ++k) dst[n][k] = *(const PG8_LAS bf16x8*)(lds + PG8_SB(b, h) + boff + n * 2048 + k * 1024); } while (0)
; #define PG8_MMA(ai, bj, At, Bt) do { __builtin_amdgcn_s_setprio(1); _Pragma("unroll") for (int m = 0; m < 4; ++m) _Pragma("unroll") for (int n = 0; n < 2; ++n) _Pragma("unroll") for (int k = 0; k < 2; ++k) \
;         acc[ai][bj][m][n] = __builtin_amdgcn_mfma_f32_16x16x32_bf16(Bt[n][k], At[m][k], acc[ai][bj][m][n], 0, 0, 0); __builtin_amdgcn_s_setprio(0); } while (0)
; #define PG8_WAIT_V(n) asm volatile("s_waitcnt vmcnt(" #n ")" ::: "memory")
; #define PG8_WAIT_L(n) asm volatile("s_waitcnt lgkmcnt(" #n ")" ::: "memory")
; #define PG8_BAR __builtin_amdgcn_s_barrier()
; #define PG8_SCHED __builtin_amdgcn_sched_barrier(0)
; template <class Epi, class Sched, bool ALIGN_EPI = false, bool SP2 = false>
; __device__ __forceinline__ void gemm_phase(PG8_LAS unsigned char* lds, const Gemm g, const Sched& S, const Epi& E) {
;     ...
;             PG8_WAIT_V(8); PG8_WAIT_L(0); PG8_BAR; PG8_MMA(1, 0, At, B0); PG8_MMA(1, 1, At, B1); PG8_BAR; PG8_SCHED;
;             PG8_LDB(B0, 1, 0); PG8_LDB(B1, 1, 1); PG8_SCHED; PG8_LDA(At, 1, 0); PG8_STAGE(PG8_SA(0, 1), a2 + hstep, voffA);
;             PG8_WAIT_V(8); PG8_WAIT_L(0); PG8_BAR; PG8_MMA(0, 0, At, B0); PG8_MMA(0, 1, At, B1); PG8_BAR; PG8_SCHED;
	s_waitcnt lgkmcnt(0)
	v_mfma_f32_16x16x32_bf16 v[60:63], v[88:91], v[160:163], v[60:63]
	v_mfma_f32_16x16x32_bf16 v[56:59], v[96:99], v[160:163], v[56:59]
	v_mfma_f32_16x16x32_bf16 v[44:47], v[88:91], v[168:171], v[44:47]
	v_mfma_f32_16x16x32_bf16 v[40:43], v[96:99], v[168:171], v[40:43]
	v_mfma_f32_16x16x32_bf16 v[28:31], v[88:91], v[176:179], v[28:31]
	v_mfma_f32_16x16x32_bf16 v[24:27], v[96:99], v[176:179], v[24:27]
	v_mfma_f32_16x16x32_bf16 v[12:15], v[88:91], v[184:187], v[12:15]
	v_mfma_f32_16x16x32_bf16 v[8:11], v[96:99], v[184:187], v[8:11]
	v_mfma_f32_16x16x32_bf16 v[60:63], v[92:95], v[164:167], v[60:63]
	v_mfma_f32_16x16x32_bf16 v[56:59], v[104:107], v[164:167], v[56:59]
	v_mfma_f32_16x16x32_bf16 v[44:47], v[92:95], v[172:175], v[44:47]
	v_mfma_f32_16x16x32_bf16 v[40:43], v[104:107], v[172:175], v[40:43]
	v_mfma_f32_16x16x32_bf16 v[28:31], v[92:95], v[180:183], v[28:31]
	v_mfma_f32_16x16x32_bf16 v[24:27], v[104:107], v[180:183], v[24:27]
	v_mfma_f32_16x16x32_bf16 v[12:15], v[92:95], v[188:191], v[12:15]
	v_mfma_f32_16x16x32_bf16 v[8:11], v[104:107], v[188:191], v[8:11]
	v_mfma_f32_16x16x32_bf16 v[52:55], v[144:147], v[160:163], v[52:55]
	v_mfma_f32_16x16x32_bf16 v[48:51], v[152:155], v[160:163], v[48:51]
	v_mfma_f32_16x16x32_bf16 v[36:39], v[144:147], v[168:171], v[36:39]
	v_mfma_f32_16x16x32_bf16 v[32:35], v[152:155], v[168:171], v[32:35]
	v_mfma_f32_16x16x32_bf16 v[20:23], v[144:147], v[176:179], v[20:23]
	v_mfma_f32_16x16x32_bf16 v[16:19], v[152:155], v[176:179], v[16:19]
	v_mfma_f32_16x16x32_bf16 v[4:7], v[144:147], v[184:187], v[4:7]
	v_mfma_f32_16x16x32_bf16 v[0:3], v[152:155], v[184:187], v[0:3]
	v_mfma_f32_16x16x32_bf16 v[52:55], v[148:151], v[164:167], v[52:55]
	v_mfma_f32_16x16x32_bf16 v[48:51], v[156:159], v[164:167], v[48:51]
	v_mfma_f32_16x16x32_bf16 v[36:39], v[148:151], v[172:175], v[36:39]
	v_mfma_f32_16x16x32_bf16 v[32:35], v[156:159], v[172:175], v[32:35]
	v_mfma_f32_16x16x32_bf16 v[20:23], v[148:151], v[180:183], v[20:23]
	v_mfma_f32_16x16x32_bf16 v[16:19], v[156:159], v[180:183], v[16:19]
	v_mfma_f32_16x16x32_bf16 v[4:7], v[148:151], v[188:191], v[4:7]
	v_mfma_f32_16x16x32_bf16 v[0:3], v[156:159], v[188:191], v[0:3]
	s_barrier
	s_add_i32 s78, 0, 0x18000
	s_add_i32 s79, 0, 0x1c000
	v_add_u32_e32 v104, s78, v223
	v_add_u32_e32 v156, s79, v223
	ds_read_b128 v[88:91], v104
	ds_read_b128 v[92:95], v104 offset:1024
	ds_read_b128 v[96:99], v104 offset:2048
	ds_read_b128 v[104:107], v104 offset:3072
	ds_read_b128 v[144:147], v156
	ds_read_b128 v[148:151], v156 offset:1024
	ds_read_b128 v[152:155], v156 offset:2048
	ds_read_b128 v[156:159], v156 offset:3072
	s_add_u32 s10, s10, 0x100
	s_addc_u32 s11, s11, 0
	s_mov_b32 m0, s54
	ds_read_b64_tr_b16 v[160:161], v249 offset:32768
	ds_read_b64_tr_b16 v[162:163], v249 offset:33792
	ds_read_b64_tr_b16 v[164:165], v249 offset:40960
	ds_read_b64_tr_b16 v[166:167], v249 offset:41984
	ds_read_b64_tr_b16 v[168:169], v250 offset:32768
	ds_read_b64_tr_b16 v[170:171], v250 offset:33792
	ds_read_b64_tr_b16 v[172:173], v250 offset:40960
	ds_read_b64_tr_b16 v[174:175], v250 offset:41984
	ds_read_b64_tr_b16 v[176:177], v251 offset:32768
	ds_read_b64_tr_b16 v[178:179], v251 offset:33792
	ds_read_b64_tr_b16 v[180:181], v251 offset:40960
	ds_read_b64_tr_b16 v[182:183], v251 offset:41984
	ds_read_b64_tr_b16 v[184:185], v254 offset:32768
	ds_read_b64_tr_b16 v[186:187], v254 offset:33792
	ds_read_b64_tr_b16 v[188:189], v254 offset:40960
	ds_read_b64_tr_b16 v[190:191], v254 offset:41984
	global_load_lds_dwordx4 v192, s[10:11]
	s_mov_b32 m0, s55
	s_nop 0
	global_load_lds_dwordx4 v196, s[10:11]
	s_waitcnt vmcnt(8)
	s_waitcnt lgkmcnt(0)
	s_barrier
	s_waitcnt lgkmcnt(0)
	v_mfma_f32_16x16x32_bf16 v[140:143], v[88:91], v[160:163], v[140:143]
	v_mfma_f32_16x16x32_bf16 v[136:139], v[96:99], v[160:163], v[136:139]
	v_mfma_f32_16x16x32_bf16 v[124:127], v[88:91], v[168:171], v[124:127]
	v_mfma_f32_16x16x32_bf16 v[120:123], v[96:99], v[168:171], v[120:123]
	v_mfma_f32_16x16x32_bf16 v[108:111], v[88:91], v[176:179], v[108:111]
	v_mfma_f32_16x16x32_bf16 v[100:103], v[96:99], v[176:179], v[100:103]
	v_mfma_f32_16x16x32_bf16 v[76:79], v[88:91], v[184:187], v[76:79]
	v_mfma_f32_16x16x32_bf16 v[72:75], v[96:99], v[184:187], v[72:75]
	v_mfma_f32_16x16x32_bf16 v[140:143], v[92:95], v[164:167], v[140:143]
	v_mfma_f32_16x16x32_bf16 v[136:139], v[104:107], v[164:167], v[136:139]
	v_mfma_f32_16x16x32_bf16 v[124:127], v[92:95], v[172:175], v[124:127]
	v_mfma_f32_16x16x32_bf16 v[120:123], v[104:107], v[172:175], v[120:123]
	v_mfma_f32_16x16x32_bf16 v[108:111], v[92:95], v[180:183], v[108:111]
	v_mfma_f32_16x16x32_bf16 v[100:103], v[104:107], v[180:183], v[100:103]
	v_mfma_f32_16x16x32_bf16 v[76:79], v[92:95], v[188:191], v[76:79]
	v_mfma_f32_16x16x32_bf16 v[72:75], v[104:107], v[188:191], v[72:75]
	v_mfma_f32_16x16x32_bf16 v[132:135], v[144:147], v[160:163], v[132:135]
	v_mfma_f32_16x16x32_bf16 v[128:131], v[152:155], v[160:163], v[128:131]
	v_mfma_f32_16x16x32_bf16 v[116:119], v[144:147], v[168:171], v[116:119]
	v_mfma_f32_16x16x32_bf16 v[112:115], v[152:155], v[168:171], v[112:115]
	v_mfma_f32_16x16x32_bf16 v[84:87], v[144:147], v[176:179], v[84:87]
	v_mfma_f32_16x16x32_bf16 v[80:83], v[152:155], v[176:179], v[80:83]
	v_mfma_f32_16x16x32_bf16 v[68:71], v[144:147], v[184:187], v[68:71]
	v_mfma_f32_16x16x32_bf16 v[64:67], v[152:155], v[184:187], v[64:67]
	v_mfma_f32_16x16x32_bf16 v[132:135], v[148:151], v[164:167], v[132:135]
	v_mfma_f32_16x16x32_bf16 v[128:131], v[156:159], v[164:167], v[128:131]
	v_mfma_f32_16x16x32_bf16 v[116:119], v[148:151], v[172:175], v[116:119]
	v_mfma_f32_16x16x32_bf16 v[112:115], v[156:159], v[172:175], v[112:115]
	v_mfma_f32_16x16x32_bf16 v[84:87], v[148:151], v[180:183], v[84:87]
	v_mfma_f32_16x16x32_bf16 v[80:83], v[156:159], v[180:183], v[80:83]
	v_mfma_f32_16x16x32_bf16 v[68:71], v[148:151], v[188:191], v[68:71]
	v_mfma_f32_16x16x32_bf16 v[64:67], v[156:159], v[188:191], v[64:67]
	s_barrier
; #define PG8_STAGE(bufoff, gbase, voff) do { _Pragma("unroll") for (int _i = 0; _i < 2; ++_i) \
;         __builtin_amdgcn_global_load_lds((const unsigned*)((const char*)(gbase) + (voff)[_i]), (PG8_LAS unsigned*)(lds + (bufoff) + ldsw + _i * 8192), 16, 0, 0); } while (0)
; #define PG8_LDA(dst, b, h) do { _Pragma("unroll") for (int m = 0; m < 4; ++m) _Pragma("unroll") for (int k = 0; k < 2; ++k) dst[m][k] = *(const PG8_LAS bf16x8*)(lds + PG8_SA(b, h) + aoff + m * 2048 + k * 1024); } while (0)
; #define PG8_MMA(ai, bj, At, Bt) do { __builtin_amdgcn_s_setprio(1); _Pragma("unroll") for (int m = 0; m < 4; ++m) _Pragma("unroll") for (int n = 0; n < 2; ++n) _Pragma("unroll") for (int k = 0; k < 2; ++k) \
;         acc[ai][bj][m][n] = __builtin_amdgcn_mfma_f32_16x16x32_bf16(Bt[n][k], At[m][k], acc[ai][bj][m][n], 0, 0, 0); __builtin_amdgcn_s_setprio(0); } while (0)
; #define PG8_WAIT_V(n) asm volatile("s_waitcnt vmcnt(" #n ")" ::: "memory")
; #define PG8_WAIT_L(n) asm volatile("s_waitcnt lgkmcnt(" #n ")" ::: "memory")
; #define PG8_BAR __builtin_amdgcn_s_barrier()
; #define PG8_SCHED __builtin_amdgcn_sched_barrier(0)
; template <class Epi, class Sched, bool ALIGN_EPI = false, bool SP2 = false>
; __device__ __forceinline__ void gemm_phase(PG8_LAS unsigned char* lds, const Gemm g, const Sched& S, const Epi& E) {
;     ...
;         for (int t = 0; t < nt; t += 2) {
;             const bool last = (t == nt - 2);
;     ...
;             PG8_LDA(At, 1, 1); PG8_STAGE(PG8_SB(1, 0), b3, voffB); PG8_STAGE(PG8_SB(1, 1), b3 + hstep, voffB); PG8_STAGE(PG8_SA(1, 0), a3, voffA);
;             PG8_WAIT_V(8); PG8_WAIT_L(0); PG8_BAR; PG8_MMA(1, 0, At, B0); PG8_MMA(1, 1, At, B1); PG8_BAR; PG8_SCHED;
	s_add_i32 s10, s78, s3
	v_lshl_add_u64 v[208:209], v[208:209], 0, s[20:21]
	s_mov_b32 m0, s10
	ds_read_b64_tr_b16 v[160:161], v249 offset:49152
	ds_read_b64_tr_b16 v[162:163], v249 offset:50176
	ds_read_b64_tr_b16 v[164:165], v249 offset:57344
	ds_read_b64_tr_b16 v[166:167], v249 offset:58368
	ds_read_b64_tr_b16 v[168:169], v250 offset:49152
	ds_read_b64_tr_b16 v[170:171], v250 offset:50176
	ds_read_b64_tr_b16 v[172:173], v250 offset:57344
	ds_read_b64_tr_b16 v[174:175], v250 offset:58368
	ds_read_b64_tr_b16 v[176:177], v251 offset:49152
	ds_read_b64_tr_b16 v[178:179], v251 offset:50176
	ds_read_b64_tr_b16 v[180:181], v251 offset:57344
	ds_read_b64_tr_b16 v[182:183], v251 offset:58368
	ds_read_b64_tr_b16 v[184:185], v254 offset:49152
	ds_read_b64_tr_b16 v[186:187], v254 offset:50176
	ds_read_b64_tr_b16 v[188:189], v254 offset:57344
	ds_read_b64_tr_b16 v[190:191], v254 offset:58368
	global_load_lds_dwordx4 v[208:209], off
	s_add_i32 m0, s10, 0x2000
	s_add_u32 s6, s6, 0x40080
	v_lshl_add_u64 v[208:209], v[210:211], 0, s[20:21]
	s_addc_u32 s7, s7, 0
	s_add_i32 s10, s79, s3
	global_load_lds_dwordx4 v[208:209], off
	s_mov_b32 m0, s10
	s_nop 0
	global_load_lds_dwordx4 v194, s[6:7]
	s_add_i32 m0, s10, 0x2000
	s_nop 0
	global_load_lds_dwordx4 v198, s[6:7]
	v_lshl_add_u64 v[208:209], v[212:213], 0, s[98:99]
	s_mov_b32 m0, s57
	s_nop 0
	global_load_lds_dwordx4 v[208:209], off
	v_lshl_add_u64 v[208:209], v[214:215], 0, s[98:99]
	s_mov_b32 m0, s58
	s_nop 0
	global_load_lds_dwordx4 v[208:209], off
	s_waitcnt vmcnt(8)
	s_waitcnt lgkmcnt(0)
	s_barrier
	s_waitcnt lgkmcnt(0)
	v_mfma_f32_16x16x32_bf16 v[60:63], v[88:91], v[160:163], v[60:63]
	v_mfma_f32_16x16x32_bf16 v[56:59], v[96:99], v[160:163], v[56:59]
	v_mfma_f32_16x16x32_bf16 v[44:47], v[88:91], v[168:171], v[44:47]
	v_mfma_f32_16x16x32_bf16 v[40:43], v[96:99], v[168:171], v[40:43]
	v_mfma_f32_16x16x32_bf16 v[28:31], v[88:91], v[176:179], v[28:31]
	v_mfma_f32_16x16x32_bf16 v[24:27], v[96:99], v[176:179], v[24:27]
	v_mfma_f32_16x16x32_bf16 v[12:15], v[88:91], v[184:187], v[12:15]
	v_mfma_f32_16x16x32_bf16 v[8:11], v[96:99], v[184:187], v[8:11]
	v_mfma_f32_16x16x32_bf16 v[60:63], v[92:95], v[164:167], v[60:63]
	v_mfma_f32_16x16x32_bf16 v[56:59], v[104:107], v[164:167], v[56:59]
	v_mfma_f32_16x16x32_bf16 v[44:47], v[92:95], v[172:175], v[44:47]
	v_mfma_f32_16x16x32_bf16 v[40:43], v[104:107], v[172:175], v[40:43]
	v_mfma_f32_16x16x32_bf16 v[28:31], v[92:95], v[180:183], v[28:31]
	v_mfma_f32_16x16x32_bf16 v[24:27], v[104:107], v[180:183], v[24:27]
	v_mfma_f32_16x16x32_bf16 v[12:15], v[92:95], v[188:191], v[12:15]
	v_mfma_f32_16x16x32_bf16 v[8:11], v[104:107], v[188:191], v[8:11]
	v_mfma_f32_16x16x32_bf16 v[52:55], v[144:147], v[160:163], v[52:55]
	v_mfma_f32_16x16x32_bf16 v[48:51], v[152:155], v[160:163], v[48:51]
	v_mfma_f32_16x16x32_bf16 v[36:39], v[144:147], v[168:171], v[36:39]
	v_mfma_f32_16x16x32_bf16 v[32:35], v[152:155], v[168:171], v[32:35]
	v_mfma_f32_16x16x32_bf16 v[20:23], v[144:147], v[176:179], v[20:23]
	v_mfma_f32_16x16x32_bf16 v[16:19], v[152:155], v[176:179], v[16:19]
	v_mfma_f32_16x16x32_bf16 v[4:7], v[144:147], v[184:187], v[4:7]
	v_mfma_f32_16x16x32_bf16 v[0:3], v[152:155], v[184:187], v[0:3]
	v_mfma_f32_16x16x32_bf16 v[52:55], v[148:151], v[164:167], v[52:55]
	v_mfma_f32_16x16x32_bf16 v[48:51], v[156:159], v[164:167], v[48:51]
	v_mfma_f32_16x16x32_bf16 v[36:39], v[148:151], v[172:175], v[36:39]
	v_mfma_f32_16x16x32_bf16 v[32:35], v[156:159], v[172:175], v[32:35]
	v_mfma_f32_16x16x32_bf16 v[20:23], v[148:151], v[180:183], v[20:23]
	v_mfma_f32_16x16x32_bf16 v[16:19], v[156:159], v[180:183], v[16:19]
	v_mfma_f32_16x16x32_bf16 v[4:7], v[148:151], v[188:191], v[4:7]
	v_mfma_f32_16x16x32_bf16 v[0:3], v[156:159], v[188:191], v[0:3]
	s_barrier
	s_add_i32 s77, s77, 2
	s_add_u32 s8, s8, 0x800000
	s_addc_u32 s9, s9, 0
	s_add_u32 s67, s67, 0x100
	s_addc_u32 s76, s76, 0
	s_cmp_gt_u32 s77, 13
	s_cbranch_scc0 .LBB0_480
	s_and_b64 vcc, exec, s[26:27]
	s_cbranch_vccz .LBB0_483
	s_barrier

; #define PG8_STAGE(bufoff, gbase, voff) do { _Pragma("unroll") for (int _i = 0; _i < 2; ++_i) \
;         __builtin_amdgcn_global_load_lds((const unsigned*)((const char*)(gbase) + (voff)[_i]), (PG8_LAS unsigned*)(lds + (bufoff) + ldsw + _i * 8192), 16, 0, 0); } while (0)
; #define PG8_LDA(dst, b, h) do { _Pragma("unroll") for (int m = 0; m < 4; ++m) _Pragma("unroll") for (int k = 0; k < 2; ++k) dst[m][k] = *(const PG8_LAS bf16x8*)(lds + PG8_SA(b, h) + aoff + m * 2048 + k * 1024); } while (0)
; #define PG8_LDB(dst, b, h) do { _Pragma("unroll") for (int n = 0; n < 2; ++n) _Pragma("unroll") for (int k = 0; k < 2; ++k) dst[n][k] = *(const PG8_LAS bf16x8*)(lds + PG8_SB(b, h) + boff + n * 2048 + k * 1024); } while (0)
; #define PG8_MMA(ai, bj, At, Bt) do { __builtin_amdgcn_s_setprio(1); _Pragma("unroll") for (int m = 0; m < 4; ++m) _Pragma("unroll") for (int n = 0; n < 2; ++n) _Pragma("unroll") for (int k = 0; k < 2; ++k) \
;         acc[ai][bj][m][n] = __builtin_amdgcn_mfma_f32_16x16x32_bf16(Bt[n][k], At[m][k], acc[ai][bj][m][n], 0, 0, 0); __builtin_amdgcn_s_setprio(0); } while (0)
; #define PG8_WAIT_V(n) asm volatile("s_waitcnt vmcnt(" #n ")" ::: "memory")
; #define PG8_WAIT_L(n) asm volatile("s_waitcnt lgkmcnt(" #n ")" ::: "memory")
; #define PG8_BAR __builtin_amdgcn_s_barrier()
; #define PG8_SCHED __builtin_amdgcn_sched_barrier(0)
; template <class Epi, class Sched, bool ALIGN_EPI = false, bool SP2 = false>
; __device__ __forceinline__ void gemm_phase(PG8_LAS unsigned char* lds, const Gemm g, const Sched& S, const Epi& E) {
;     ...
;             PG8_LDB(B0, 0, 0); PG8_LDB(B1, 0, 1); PG8_SCHED; PG8_LDA(At, 0, 0); PG8_STAGE(PG8_SA(1, 1), a1 + hstep, voffA);
;             PG8_WAIT_V(8); PG8_WAIT_L(0); PG8_BAR; PG8_MMA(0, 0, At, B0); PG8_MMA(0, 1, At, B1); PG8_BAR; PG8_SCHED;
;             PG8_LDA(At, 0, 1); PG8_STAGE(PG8_SB(0, 0), b2, voffB); PG8_STAGE(PG8_SB(0, 1), b2 + hstep, voffB); PG8_STAGE(PG8_SA(0, 0), a2, voffA);
;             PG8_WAIT_V(8); PG8_WAIT_L(0); PG8_BAR; PG8_MMA(1, 0, At, B0); PG8_MMA(1, 1, At, B1); PG8_BAR; PG8_SCHED;
.LBB0_575:
	ds_read_b128 v[154:157], v149
	ds_read_b128 v[158:161], v149 offset:1024
	ds_read_b128 v[162:165], v149 offset:2048
	ds_read_b128 v[166:169], v149 offset:3072
	ds_read_b128 v[170:173], v150
	ds_read_b128 v[174:177], v150 offset:1024
	ds_read_b128 v[178:181], v150 offset:2048
	ds_read_b128 v[182:185], v150 offset:3072
	s_add_u32 s6, s30, 0xfffc0080
	s_addc_u32 s7, s31, -1
	s_cmp_eq_u32 s61, 12
	s_cselect_b32 s11, s19, s7
	s_cselect_b32 s10, s57, s6
	s_cselect_b32 s7, s17, s60
	s_cselect_b32 s6, s58, s59
	s_add_i32 m0, s29, 0xc000
	ds_read_b128 v[186:189], v151
	ds_read_b128 v[190:193], v151 offset:1024
	ds_read_b128 v[194:197], v151 offset:2048
	ds_read_b128 v[198:201], v151 offset:3072
	ds_read_b128 v[202:205], v151 offset:4096
	ds_read_b128 v[206:209], v151 offset:5120
	ds_read_b128 v[210:213], v151 offset:6144
	ds_read_b128 v[214:217], v151 offset:7168
	global_load_lds_dwordx4 v136, s[30:31]
	s_add_i32 m0, s29, 0xe000
	s_nop 0
	global_load_lds_dwordx4 v138, s[30:31]
	s_waitcnt vmcnt(8)
	s_waitcnt lgkmcnt(0)
	s_barrier
	s_waitcnt lgkmcnt(0)
	v_mfma_f32_16x16x32_bf16 v[116:119], v[154:157], v[186:189], v[116:119]
	v_mfma_f32_16x16x32_bf16 v[112:115], v[162:165], v[186:189], v[112:115]
	v_mfma_f32_16x16x32_bf16 v[100:103], v[154:157], v[194:197], v[100:103]
	v_mfma_f32_16x16x32_bf16 v[96:99], v[162:165], v[194:197], v[96:99]
	v_mfma_f32_16x16x32_bf16 v[84:87], v[154:157], v[202:205], v[84:87]
	v_mfma_f32_16x16x32_bf16 v[80:83], v[162:165], v[202:205], v[80:83]
	v_mfma_f32_16x16x32_bf16 v[68:71], v[154:157], v[210:213], v[68:71]
	v_mfma_f32_16x16x32_bf16 v[64:67], v[162:165], v[210:213], v[64:67]
	v_mfma_f32_16x16x32_bf16 v[116:119], v[158:161], v[190:193], v[116:119]
	v_mfma_f32_16x16x32_bf16 v[112:115], v[166:169], v[190:193], v[112:115]
	v_mfma_f32_16x16x32_bf16 v[100:103], v[158:161], v[198:201], v[100:103]
	v_mfma_f32_16x16x32_bf16 v[96:99], v[166:169], v[198:201], v[96:99]
	v_mfma_f32_16x16x32_bf16 v[84:87], v[158:161], v[206:209], v[84:87]
	v_mfma_f32_16x16x32_bf16 v[80:83], v[166:169], v[206:209], v[80:83]
	v_mfma_f32_16x16x32_bf16 v[68:71], v[158:161], v[214:217], v[68:71]
	v_mfma_f32_16x16x32_bf16 v[64:67], v[166:169], v[214:217], v[64:67]
	v_mfma_f32_16x16x32_bf16 v[124:127], v[170:173], v[186:189], v[124:127]
	v_mfma_f32_16x16x32_bf16 v[120:123], v[178:181], v[186:189], v[120:123]
	v_mfma_f32_16x16x32_bf16 v[108:111], v[170:173], v[194:197], v[108:111]
	v_mfma_f32_16x16x32_bf16 v[104:107], v[178:181], v[194:197], v[104:107]
	v_mfma_f32_16x16x32_bf16 v[92:95], v[170:173], v[202:205], v[92:95]
	v_mfma_f32_16x16x32_bf16 v[88:91], v[178:181], v[202:205], v[88:91]
	v_mfma_f32_16x16x32_bf16 v[76:79], v[170:173], v[210:213], v[76:79]
	v_mfma_f32_16x16x32_bf16 v[72:75], v[178:181], v[210:213], v[72:75]
	v_mfma_f32_16x16x32_bf16 v[124:127], v[174:177], v[190:193], v[124:127]
	v_mfma_f32_16x16x32_bf16 v[120:123], v[182:185], v[190:193], v[120:123]
	v_mfma_f32_16x16x32_bf16 v[108:111], v[174:177], v[198:201], v[108:111]
	v_mfma_f32_16x16x32_bf16 v[104:107], v[182:185], v[198:201], v[104:107]
	v_mfma_f32_16x16x32_bf16 v[92:95], v[174:177], v[206:209], v[92:95]
	v_mfma_f32_16x16x32_bf16 v[88:91], v[182:185], v[206:209], v[88:91]
	v_mfma_f32_16x16x32_bf16 v[76:79], v[174:177], v[214:217], v[76:79]
	v_mfma_f32_16x16x32_bf16 v[72:75], v[182:185], v[214:217], v[72:75]
	s_barrier
	s_add_i32 s62, s53, s34
	v_lshl_add_u64 v[144:145], s[6:7], 0, v[132:133]
	s_mov_b32 m0, s62
	ds_read_b128 v[186:189], v151 offset:16384
	ds_read_b128 v[190:193], v151 offset:17408
	ds_read_b128 v[194:197], v151 offset:18432
	ds_read_b128 v[198:201], v151 offset:19456
	ds_read_b128 v[202:205], v151 offset:20480
	ds_read_b128 v[206:209], v151 offset:21504
	ds_read_b128 v[210:213], v151 offset:22528
	ds_read_b128 v[214:217], v151 offset:23552
	global_load_lds_dwordx4 v[144:145], off
	s_add_i32 m0, s62, 0x2000
	s_add_u32 s62, s6, 0x40000
	v_lshl_add_u64 v[218:219], s[6:7], 0, v[128:129]
	s_addc_u32 s63, s7, 0
	s_add_i32 s64, s54, s34
	global_load_lds_dwordx4 v[218:219], off
	s_mov_b32 m0, s64
	v_lshl_add_u64 v[224:225], s[10:11], 0, v[130:131]
	global_load_lds_dwordx4 v132, s[62:63]
	s_add_i32 m0, s64, 0x2000
	s_nop 0
	global_load_lds_dwordx4 v128, s[62:63]
	v_lshl_add_u64 v[222:223], s[10:11], 0, v[134:135]
	s_mov_b32 m0, s29
	s_nop 0
	global_load_lds_dwordx4 v[222:223], off
	s_mov_b32 m0, s37
	s_nop 0
	global_load_lds_dwordx4 v[224:225], off
	s_waitcnt vmcnt(8)
	s_waitcnt lgkmcnt(0)
	s_barrier
	s_waitcnt lgkmcnt(0)
	v_mfma_f32_16x16x32_bf16 v[52:55], v[154:157], v[186:189], v[52:55]
	v_mfma_f32_16x16x32_bf16 v[48:51], v[162:165], v[186:189], v[48:51]
	v_mfma_f32_16x16x32_bf16 v[36:39], v[154:157], v[194:197], v[36:39]
	v_mfma_f32_16x16x32_bf16 v[32:35], v[162:165], v[194:197], v[32:35]
	v_mfma_f32_16x16x32_bf16 v[20:23], v[154:157], v[202:205], v[20:23]
	v_mfma_f32_16x16x32_bf16 v[16:19], v[162:165], v[202:205], v[16:19]
	v_mfma_f32_16x16x32_bf16 v[4:7], v[154:157], v[210:213], v[4:7]
	v_mfma_f32_16x16x32_bf16 v[0:3], v[162:165], v[210:213], v[0:3]
	v_mfma_f32_16x16x32_bf16 v[52:55], v[158:161], v[190:193], v[52:55]
	v_mfma_f32_16x16x32_bf16 v[48:51], v[166:169], v[190:193], v[48:51]
	v_mfma_f32_16x16x32_bf16 v[36:39], v[158:161], v[198:201], v[36:39]
	v_mfma_f32_16x16x32_bf16 v[32:35], v[166:169], v[198:201], v[32:35]
	v_mfma_f32_16x16x32_bf16 v[20:23], v[158:161], v[206:209], v[20:23]
	v_mfma_f32_16x16x32_bf16 v[16:19], v[166:169], v[206:209], v[16:19]
	v_mfma_f32_16x16x32_bf16 v[4:7], v[158:161], v[214:217], v[4:7]
	v_mfma_f32_16x16x32_bf16 v[0:3], v[166:169], v[214:217], v[0:3]
	v_mfma_f32_16x16x32_bf16 v[60:63], v[170:173], v[186:189], v[60:63]
	v_mfma_f32_16x16x32_bf16 v[56:59], v[178:181], v[186:189], v[56:59]
	v_mfma_f32_16x16x32_bf16 v[44:47], v[170:173], v[194:197], v[44:47]
	v_mfma_f32_16x16x32_bf16 v[40:43], v[178:181], v[194:197], v[40:43]
	v_mfma_f32_16x16x32_bf16 v[28:31], v[170:173], v[202:205], v[28:31]
	v_mfma_f32_16x16x32_bf16 v[24:27], v[178:181], v[202:205], v[24:27]
	v_mfma_f32_16x16x32_bf16 v[12:15], v[170:173], v[210:213], v[12:15]
	v_mfma_f32_16x16x32_bf16 v[8:11], v[178:181], v[210:213], v[8:11]
	v_mfma_f32_16x16x32_bf16 v[60:63], v[174:177], v[190:193], v[60:63]
	v_mfma_f32_16x16x32_bf16 v[56:59], v[182:185], v[190:193], v[56:59]
	v_mfma_f32_16x16x32_bf16 v[44:47], v[174:177], v[198:201], v[44:47]
	v_mfma_f32_16x16x32_bf16 v[40:43], v[182:185], v[198:201], v[40:43]
	v_mfma_f32_16x16x32_bf16 v[28:31], v[174:177], v[206:209], v[28:31]
	v_mfma_f32_16x16x32_bf16 v[24:27], v[182:185], v[206:209], v[24:27]
	v_mfma_f32_16x16x32_bf16 v[12:15], v[174:177], v[214:217], v[12:15]
	v_mfma_f32_16x16x32_bf16 v[8:11], v[182:185], v[214:217], v[8:11]
	s_barrier
; #define PG8_STAGE(bufoff, gbase, voff) do { _Pragma("unroll") for (int _i = 0; _i < 2; ++_i) \
;         __builtin_amdgcn_global_load_lds((const unsigned*)((const char*)(gbase) + (voff)[_i]), (PG8_LAS unsigned*)(lds + (bufoff) + ldsw + _i * 8192), 16, 0, 0); } while (0)
; #define PG8_LDA(dst, b, h) do { _Pragma("unroll") for (int m = 0; m < 4; ++m) _Pragma("unroll") for (int k = 0; k < 2; ++k) dst[m][k] = *(const PG8_LAS bf16x8*)(lds + PG8_SA(b, h) + aoff + m * 2048 + k * 1024); } while (0)
; #define PG8_LDB(dst, b, h) do { _Pragma("unroll") for (int n = 0; n < 2; ++n) _Pragma("unroll") for (int k = 0; k < 2; ++k) dst[n][k] = *(const PG8_LAS bf16x8*)(lds + PG8_SB(b, h) + boff + n * 2048 + k * 1024); } while (0)
; #define PG8_MMA(ai, bj, At, Bt) do { __builtin_amdgcn_s_setprio(1); _Pragma("unroll") for (int m = 0; m < 4; ++m) _Pragma("unroll") for (int n = 0; n < 2; ++n) _Pragma("unroll") for (int k = 0; k < 2; ++k) \
;         acc[ai][bj][m][n] = __builtin_amdgcn_mfma_f32_16x16x32_bf16(Bt[n][k], At[m][k], acc[ai][bj][m][n], 0, 0, 0); __builtin_amdgcn_s_setprio(0); } while (0)
; #define PG8_WAIT_V(n) asm volatile("s_waitcnt vmcnt(" #n ")" ::: "memory")
; #define PG8_WAIT_L(n) asm volatile("s_waitcnt lgkmcnt(" #n ")" ::: "memory")
; #define PG8_BAR __builtin_amdgcn_s_barrier()
; #define PG8_SCHED __builtin_amdgcn_sched_barrier(0)
; template <class Epi, class Sched, bool ALIGN_EPI = false, bool SP2 = false>
; __device__ __forceinline__ void gemm_phase(PG8_LAS unsigned char* lds, const Gemm g, const Sched& S, const Epi& E) {
;     ...
;         for (int t = 0; t < nt; t += 2) {
;             const bool last = (t == nt - 2);
;     ...
;             PG8_LDB(B0, 1, 0); PG8_LDB(B1, 1, 1); PG8_SCHED; PG8_LDA(At, 1, 0); PG8_STAGE(PG8_SA(0, 1), a2 + hstep, voffA);
;             PG8_WAIT_V(8); PG8_WAIT_L(0); PG8_BAR; PG8_MMA(0, 0, At, B0); PG8_MMA(0, 1, At, B1); PG8_BAR; PG8_SCHED;
;             PG8_LDA(At, 1, 1); PG8_STAGE(PG8_SB(1, 0), b3, voffB); PG8_STAGE(PG8_SB(1, 1), b3 + hstep, voffB); PG8_STAGE(PG8_SA(1, 0), a3, voffA);
;             PG8_WAIT_V(8); PG8_WAIT_L(0); PG8_BAR; PG8_MMA(1, 0, At, B0); PG8_MMA(1, 1, At, B1); PG8_BAR; PG8_SCHED;
	s_add_i32 s62, 0, 0x18000
	v_add_u32_e32 v153, s62, v147
	s_add_i32 s63, 0, 0x1c000
	ds_read_b128 v[154:157], v153
	ds_read_b128 v[158:161], v153 offset:1024
	ds_read_b128 v[162:165], v153 offset:2048
	ds_read_b128 v[166:169], v153 offset:3072
	v_add_u32_e32 v153, s63, v147
	ds_read_b128 v[170:173], v153
	ds_read_b128 v[174:177], v153 offset:1024
	ds_read_b128 v[178:181], v153 offset:2048
	ds_read_b128 v[182:185], v153 offset:3072
	s_add_u32 s10, s10, 0x40000
	s_addc_u32 s11, s11, 0
	s_mov_b32 m0, s46
	ds_read_b128 v[186:189], v151 offset:32768
	ds_read_b128 v[190:193], v151 offset:33792
	ds_read_b128 v[194:197], v151 offset:34816
	ds_read_b128 v[198:201], v151 offset:35840
	ds_read_b128 v[202:205], v151 offset:36864
	ds_read_b128 v[206:209], v151 offset:37888
	ds_read_b128 v[210:213], v151 offset:38912
	ds_read_b128 v[214:217], v151 offset:39936
	global_load_lds_dwordx4 v134, s[10:11]
	s_mov_b32 m0, s47
	s_nop 0
	global_load_lds_dwordx4 v130, s[10:11]
	s_waitcnt vmcnt(8)
	s_waitcnt lgkmcnt(0)
	s_barrier
	s_waitcnt lgkmcnt(0)
	v_mfma_f32_16x16x32_bf16 v[116:119], v[154:157], v[186:189], v[116:119]
	v_mfma_f32_16x16x32_bf16 v[112:115], v[162:165], v[186:189], v[112:115]
	v_mfma_f32_16x16x32_bf16 v[100:103], v[154:157], v[194:197], v[100:103]
	v_mfma_f32_16x16x32_bf16 v[96:99], v[162:165], v[194:197], v[96:99]
	v_mfma_f32_16x16x32_bf16 v[84:87], v[154:157], v[202:205], v[84:87]
	v_mfma_f32_16x16x32_bf16 v[80:83], v[162:165], v[202:205], v[80:83]
	v_mfma_f32_16x16x32_bf16 v[68:71], v[154:157], v[210:213], v[68:71]
	v_mfma_f32_16x16x32_bf16 v[64:67], v[162:165], v[210:213], v[64:67]
	v_mfma_f32_16x16x32_bf16 v[116:119], v[158:161], v[190:193], v[116:119]
	v_mfma_f32_16x16x32_bf16 v[112:115], v[166:169], v[190:193], v[112:115]
	v_mfma_f32_16x16x32_bf16 v[100:103], v[158:161], v[198:201], v[100:103]
	v_mfma_f32_16x16x32_bf16 v[96:99], v[166:169], v[198:201], v[96:99]
	v_mfma_f32_16x16x32_bf16 v[84:87], v[158:161], v[206:209], v[84:87]
	v_mfma_f32_16x16x32_bf16 v[80:83], v[166:169], v[206:209], v[80:83]
	v_mfma_f32_16x16x32_bf16 v[68:71], v[158:161], v[214:217], v[68:71]
	v_mfma_f32_16x16x32_bf16 v[64:67], v[166:169], v[214:217], v[64:67]
	v_mfma_f32_16x16x32_bf16 v[124:127], v[170:173], v[186:189], v[124:127]
	v_mfma_f32_16x16x32_bf16 v[120:123], v[178:181], v[186:189], v[120:123]
	v_mfma_f32_16x16x32_bf16 v[108:111], v[170:173], v[194:197], v[108:111]
	v_mfma_f32_16x16x32_bf16 v[104:107], v[178:181], v[194:197], v[104:107]
	v_mfma_f32_16x16x32_bf16 v[92:95], v[170:173], v[202:205], v[92:95]
	v_mfma_f32_16x16x32_bf16 v[88:91], v[178:181], v[202:205], v[88:91]
	v_mfma_f32_16x16x32_bf16 v[76:79], v[170:173], v[210:213], v[76:79]
	v_mfma_f32_16x16x32_bf16 v[72:75], v[178:181], v[210:213], v[72:75]
	v_mfma_f32_16x16x32_bf16 v[124:127], v[174:177], v[190:193], v[124:127]
	v_mfma_f32_16x16x32_bf16 v[120:123], v[182:185], v[190:193], v[120:123]
	v_mfma_f32_16x16x32_bf16 v[108:111], v[174:177], v[198:201], v[108:111]
	v_mfma_f32_16x16x32_bf16 v[104:107], v[182:185], v[198:201], v[104:107]
	v_mfma_f32_16x16x32_bf16 v[92:95], v[174:177], v[206:209], v[92:95]
	v_mfma_f32_16x16x32_bf16 v[88:91], v[182:185], v[206:209], v[88:91]
	v_mfma_f32_16x16x32_bf16 v[76:79], v[174:177], v[214:217], v[76:79]
	v_mfma_f32_16x16x32_bf16 v[72:75], v[182:185], v[214:217], v[72:75]
	s_barrier
	s_add_i32 s10, s62, s34
	v_lshl_add_u64 v[144:145], v[144:145], 0, s[12:13]
	s_mov_b32 m0, s10
	ds_read_b128 v[186:189], v151 offset:49152
	ds_read_b128 v[190:193], v151 offset:50176
	ds_read_b128 v[194:197], v151 offset:51200
	ds_read_b128 v[198:201], v151 offset:52224
	ds_read_b128 v[202:205], v151 offset:53248
	ds_read_b128 v[206:209], v151 offset:54272
	ds_read_b128 v[210:213], v151 offset:55296
	ds_read_b128 v[214:217], v151 offset:56320
	global_load_lds_dwordx4 v[144:145], off
	s_add_i32 m0, s10, 0x2000
	s_add_u32 s6, s6, 0x40080
	v_lshl_add_u64 v[144:145], v[218:219], 0, s[12:13]
	s_addc_u32 s7, s7, 0
	s_add_i32 s10, s63, s34
	global_load_lds_dwordx4 v[144:145], off
	s_mov_b32 m0, s10
	s_nop 0
	global_load_lds_dwordx4 v132, s[6:7]
	s_add_i32 m0, s10, 0x2000
	s_nop 0
	global_load_lds_dwordx4 v128, s[6:7]
	v_lshl_add_u64 v[144:145], v[222:223], 0, s[12:13]
	s_mov_b32 m0, s49
	s_nop 0
	global_load_lds_dwordx4 v[144:145], off
	v_lshl_add_u64 v[144:145], v[224:225], 0, s[12:13]
	s_mov_b32 m0, s50
	s_nop 0
	global_load_lds_dwordx4 v[144:145], off
	s_waitcnt vmcnt(8)
	s_waitcnt lgkmcnt(0)
	s_barrier
	s_waitcnt lgkmcnt(0)
	v_mfma_f32_16x16x32_bf16 v[52:55], v[154:157], v[186:189], v[52:55]
	v_mfma_f32_16x16x32_bf16 v[48:51], v[162:165], v[186:189], v[48:51]
	v_mfma_f32_16x16x32_bf16 v[36:39], v[154:157], v[194:197], v[36:39]
	v_mfma_f32_16x16x32_bf16 v[32:35], v[162:165], v[194:197], v[32:35]
	v_mfma_f32_16x16x32_bf16 v[20:23], v[154:157], v[202:205], v[20:23]
	v_mfma_f32_16x16x32_bf16 v[16:19], v[162:165], v[202:205], v[16:19]
	v_mfma_f32_16x16x32_bf16 v[4:7], v[154:157], v[210:213], v[4:7]
	v_mfma_f32_16x16x32_bf16 v[0:3], v[162:165], v[210:213], v[0:3]
	v_mfma_f32_16x16x32_bf16 v[52:55], v[158:161], v[190:193], v[52:55]
	v_mfma_f32_16x16x32_bf16 v[48:51], v[166:169], v[190:193], v[48:51]
	v_mfma_f32_16x16x32_bf16 v[36:39], v[158:161], v[198:201], v[36:39]
	v_mfma_f32_16x16x32_bf16 v[32:35], v[166:169], v[198:201], v[32:35]
	v_mfma_f32_16x16x32_bf16 v[20:23], v[158:161], v[206:209], v[20:23]
	v_mfma_f32_16x16x32_bf16 v[16:19], v[166:169], v[206:209], v[16:19]
	v_mfma_f32_16x16x32_bf16 v[4:7], v[158:161], v[214:217], v[4:7]
	v_mfma_f32_16x16x32_bf16 v[0:3], v[166:169], v[214:217], v[0:3]
	v_mfma_f32_16x16x32_bf16 v[60:63], v[170:173], v[186:189], v[60:63]
	v_mfma_f32_16x16x32_bf16 v[56:59], v[178:181], v[186:189], v[56:59]
	v_mfma_f32_16x16x32_bf16 v[44:47], v[170:173], v[194:197], v[44:47]
	v_mfma_f32_16x16x32_bf16 v[40:43], v[178:181], v[194:197], v[40:43]
	v_mfma_f32_16x16x32_bf16 v[28:31], v[170:173], v[202:205], v[28:31]
	v_mfma_f32_16x16x32_bf16 v[24:27], v[178:181], v[202:205], v[24:27]
	v_mfma_f32_16x16x32_bf16 v[12:15], v[170:173], v[210:213], v[12:15]
	v_mfma_f32_16x16x32_bf16 v[8:11], v[178:181], v[210:213], v[8:11]
	v_mfma_f32_16x16x32_bf16 v[60:63], v[174:177], v[190:193], v[60:63]
	v_mfma_f32_16x16x32_bf16 v[56:59], v[182:185], v[190:193], v[56:59]
	v_mfma_f32_16x16x32_bf16 v[44:47], v[174:177], v[198:201], v[44:47]
	v_mfma_f32_16x16x32_bf16 v[40:43], v[182:185], v[198:201], v[40:43]
	v_mfma_f32_16x16x32_bf16 v[28:31], v[174:177], v[206:209], v[28:31]
	v_mfma_f32_16x16x32_bf16 v[24:27], v[182:185], v[206:209], v[24:27]
	v_mfma_f32_16x16x32_bf16 v[12:15], v[174:177], v[214:217], v[12:15]
	v_mfma_f32_16x16x32_bf16 v[8:11], v[182:185], v[214:217], v[8:11]
	s_barrier
	s_add_i32 s61, s61, 2
	s_add_u32 s30, s30, 0x100
	s_addc_u32 s31, s31, 0
	s_add_u32 s59, s59, 0x100
	s_addc_u32 s60, s60, 0
	s_cmp_gt_u32 s61, 13
	s_cbranch_scc0 .LBB0_575
	s_and_b64 vcc, exec, s[14:15]
	s_cbranch_vccz .LBB0_578
	s_barrier

; #define PG8_STAGE(bufoff, gbase, voff) do { _Pragma("unroll") for (int _i = 0; _i < 2; ++_i) \
;         __builtin_amdgcn_global_load_lds((const unsigned*)((const char*)(gbase) + (voff)[_i]), (PG8_LAS unsigned*)(lds + (bufoff) + ldsw + _i * 8192), 16, 0, 0); } while (0)
; #define PG8_LDA(dst, b, h) do { _Pragma("unroll") for (int m = 0; m < 4; ++m) _Pragma("unroll") for (int k = 0; k < 2; ++k) dst[m][k] = *(const PG8_LAS bf16x8*)(lds + PG8_SA(b, h) + aoff + m * 2048 + k * 1024); } while (0)
; #define PG8_LDB(dst, b, h) do { _Pragma("unroll") for (int n = 0; n < 2; ++n) _Pragma("unroll") for (int k = 0; k < 2; ++k) dst[n][k] = *(const PG8_LAS bf16x8*)(lds + PG8_SB(b, h) + boff + n * 2048 + k * 1024); } while (0)
; #define PG8_MMA(ai, bj, At, Bt) do { __builtin_amdgcn_s_setprio(1); _Pragma("unroll") for (int m = 0; m < 4; ++m) _Pragma("unroll") for (int n = 0; n < 2; ++n) _Pragma("unroll") for (int k = 0; k < 2; ++k) \
;         acc[ai][bj][m][n] = __builtin_amdgcn_mfma_f32_16x16x32_bf16(Bt[n][k], At[m][k], acc[ai][bj][m][n], 0, 0, 0); __builtin_amdgcn_s_setprio(0); } while (0)
; #define PG8_WAIT_V(n) asm volatile("s_waitcnt vmcnt(" #n ")" ::: "memory")
; #define PG8_WAIT_L(n) asm volatile("s_waitcnt lgkmcnt(" #n ")" ::: "memory")
; #define PG8_BAR __builtin_amdgcn_s_barrier()
; #define PG8_SCHED __builtin_amdgcn_sched_barrier(0)
; template <class Epi, class Sched, bool ALIGN_EPI = false, bool SP2 = false>
; __device__ __forceinline__ void gemm_phase(PG8_LAS unsigned char* lds, const Gemm g, const Sched& S, const Epi& E) {
;     ...
;             PG8_LDB(B0, 0, 0); PG8_LDB(B1, 0, 1); PG8_SCHED; PG8_LDA(At, 0, 0); PG8_STAGE(PG8_SA(1, 1), a1 + hstep, voffA);
;             PG8_WAIT_V(8); PG8_WAIT_L(0); PG8_BAR; PG8_MMA(0, 0, At, B0); PG8_MMA(0, 1, At, B1); PG8_BAR; PG8_SCHED;
;             PG8_LDA(At, 0, 1); PG8_STAGE(PG8_SB(0, 0), b2, voffB); PG8_STAGE(PG8_SB(0, 1), b2 + hstep, voffB); PG8_STAGE(PG8_SA(0, 0), a2, voffA);
;             PG8_WAIT_V(8); PG8_WAIT_L(0); PG8_BAR; PG8_MMA(1, 0, At, B0); PG8_MMA(1, 1, At, B1); PG8_BAR; PG8_SCHED;
.LBB0_660:
	ds_read_b128 v[128:131], v189
	ds_read_b128 v[132:135], v189 offset:1024
	ds_read_b128 v[136:139], v189 offset:2048
	ds_read_b128 v[140:143], v189 offset:3072
	ds_read_b128 v[144:147], v190
	ds_read_b128 v[148:151], v190 offset:1024
	ds_read_b128 v[168:171], v190 offset:2048
	ds_read_b128 v[172:175], v190 offset:3072
	s_add_u32 s6, s28, 0xfff50080
	s_addc_u32 s7, s29, -1
	s_cmp_eq_u32 s59, 40
	s_cselect_b32 s11, s9, s7
	s_cselect_b32 s10, s8, s6
	s_cselect_b32 s7, s27, s58
	s_cselect_b32 s6, s26, s57
	s_add_i32 m0, s33, 0xc000
	ds_read_b128 v[176:179], v191
	ds_read_b128 v[180:183], v191 offset:1024
	ds_read_b128 v[194:197], v191 offset:2048
	ds_read_b128 v[198:201], v191 offset:3072
	ds_read_b128 v[202:205], v191 offset:4096
	ds_read_b128 v[206:209], v191 offset:5120
	ds_read_b128 v[210:213], v191 offset:6144
	ds_read_b128 v[214:217], v191 offset:7168
	global_load_lds_dwordx4 v160, s[28:29]
	s_add_i32 m0, s33, 0xe000
	s_nop 0
	global_load_lds_dwordx4 v162, s[28:29]
	s_waitcnt vmcnt(8)
	s_waitcnt lgkmcnt(0)
	s_barrier
	s_waitcnt lgkmcnt(0)
	v_mfma_f32_16x16x32_bf16 v[124:127], v[128:131], v[176:179], v[124:127]
	v_mfma_f32_16x16x32_bf16 v[120:123], v[136:139], v[176:179], v[120:123]
	v_mfma_f32_16x16x32_bf16 v[108:111], v[128:131], v[194:197], v[108:111]
	v_mfma_f32_16x16x32_bf16 v[104:107], v[136:139], v[194:197], v[104:107]
	v_mfma_f32_16x16x32_bf16 v[92:95], v[128:131], v[202:205], v[92:95]
	v_mfma_f32_16x16x32_bf16 v[88:91], v[136:139], v[202:205], v[88:91]
	v_mfma_f32_16x16x32_bf16 v[76:79], v[128:131], v[210:213], v[76:79]
	v_mfma_f32_16x16x32_bf16 v[72:75], v[136:139], v[210:213], v[72:75]
	v_mfma_f32_16x16x32_bf16 v[124:127], v[132:135], v[180:183], v[124:127]
	v_mfma_f32_16x16x32_bf16 v[120:123], v[140:143], v[180:183], v[120:123]
	v_mfma_f32_16x16x32_bf16 v[108:111], v[132:135], v[198:201], v[108:111]
	v_mfma_f32_16x16x32_bf16 v[104:107], v[140:143], v[198:201], v[104:107]
	v_mfma_f32_16x16x32_bf16 v[92:95], v[132:135], v[206:209], v[92:95]
	v_mfma_f32_16x16x32_bf16 v[88:91], v[140:143], v[206:209], v[88:91]
	v_mfma_f32_16x16x32_bf16 v[76:79], v[132:135], v[214:217], v[76:79]
	v_mfma_f32_16x16x32_bf16 v[72:75], v[140:143], v[214:217], v[72:75]
	v_mfma_f32_16x16x32_bf16 v[116:119], v[144:147], v[176:179], v[116:119]
	v_mfma_f32_16x16x32_bf16 v[112:115], v[168:171], v[176:179], v[112:115]
	v_mfma_f32_16x16x32_bf16 v[100:103], v[144:147], v[194:197], v[100:103]
	v_mfma_f32_16x16x32_bf16 v[96:99], v[168:171], v[194:197], v[96:99]
	v_mfma_f32_16x16x32_bf16 v[84:87], v[144:147], v[202:205], v[84:87]
	v_mfma_f32_16x16x32_bf16 v[80:83], v[168:171], v[202:205], v[80:83]
	v_mfma_f32_16x16x32_bf16 v[68:71], v[144:147], v[210:213], v[68:71]
	v_mfma_f32_16x16x32_bf16 v[64:67], v[168:171], v[210:213], v[64:67]
	v_mfma_f32_16x16x32_bf16 v[116:119], v[148:151], v[180:183], v[116:119]
	v_mfma_f32_16x16x32_bf16 v[112:115], v[172:175], v[180:183], v[112:115]
	v_mfma_f32_16x16x32_bf16 v[100:103], v[148:151], v[198:201], v[100:103]
	v_mfma_f32_16x16x32_bf16 v[96:99], v[172:175], v[198:201], v[96:99]
	v_mfma_f32_16x16x32_bf16 v[84:87], v[148:151], v[206:209], v[84:87]
	v_mfma_f32_16x16x32_bf16 v[80:83], v[172:175], v[206:209], v[80:83]
	v_mfma_f32_16x16x32_bf16 v[68:71], v[148:151], v[214:217], v[68:71]
	v_mfma_f32_16x16x32_bf16 v[64:67], v[172:175], v[214:217], v[64:67]
	s_barrier
	s_add_i32 s60, s51, s31
	v_lshl_add_u64 v[184:185], s[6:7], 0, v[154:155]
	s_mov_b32 m0, s60
	ds_read_b128 v[176:179], v191 offset:16384
	ds_read_b128 v[180:183], v191 offset:17408
	ds_read_b128 v[194:197], v191 offset:18432
	ds_read_b128 v[198:201], v191 offset:19456
	ds_read_b128 v[202:205], v191 offset:20480
	ds_read_b128 v[206:209], v191 offset:21504
	ds_read_b128 v[210:213], v191 offset:22528
	ds_read_b128 v[214:217], v191 offset:23552
	global_load_lds_dwordx4 v[184:185], off
	s_add_i32 m0, s60, 0x2000
	s_add_u32 s60, s6, 0xb0000
	v_lshl_add_u64 v[218:219], s[6:7], 0, v[158:159]
	s_addc_u32 s61, s7, 0
	s_add_i32 s62, s52, s31
	global_load_lds_dwordx4 v[218:219], off
	s_mov_b32 m0, s62
	v_lshl_add_u64 v[224:225], s[10:11], 0, v[156:157]
	global_load_lds_dwordx4 v154, s[60:61]
	s_add_i32 m0, s62, 0x2000
	s_nop 0
	global_load_lds_dwordx4 v158, s[60:61]
	v_lshl_add_u64 v[222:223], s[10:11], 0, v[152:153]
	s_mov_b32 m0, s33
	s_nop 0
	global_load_lds_dwordx4 v[222:223], off
	s_mov_b32 m0, s34
	s_nop 0
	global_load_lds_dwordx4 v[224:225], off
	s_waitcnt vmcnt(8)
	s_waitcnt lgkmcnt(0)
	s_barrier
	s_waitcnt lgkmcnt(0)
	v_mfma_f32_16x16x32_bf16 v[60:63], v[128:131], v[176:179], v[60:63]
	v_mfma_f32_16x16x32_bf16 v[56:59], v[136:139], v[176:179], v[56:59]
	v_mfma_f32_16x16x32_bf16 v[44:47], v[128:131], v[194:197], v[44:47]
	v_mfma_f32_16x16x32_bf16 v[40:43], v[136:139], v[194:197], v[40:43]
	v_mfma_f32_16x16x32_bf16 v[28:31], v[128:131], v[202:205], v[28:31]
	v_mfma_f32_16x16x32_bf16 v[24:27], v[136:139], v[202:205], v[24:27]
	v_mfma_f32_16x16x32_bf16 v[12:15], v[128:131], v[210:213], v[12:15]
	v_mfma_f32_16x16x32_bf16 v[8:11], v[136:139], v[210:213], v[8:11]
	v_mfma_f32_16x16x32_bf16 v[60:63], v[132:135], v[180:183], v[60:63]
	v_mfma_f32_16x16x32_bf16 v[56:59], v[140:143], v[180:183], v[56:59]
	v_mfma_f32_16x16x32_bf16 v[44:47], v[132:135], v[198:201], v[44:47]
	v_mfma_f32_16x16x32_bf16 v[40:43], v[140:143], v[198:201], v[40:43]
	v_mfma_f32_16x16x32_bf16 v[28:31], v[132:135], v[206:209], v[28:31]
	v_mfma_f32_16x16x32_bf16 v[24:27], v[140:143], v[206:209], v[24:27]
	v_mfma_f32_16x16x32_bf16 v[12:15], v[132:135], v[214:217], v[12:15]
	v_mfma_f32_16x16x32_bf16 v[8:11], v[140:143], v[214:217], v[8:11]
	v_mfma_f32_16x16x32_bf16 v[52:55], v[144:147], v[176:179], v[52:55]
	v_mfma_f32_16x16x32_bf16 v[48:51], v[168:171], v[176:179], v[48:51]
	v_mfma_f32_16x16x32_bf16 v[36:39], v[144:147], v[194:197], v[36:39]
	v_mfma_f32_16x16x32_bf16 v[32:35], v[168:171], v[194:197], v[32:35]
	v_mfma_f32_16x16x32_bf16 v[20:23], v[144:147], v[202:205], v[20:23]
	v_mfma_f32_16x16x32_bf16 v[16:19], v[168:171], v[202:205], v[16:19]
	v_mfma_f32_16x16x32_bf16 v[4:7], v[144:147], v[210:213], v[4:7]
	v_mfma_f32_16x16x32_bf16 v[0:3], v[168:171], v[210:213], v[0:3]
	v_mfma_f32_16x16x32_bf16 v[52:55], v[148:151], v[180:183], v[52:55]
	v_mfma_f32_16x16x32_bf16 v[48:51], v[172:175], v[180:183], v[48:51]
	v_mfma_f32_16x16x32_bf16 v[36:39], v[148:151], v[198:201], v[36:39]
	v_mfma_f32_16x16x32_bf16 v[32:35], v[172:175], v[198:201], v[32:35]
	v_mfma_f32_16x16x32_bf16 v[20:23], v[148:151], v[206:209], v[20:23]
	v_mfma_f32_16x16x32_bf16 v[16:19], v[172:175], v[206:209], v[16:19]
	v_mfma_f32_16x16x32_bf16 v[4:7], v[148:151], v[214:217], v[4:7]
	v_mfma_f32_16x16x32_bf16 v[0:3], v[172:175], v[214:217], v[0:3]
	s_barrier
; #define PG8_STAGE(bufoff, gbase, voff) do { _Pragma("unroll") for (int _i = 0; _i < 2; ++_i) \
;         __builtin_amdgcn_global_load_lds((const unsigned*)((const char*)(gbase) + (voff)[_i]), (PG8_LAS unsigned*)(lds + (bufoff) + ldsw + _i * 8192), 16, 0, 0); } while (0)
; #define PG8_LDA(dst, b, h) do { _Pragma("unroll") for (int m = 0; m < 4; ++m) _Pragma("unroll") for (int k = 0; k < 2; ++k) dst[m][k] = *(const PG8_LAS bf16x8*)(lds + PG8_SA(b, h) + aoff + m * 2048 + k * 1024); } while (0)
; #define PG8_LDB(dst, b, h) do { _Pragma("unroll") for (int n = 0; n < 2; ++n) _Pragma("unroll") for (int k = 0; k < 2; ++k) dst[n][k] = *(const PG8_LAS bf16x8*)(lds + PG8_SB(b, h) + boff + n * 2048 + k * 1024); } while (0)
; #define PG8_MMA(ai, bj, At, Bt) do { __builtin_amdgcn_s_setprio(1); _Pragma("unroll") for (int m = 0; m < 4; ++m) _Pragma("unroll") for (int n = 0; n < 2; ++n) _Pragma("unroll") for (int k = 0; k < 2; ++k) \
;         acc[ai][bj][m][n] = __builtin_amdgcn_mfma_f32_16x16x32_bf16(Bt[n][k], At[m][k], acc[ai][bj][m][n], 0, 0, 0); __builtin_amdgcn_s_setprio(0); } while (0)
; #define PG8_WAIT_V(n) asm volatile("s_waitcnt vmcnt(" #n ")" ::: "memory")
; #define PG8_WAIT_L(n) asm volatile("s_waitcnt lgkmcnt(" #n ")" ::: "memory")
; #define PG8_BAR __builtin_amdgcn_s_barrier()
; #define PG8_SCHED __builtin_amdgcn_sched_barrier(0)
; template <class Epi, class Sched, bool ALIGN_EPI = false, bool SP2 = false>
; __device__ __forceinline__ void gemm_phase(PG8_LAS unsigned char* lds, const Gemm g, const Sched& S, const Epi& E) {
;     ...
;         for (int t = 0; t < nt; t += 2) {
;             const bool last = (t == nt - 2);
;     ...
;             PG8_LDB(B0, 1, 0); PG8_LDB(B1, 1, 1); PG8_SCHED; PG8_LDA(At, 1, 0); PG8_STAGE(PG8_SA(0, 1), a2 + hstep, voffA);
;             PG8_WAIT_V(8); PG8_WAIT_L(0); PG8_BAR; PG8_MMA(0, 0, At, B0); PG8_MMA(0, 1, At, B1); PG8_BAR; PG8_SCHED;
;             PG8_LDA(At, 1, 1); PG8_STAGE(PG8_SB(1, 0), b3, voffB); PG8_STAGE(PG8_SB(1, 1), b3 + hstep, voffB); PG8_STAGE(PG8_SA(1, 0), a3, voffA);
;             PG8_WAIT_V(8); PG8_WAIT_L(0); PG8_BAR; PG8_MMA(1, 0, At, B0); PG8_MMA(1, 1, At, B1); PG8_BAR; PG8_SCHED;
	s_add_i32 s60, 0, 0x18000
	s_add_i32 s61, 0, 0x1c000
	v_add_u32_e32 v140, s60, v187
	v_add_u32_e32 v172, s61, v187
	ds_read_b128 v[128:131], v140
	ds_read_b128 v[132:135], v140 offset:1024
	ds_read_b128 v[136:139], v140 offset:2048
	ds_read_b128 v[140:143], v140 offset:3072
	ds_read_b128 v[144:147], v172
	ds_read_b128 v[148:151], v172 offset:1024
	ds_read_b128 v[168:171], v172 offset:2048
	ds_read_b128 v[172:175], v172 offset:3072
	s_add_u32 s10, s10, 0xb0000
	s_addc_u32 s11, s11, 0
	s_mov_b32 m0, s35
	ds_read_b128 v[176:179], v191 offset:32768
	ds_read_b128 v[180:183], v191 offset:33792
	ds_read_b128 v[194:197], v191 offset:34816
	ds_read_b128 v[198:201], v191 offset:35840
	ds_read_b128 v[202:205], v191 offset:36864
	ds_read_b128 v[206:209], v191 offset:37888
	ds_read_b128 v[210:213], v191 offset:38912
	ds_read_b128 v[214:217], v191 offset:39936
	global_load_lds_dwordx4 v152, s[10:11]
	s_mov_b32 m0, s36
	s_nop 0
	global_load_lds_dwordx4 v156, s[10:11]
	s_waitcnt vmcnt(8)
	s_waitcnt lgkmcnt(0)
	s_barrier
	s_waitcnt lgkmcnt(0)
	v_mfma_f32_16x16x32_bf16 v[124:127], v[128:131], v[176:179], v[124:127]
	v_mfma_f32_16x16x32_bf16 v[120:123], v[136:139], v[176:179], v[120:123]
	v_mfma_f32_16x16x32_bf16 v[108:111], v[128:131], v[194:197], v[108:111]
	v_mfma_f32_16x16x32_bf16 v[104:107], v[136:139], v[194:197], v[104:107]
	v_mfma_f32_16x16x32_bf16 v[92:95], v[128:131], v[202:205], v[92:95]
	v_mfma_f32_16x16x32_bf16 v[88:91], v[136:139], v[202:205], v[88:91]
	v_mfma_f32_16x16x32_bf16 v[76:79], v[128:131], v[210:213], v[76:79]
	v_mfma_f32_16x16x32_bf16 v[72:75], v[136:139], v[210:213], v[72:75]
	v_mfma_f32_16x16x32_bf16 v[124:127], v[132:135], v[180:183], v[124:127]
	v_mfma_f32_16x16x32_bf16 v[120:123], v[140:143], v[180:183], v[120:123]
	v_mfma_f32_16x16x32_bf16 v[108:111], v[132:135], v[198:201], v[108:111]
	v_mfma_f32_16x16x32_bf16 v[104:107], v[140:143], v[198:201], v[104:107]
	v_mfma_f32_16x16x32_bf16 v[92:95], v[132:135], v[206:209], v[92:95]
	v_mfma_f32_16x16x32_bf16 v[88:91], v[140:143], v[206:209], v[88:91]
	v_mfma_f32_16x16x32_bf16 v[76:79], v[132:135], v[214:217], v[76:79]
	v_mfma_f32_16x16x32_bf16 v[72:75], v[140:143], v[214:217], v[72:75]
	v_mfma_f32_16x16x32_bf16 v[116:119], v[144:147], v[176:179], v[116:119]
	v_mfma_f32_16x16x32_bf16 v[112:115], v[168:171], v[176:179], v[112:115]
	v_mfma_f32_16x16x32_bf16 v[100:103], v[144:147], v[194:197], v[100:103]
	v_mfma_f32_16x16x32_bf16 v[96:99], v[168:171], v[194:197], v[96:99]
	v_mfma_f32_16x16x32_bf16 v[84:87], v[144:147], v[202:205], v[84:87]
	v_mfma_f32_16x16x32_bf16 v[80:83], v[168:171], v[202:205], v[80:83]
	v_mfma_f32_16x16x32_bf16 v[68:71], v[144:147], v[210:213], v[68:71]
	v_mfma_f32_16x16x32_bf16 v[64:67], v[168:171], v[210:213], v[64:67]
	v_mfma_f32_16x16x32_bf16 v[116:119], v[148:151], v[180:183], v[116:119]
	v_mfma_f32_16x16x32_bf16 v[112:115], v[172:175], v[180:183], v[112:115]
	v_mfma_f32_16x16x32_bf16 v[100:103], v[148:151], v[198:201], v[100:103]
	v_mfma_f32_16x16x32_bf16 v[96:99], v[172:175], v[198:201], v[96:99]
	v_mfma_f32_16x16x32_bf16 v[84:87], v[148:151], v[206:209], v[84:87]
	v_mfma_f32_16x16x32_bf16 v[80:83], v[172:175], v[206:209], v[80:83]
	v_mfma_f32_16x16x32_bf16 v[68:71], v[148:151], v[214:217], v[68:71]
	v_mfma_f32_16x16x32_bf16 v[64:67], v[172:175], v[214:217], v[64:67]
	s_barrier
	s_add_i32 s10, s60, s31
	v_lshl_add_u64 v[184:185], v[184:185], 0, s[18:19]
	s_mov_b32 m0, s10
	ds_read_b128 v[176:179], v191 offset:49152
	ds_read_b128 v[180:183], v191 offset:50176
	ds_read_b128 v[194:197], v191 offset:51200
	ds_read_b128 v[198:201], v191 offset:52224
	ds_read_b128 v[202:205], v191 offset:53248
	ds_read_b128 v[206:209], v191 offset:54272
	ds_read_b128 v[210:213], v191 offset:55296
	ds_read_b128 v[214:217], v191 offset:56320
	global_load_lds_dwordx4 v[184:185], off
	s_add_i32 m0, s10, 0x2000
	s_add_u32 s6, s6, 0xb0080
	v_lshl_add_u64 v[184:185], v[218:219], 0, s[18:19]
	s_addc_u32 s7, s7, 0
	s_add_i32 s10, s61, s31
	global_load_lds_dwordx4 v[184:185], off
	s_mov_b32 m0, s10
	s_nop 0
	global_load_lds_dwordx4 v154, s[6:7]
	s_add_i32 m0, s10, 0x2000
	s_nop 0
	global_load_lds_dwordx4 v158, s[6:7]
	v_lshl_add_u64 v[184:185], v[222:223], 0, s[18:19]
	s_mov_b32 m0, s46
	s_nop 0
	global_load_lds_dwordx4 v[184:185], off
	v_lshl_add_u64 v[184:185], v[224:225], 0, s[18:19]
	s_mov_b32 m0, s47
	s_nop 0
	global_load_lds_dwordx4 v[184:185], off
	s_waitcnt vmcnt(8)
	s_waitcnt lgkmcnt(0)
	s_barrier
	s_waitcnt lgkmcnt(0)
	v_mfma_f32_16x16x32_bf16 v[60:63], v[128:131], v[176:179], v[60:63]
	v_mfma_f32_16x16x32_bf16 v[56:59], v[136:139], v[176:179], v[56:59]
	v_mfma_f32_16x16x32_bf16 v[44:47], v[128:131], v[194:197], v[44:47]
	v_mfma_f32_16x16x32_bf16 v[40:43], v[136:139], v[194:197], v[40:43]
	v_mfma_f32_16x16x32_bf16 v[28:31], v[128:131], v[202:205], v[28:31]
	v_mfma_f32_16x16x32_bf16 v[24:27], v[136:139], v[202:205], v[24:27]
	v_mfma_f32_16x16x32_bf16 v[12:15], v[128:131], v[210:213], v[12:15]
	v_mfma_f32_16x16x32_bf16 v[8:11], v[136:139], v[210:213], v[8:11]
	v_mfma_f32_16x16x32_bf16 v[60:63], v[132:135], v[180:183], v[60:63]
	v_mfma_f32_16x16x32_bf16 v[56:59], v[140:143], v[180:183], v[56:59]
	v_mfma_f32_16x16x32_bf16 v[44:47], v[132:135], v[198:201], v[44:47]
	v_mfma_f32_16x16x32_bf16 v[40:43], v[140:143], v[198:201], v[40:43]
	v_mfma_f32_16x16x32_bf16 v[28:31], v[132:135], v[206:209], v[28:31]
	v_mfma_f32_16x16x32_bf16 v[24:27], v[140:143], v[206:209], v[24:27]
	v_mfma_f32_16x16x32_bf16 v[12:15], v[132:135], v[214:217], v[12:15]
	v_mfma_f32_16x16x32_bf16 v[8:11], v[140:143], v[214:217], v[8:11]
	v_mfma_f32_16x16x32_bf16 v[52:55], v[144:147], v[176:179], v[52:55]
	v_mfma_f32_16x16x32_bf16 v[48:51], v[168:171], v[176:179], v[48:51]
	v_mfma_f32_16x16x32_bf16 v[36:39], v[144:147], v[194:197], v[36:39]
	v_mfma_f32_16x16x32_bf16 v[32:35], v[168:171], v[194:197], v[32:35]
	v_mfma_f32_16x16x32_bf16 v[20:23], v[144:147], v[202:205], v[20:23]
	v_mfma_f32_16x16x32_bf16 v[16:19], v[168:171], v[202:205], v[16:19]
	v_mfma_f32_16x16x32_bf16 v[4:7], v[144:147], v[210:213], v[4:7]
	v_mfma_f32_16x16x32_bf16 v[0:3], v[168:171], v[210:213], v[0:3]
	v_mfma_f32_16x16x32_bf16 v[52:55], v[148:151], v[180:183], v[52:55]
	v_mfma_f32_16x16x32_bf16 v[48:51], v[172:175], v[180:183], v[48:51]
	v_mfma_f32_16x16x32_bf16 v[36:39], v[148:151], v[198:201], v[36:39]
	v_mfma_f32_16x16x32_bf16 v[32:35], v[172:175], v[198:201], v[32:35]
	v_mfma_f32_16x16x32_bf16 v[20:23], v[148:151], v[206:209], v[20:23]
	v_mfma_f32_16x16x32_bf16 v[16:19], v[172:175], v[206:209], v[16:19]
	v_mfma_f32_16x16x32_bf16 v[4:7], v[148:151], v[214:217], v[4:7]
	v_mfma_f32_16x16x32_bf16 v[0:3], v[172:175], v[214:217], v[0:3]
	s_barrier
	s_add_i32 s59, s59, 2
	s_add_u32 s28, s28, 0x100
	s_addc_u32 s29, s29, 0
	s_add_u32 s57, s57, 0x100
	s_addc_u32 s58, s58, 0
	s_cmp_gt_u32 s59, 41
	s_cbranch_scc0 .LBB0_660
	s_and_b64 vcc, exec, s[20:21]
	s_cbranch_vccz .LBB0_663
	s_barrier

; #define PG8_STAGE(bufoff, gbase, voff) do { _Pragma("unroll") for (int _i = 0; _i < 2; ++_i) \
;         __builtin_amdgcn_global_load_lds((const unsigned*)((const char*)(gbase) + (voff)[_i]), (PG8_LAS unsigned*)(lds + (bufoff) + ldsw + _i * 8192), 16, 0, 0); } while (0)
; #define PG8_LDA(dst, b, h) do { _Pragma("unroll") for (int m = 0; m < 4; ++m) _Pragma("unroll") for (int k = 0; k < 2; ++k) dst[m][k] = *(const PG8_LAS bf16x8*)(lds + PG8_SA(b, h) + aoff + m * 2048 + k * 1024); } while (0)
; #define PG8_LDB(dst, b, h) do { _Pragma("unroll") for (int n = 0; n < 2; ++n) _Pragma("unroll") for (int k = 0; k < 2; ++k) dst[n][k] = *(const PG8_LAS bf16x8*)(lds + PG8_SB(b, h) + boff + n * 2048 + k * 1024); } while (0)
; #define PG8_MMA(ai, bj, At, Bt) do { __builtin_amdgcn_s_setprio(1); _Pragma("unroll") for (int m = 0; m < 4; ++m) _Pragma("unroll") for (int n = 0; n < 2; ++n) _Pragma("unroll") for (int k = 0; k < 2; ++k) \
;         acc[ai][bj][m][n] = __builtin_amdgcn_mfma_f32_16x16x32_bf16(Bt[n][k], At[m][k], acc[ai][bj][m][n], 0, 0, 0); __builtin_amdgcn_s_setprio(0); } while (0)
; #define PG8_WAIT_V(n) asm volatile("s_waitcnt vmcnt(" #n ")" ::: "memory")
; #define PG8_WAIT_L(n) asm volatile("s_waitcnt lgkmcnt(" #n ")" ::: "memory")
; #define PG8_BAR __builtin_amdgcn_s_barrier()
; #define PG8_SCHED __builtin_amdgcn_sched_barrier(0)
; template <class Epi, class Sched, bool ALIGN_EPI = false, bool SP2 = false>
; __device__ __forceinline__ void gemm_phase(PG8_LAS unsigned char* lds, const Gemm g, const Sched& S, const Epi& E) {
;     ...
;             PG8_LDB(B0, 0, 0); PG8_LDB(B1, 0, 1); PG8_SCHED; PG8_LDA(At, 0, 0); PG8_STAGE(PG8_SA(1, 1), a1 + hstep, voffA);
;             PG8_WAIT_V(8); PG8_WAIT_L(0); PG8_BAR; PG8_MMA(0, 0, At, B0); PG8_MMA(0, 1, At, B1); PG8_BAR; PG8_SCHED;
;             PG8_LDA(At, 0, 1); PG8_STAGE(PG8_SB(0, 0), b2, voffB); PG8_STAGE(PG8_SB(0, 1), b2 + hstep, voffB); PG8_STAGE(PG8_SA(0, 0), a2, voffA);
;             PG8_WAIT_V(8); PG8_WAIT_L(0); PG8_BAR; PG8_MMA(1, 0, At, B0); PG8_MMA(1, 1, At, B1); PG8_BAR; PG8_SCHED;
.LBB0_814:
	ds_read_b128 v[128:131], v176
	ds_read_b128 v[132:135], v176 offset:1024
	ds_read_b128 v[136:139], v176 offset:2048
	ds_read_b128 v[140:143], v176 offset:3072
	ds_read_b128 v[164:167], v177
	ds_read_b128 v[180:183], v177 offset:1024
	ds_read_b128 v[184:187], v177 offset:2048
	ds_read_b128 v[188:191], v177 offset:3072
	s_add_u32 s6, s36, 0xfffc0080
	s_addc_u32 s7, s37, -1
	s_cmp_eq_u32 s62, 12
	s_cselect_b32 s11, s27, s7
	s_cselect_b32 s10, s58, s6
	s_cselect_b32 s7, s21, s61
	s_cselect_b32 s6, s59, s60
	s_add_i32 m0, s46, 0xc000
	ds_read_b128 v[192:195], v178
	ds_read_b128 v[196:199], v178 offset:1024
	ds_read_b128 v[200:203], v178 offset:2048
	ds_read_b128 v[204:207], v178 offset:3072
	ds_read_b128 v[208:211], v178 offset:4096
	ds_read_b128 v[212:215], v178 offset:5120
	ds_read_b128 v[216:219], v178 offset:6144
	ds_read_b128 v[222:225], v178 offset:7168
	global_load_lds_dwordx4 v156, s[36:37]
	s_add_i32 m0, s46, 0xe000
	s_nop 0
	global_load_lds_dwordx4 v158, s[36:37]
	s_waitcnt vmcnt(8)
	s_waitcnt lgkmcnt(0)
	s_barrier
	s_waitcnt lgkmcnt(0)
	v_mfma_f32_16x16x32_bf16 v[124:127], v[128:131], v[192:195], v[124:127]
	v_mfma_f32_16x16x32_bf16 v[120:123], v[136:139], v[192:195], v[120:123]
	v_mfma_f32_16x16x32_bf16 v[108:111], v[128:131], v[200:203], v[108:111]
	v_mfma_f32_16x16x32_bf16 v[104:107], v[136:139], v[200:203], v[104:107]
	v_mfma_f32_16x16x32_bf16 v[92:95], v[128:131], v[208:211], v[92:95]
	v_mfma_f32_16x16x32_bf16 v[88:91], v[136:139], v[208:211], v[88:91]
	v_mfma_f32_16x16x32_bf16 v[76:79], v[128:131], v[216:219], v[76:79]
	v_mfma_f32_16x16x32_bf16 v[72:75], v[136:139], v[216:219], v[72:75]
	v_mfma_f32_16x16x32_bf16 v[124:127], v[132:135], v[196:199], v[124:127]
	v_mfma_f32_16x16x32_bf16 v[120:123], v[140:143], v[196:199], v[120:123]
	v_mfma_f32_16x16x32_bf16 v[108:111], v[132:135], v[204:207], v[108:111]
	v_mfma_f32_16x16x32_bf16 v[104:107], v[140:143], v[204:207], v[104:107]
	v_mfma_f32_16x16x32_bf16 v[92:95], v[132:135], v[212:215], v[92:95]
	v_mfma_f32_16x16x32_bf16 v[88:91], v[140:143], v[212:215], v[88:91]
	v_mfma_f32_16x16x32_bf16 v[76:79], v[132:135], v[222:225], v[76:79]
	v_mfma_f32_16x16x32_bf16 v[72:75], v[140:143], v[222:225], v[72:75]
	v_mfma_f32_16x16x32_bf16 v[116:119], v[164:167], v[192:195], v[116:119]
	v_mfma_f32_16x16x32_bf16 v[112:115], v[184:187], v[192:195], v[112:115]
	v_mfma_f32_16x16x32_bf16 v[100:103], v[164:167], v[200:203], v[100:103]
	v_mfma_f32_16x16x32_bf16 v[96:99], v[184:187], v[200:203], v[96:99]
	v_mfma_f32_16x16x32_bf16 v[84:87], v[164:167], v[208:211], v[84:87]
	v_mfma_f32_16x16x32_bf16 v[80:83], v[184:187], v[208:211], v[80:83]
	v_mfma_f32_16x16x32_bf16 v[68:71], v[164:167], v[216:219], v[68:71]
	v_mfma_f32_16x16x32_bf16 v[64:67], v[184:187], v[216:219], v[64:67]
	v_mfma_f32_16x16x32_bf16 v[116:119], v[180:183], v[196:199], v[116:119]
	v_mfma_f32_16x16x32_bf16 v[112:115], v[188:191], v[196:199], v[112:115]
	v_mfma_f32_16x16x32_bf16 v[100:103], v[180:183], v[204:207], v[100:103]
	v_mfma_f32_16x16x32_bf16 v[96:99], v[188:191], v[204:207], v[96:99]
	v_mfma_f32_16x16x32_bf16 v[84:87], v[180:183], v[212:215], v[84:87]
	v_mfma_f32_16x16x32_bf16 v[80:83], v[188:191], v[212:215], v[80:83]
	v_mfma_f32_16x16x32_bf16 v[68:71], v[180:183], v[222:225], v[68:71]
	v_mfma_f32_16x16x32_bf16 v[64:67], v[188:191], v[222:225], v[64:67]
	s_barrier
	s_add_i32 s63, s55, s33
	v_lshl_add_u64 v[226:227], s[6:7], 0, v[148:149]
	s_mov_b32 m0, s63
	ds_read_b128 v[192:195], v178 offset:16384
	ds_read_b128 v[196:199], v178 offset:17408
	ds_read_b128 v[200:203], v178 offset:18432
	ds_read_b128 v[204:207], v178 offset:19456
	ds_read_b128 v[208:211], v178 offset:20480
	ds_read_b128 v[212:215], v178 offset:21504
	ds_read_b128 v[216:219], v178 offset:22528
	ds_read_b128 v[222:225], v178 offset:23552
	global_load_lds_dwordx4 v[226:227], off
	s_add_i32 m0, s63, 0x2000
	s_add_u32 s64, s6, 0x40000
	v_lshl_add_u64 v[228:229], s[6:7], 0, v[152:153]
	s_addc_u32 s65, s7, 0
	s_add_i32 s63, s56, s33
	global_load_lds_dwordx4 v[228:229], off
	s_mov_b32 m0, s63
	v_lshl_add_u64 v[232:233], s[10:11], 0, v[150:151]
	global_load_lds_dwordx4 v148, s[64:65]
	s_add_i32 m0, s63, 0x2000
	s_nop 0
	global_load_lds_dwordx4 v152, s[64:65]
	v_lshl_add_u64 v[230:231], s[10:11], 0, v[146:147]
	s_mov_b32 m0, s46
	s_nop 0
	global_load_lds_dwordx4 v[230:231], off
	s_mov_b32 m0, s47
	s_nop 0
	global_load_lds_dwordx4 v[232:233], off
	s_waitcnt vmcnt(8)
	s_waitcnt lgkmcnt(0)
	s_barrier
	s_waitcnt lgkmcnt(0)
	v_mfma_f32_16x16x32_bf16 v[60:63], v[128:131], v[192:195], v[60:63]
	v_mfma_f32_16x16x32_bf16 v[56:59], v[136:139], v[192:195], v[56:59]
	v_mfma_f32_16x16x32_bf16 v[44:47], v[128:131], v[200:203], v[44:47]
	v_mfma_f32_16x16x32_bf16 v[40:43], v[136:139], v[200:203], v[40:43]
	v_mfma_f32_16x16x32_bf16 v[28:31], v[128:131], v[208:211], v[28:31]
	v_mfma_f32_16x16x32_bf16 v[24:27], v[136:139], v[208:211], v[24:27]
	v_mfma_f32_16x16x32_bf16 v[12:15], v[128:131], v[216:219], v[12:15]
	v_mfma_f32_16x16x32_bf16 v[8:11], v[136:139], v[216:219], v[8:11]
	v_mfma_f32_16x16x32_bf16 v[60:63], v[132:135], v[196:199], v[60:63]
	v_mfma_f32_16x16x32_bf16 v[56:59], v[140:143], v[196:199], v[56:59]
	v_mfma_f32_16x16x32_bf16 v[44:47], v[132:135], v[204:207], v[44:47]
	v_mfma_f32_16x16x32_bf16 v[40:43], v[140:143], v[204:207], v[40:43]
	v_mfma_f32_16x16x32_bf16 v[28:31], v[132:135], v[212:215], v[28:31]
	v_mfma_f32_16x16x32_bf16 v[24:27], v[140:143], v[212:215], v[24:27]
	v_mfma_f32_16x16x32_bf16 v[12:15], v[132:135], v[222:225], v[12:15]
	v_mfma_f32_16x16x32_bf16 v[8:11], v[140:143], v[222:225], v[8:11]
	v_mfma_f32_16x16x32_bf16 v[52:55], v[164:167], v[192:195], v[52:55]
	v_mfma_f32_16x16x32_bf16 v[48:51], v[184:187], v[192:195], v[48:51]
	v_mfma_f32_16x16x32_bf16 v[36:39], v[164:167], v[200:203], v[36:39]
	v_mfma_f32_16x16x32_bf16 v[32:35], v[184:187], v[200:203], v[32:35]
	v_mfma_f32_16x16x32_bf16 v[20:23], v[164:167], v[208:211], v[20:23]
	v_mfma_f32_16x16x32_bf16 v[16:19], v[184:187], v[208:211], v[16:19]
	v_mfma_f32_16x16x32_bf16 v[4:7], v[164:167], v[216:219], v[4:7]
	v_mfma_f32_16x16x32_bf16 v[0:3], v[184:187], v[216:219], v[0:3]
	v_mfma_f32_16x16x32_bf16 v[52:55], v[180:183], v[196:199], v[52:55]
	v_mfma_f32_16x16x32_bf16 v[48:51], v[188:191], v[196:199], v[48:51]
	v_mfma_f32_16x16x32_bf16 v[36:39], v[180:183], v[204:207], v[36:39]
	v_mfma_f32_16x16x32_bf16 v[32:35], v[188:191], v[204:207], v[32:35]
	v_mfma_f32_16x16x32_bf16 v[20:23], v[180:183], v[212:215], v[20:23]
	v_mfma_f32_16x16x32_bf16 v[16:19], v[188:191], v[212:215], v[16:19]
	v_mfma_f32_16x16x32_bf16 v[4:7], v[180:183], v[222:225], v[4:7]
	v_mfma_f32_16x16x32_bf16 v[0:3], v[188:191], v[222:225], v[0:3]
	s_barrier
; #define PG8_STAGE(bufoff, gbase, voff) do { _Pragma("unroll") for (int _i = 0; _i < 2; ++_i) \
;         __builtin_amdgcn_global_load_lds((const unsigned*)((const char*)(gbase) + (voff)[_i]), (PG8_LAS unsigned*)(lds + (bufoff) + ldsw + _i * 8192), 16, 0, 0); } while (0)
; #define PG8_LDA(dst, b, h) do { _Pragma("unroll") for (int m = 0; m < 4; ++m) _Pragma("unroll") for (int k = 0; k < 2; ++k) dst[m][k] = *(const PG8_LAS bf16x8*)(lds + PG8_SA(b, h) + aoff + m * 2048 + k * 1024); } while (0)
; #define PG8_LDB(dst, b, h) do { _Pragma("unroll") for (int n = 0; n < 2; ++n) _Pragma("unroll") for (int k = 0; k < 2; ++k) dst[n][k] = *(const PG8_LAS bf16x8*)(lds + PG8_SB(b, h) + boff + n * 2048 + k * 1024); } while (0)
; #define PG8_MMA(ai, bj, At, Bt) do { __builtin_amdgcn_s_setprio(1); _Pragma("unroll") for (int m = 0; m < 4; ++m) _Pragma("unroll") for (int n = 0; n < 2; ++n) _Pragma("unroll") for (int k = 0; k < 2; ++k) \
;         acc[ai][bj][m][n] = __builtin_amdgcn_mfma_f32_16x16x32_bf16(Bt[n][k], At[m][k], acc[ai][bj][m][n], 0, 0, 0); __builtin_amdgcn_s_setprio(0); } while (0)
; #define PG8_WAIT_V(n) asm volatile("s_waitcnt vmcnt(" #n ")" ::: "memory")
; #define PG8_WAIT_L(n) asm volatile("s_waitcnt lgkmcnt(" #n ")" ::: "memory")
; #define PG8_BAR __builtin_amdgcn_s_barrier()
; #define PG8_SCHED __builtin_amdgcn_sched_barrier(0)
; template <class Epi, class Sched, bool ALIGN_EPI = false, bool SP2 = false>
; __device__ __forceinline__ void gemm_phase(PG8_LAS unsigned char* lds, const Gemm g, const Sched& S, const Epi& E) {
;     ...
;         for (int t = 0; t < nt; t += 2) {
;             const bool last = (t == nt - 2);
;     ...
;             PG8_LDB(B0, 1, 0); PG8_LDB(B1, 1, 1); PG8_SCHED; PG8_LDA(At, 1, 0); PG8_STAGE(PG8_SA(0, 1), a2 + hstep, voffA);
;             PG8_WAIT_V(8); PG8_WAIT_L(0); PG8_BAR; PG8_MMA(0, 0, At, B0); PG8_MMA(0, 1, At, B1); PG8_BAR; PG8_SCHED;
;             PG8_LDA(At, 1, 1); PG8_STAGE(PG8_SB(1, 0), b3, voffB); PG8_STAGE(PG8_SB(1, 1), b3 + hstep, voffB); PG8_STAGE(PG8_SA(1, 0), a3, voffA);
;             PG8_WAIT_V(8); PG8_WAIT_L(0); PG8_BAR; PG8_MMA(1, 0, At, B0); PG8_MMA(1, 1, At, B1); PG8_BAR; PG8_SCHED;
	s_add_i32 s63, 0, 0x18000
	s_add_i32 s64, 0, 0x1c000
	v_add_u32_e32 v140, s63, v175
	v_add_u32_e32 v179, s64, v175
	ds_read_b128 v[128:131], v140
	ds_read_b128 v[132:135], v140 offset:1024
	ds_read_b128 v[136:139], v140 offset:2048
	ds_read_b128 v[140:143], v140 offset:3072
	ds_read_b128 v[164:167], v179
	ds_read_b128 v[180:183], v179 offset:1024
	ds_read_b128 v[184:187], v179 offset:2048
	ds_read_b128 v[188:191], v179 offset:3072
	s_add_u32 s10, s10, 0x40000
	s_addc_u32 s11, s11, 0
	s_mov_b32 m0, s48
	ds_read_b128 v[192:195], v178 offset:32768
	ds_read_b128 v[196:199], v178 offset:33792
	ds_read_b128 v[200:203], v178 offset:34816
	ds_read_b128 v[204:207], v178 offset:35840
	ds_read_b128 v[208:211], v178 offset:36864
	ds_read_b128 v[212:215], v178 offset:37888
	ds_read_b128 v[216:219], v178 offset:38912
	ds_read_b128 v[222:225], v178 offset:39936
	global_load_lds_dwordx4 v146, s[10:11]
	s_mov_b32 m0, s49
	s_nop 0
	global_load_lds_dwordx4 v150, s[10:11]
	s_waitcnt vmcnt(8)
	s_waitcnt lgkmcnt(0)
	s_barrier
	s_waitcnt lgkmcnt(0)
	v_mfma_f32_16x16x32_bf16 v[124:127], v[128:131], v[192:195], v[124:127]
	v_mfma_f32_16x16x32_bf16 v[120:123], v[136:139], v[192:195], v[120:123]
	v_mfma_f32_16x16x32_bf16 v[108:111], v[128:131], v[200:203], v[108:111]
	v_mfma_f32_16x16x32_bf16 v[104:107], v[136:139], v[200:203], v[104:107]
	v_mfma_f32_16x16x32_bf16 v[92:95], v[128:131], v[208:211], v[92:95]
	v_mfma_f32_16x16x32_bf16 v[88:91], v[136:139], v[208:211], v[88:91]
	v_mfma_f32_16x16x32_bf16 v[76:79], v[128:131], v[216:219], v[76:79]
	v_mfma_f32_16x16x32_bf16 v[72:75], v[136:139], v[216:219], v[72:75]
	v_mfma_f32_16x16x32_bf16 v[124:127], v[132:135], v[196:199], v[124:127]
	v_mfma_f32_16x16x32_bf16 v[120:123], v[140:143], v[196:199], v[120:123]
	v_mfma_f32_16x16x32_bf16 v[108:111], v[132:135], v[204:207], v[108:111]
	v_mfma_f32_16x16x32_bf16 v[104:107], v[140:143], v[204:207], v[104:107]
	v_mfma_f32_16x16x32_bf16 v[92:95], v[132:135], v[212:215], v[92:95]
	v_mfma_f32_16x16x32_bf16 v[88:91], v[140:143], v[212:215], v[88:91]
	v_mfma_f32_16x16x32_bf16 v[76:79], v[132:135], v[222:225], v[76:79]
	v_mfma_f32_16x16x32_bf16 v[72:75], v[140:143], v[222:225], v[72:75]
	v_mfma_f32_16x16x32_bf16 v[116:119], v[164:167], v[192:195], v[116:119]
	v_mfma_f32_16x16x32_bf16 v[112:115], v[184:187], v[192:195], v[112:115]
	v_mfma_f32_16x16x32_bf16 v[100:103], v[164:167], v[200:203], v[100:103]
	v_mfma_f32_16x16x32_bf16 v[96:99], v[184:187], v[200:203], v[96:99]
	v_mfma_f32_16x16x32_bf16 v[84:87], v[164:167], v[208:211], v[84:87]
	v_mfma_f32_16x16x32_bf16 v[80:83], v[184:187], v[208:211], v[80:83]
	v_mfma_f32_16x16x32_bf16 v[68:71], v[164:167], v[216:219], v[68:71]
	v_mfma_f32_16x16x32_bf16 v[64:67], v[184:187], v[216:219], v[64:67]
	v_mfma_f32_16x16x32_bf16 v[116:119], v[180:183], v[196:199], v[116:119]
	v_mfma_f32_16x16x32_bf16 v[112:115], v[188:191], v[196:199], v[112:115]
	v_mfma_f32_16x16x32_bf16 v[100:103], v[180:183], v[204:207], v[100:103]
	v_mfma_f32_16x16x32_bf16 v[96:99], v[188:191], v[204:207], v[96:99]
	v_mfma_f32_16x16x32_bf16 v[84:87], v[180:183], v[212:215], v[84:87]
	v_mfma_f32_16x16x32_bf16 v[80:83], v[188:191], v[212:215], v[80:83]
	v_mfma_f32_16x16x32_bf16 v[68:71], v[180:183], v[222:225], v[68:71]
	v_mfma_f32_16x16x32_bf16 v[64:67], v[188:191], v[222:225], v[64:67]
	s_barrier
	s_add_i32 s10, s63, s33
	v_lshl_add_u64 v[226:227], v[226:227], 0, s[16:17]
	s_mov_b32 m0, s10
	ds_read_b128 v[192:195], v178 offset:49152
	ds_read_b128 v[196:199], v178 offset:50176
	ds_read_b128 v[200:203], v178 offset:51200
	ds_read_b128 v[204:207], v178 offset:52224
	ds_read_b128 v[208:211], v178 offset:53248
	ds_read_b128 v[212:215], v178 offset:54272
	ds_read_b128 v[216:219], v178 offset:55296
	ds_read_b128 v[222:225], v178 offset:56320
	global_load_lds_dwordx4 v[226:227], off
	s_add_i32 m0, s10, 0x2000
	s_add_u32 s6, s6, 0x40080
	v_lshl_add_u64 v[226:227], v[228:229], 0, s[16:17]
	s_addc_u32 s7, s7, 0
	s_add_i32 s10, s64, s33
	global_load_lds_dwordx4 v[226:227], off
	s_mov_b32 m0, s10
	s_nop 0
	global_load_lds_dwordx4 v148, s[6:7]
	s_add_i32 m0, s10, 0x2000
	s_nop 0
	global_load_lds_dwordx4 v152, s[6:7]
	v_lshl_add_u64 v[226:227], v[230:231], 0, s[16:17]
	s_mov_b32 m0, s51
	s_nop 0
	global_load_lds_dwordx4 v[226:227], off
	v_lshl_add_u64 v[226:227], v[232:233], 0, s[16:17]
	s_mov_b32 m0, s52
	s_nop 0
	global_load_lds_dwordx4 v[226:227], off
	s_waitcnt vmcnt(8)
	s_waitcnt lgkmcnt(0)
	s_barrier
	s_waitcnt lgkmcnt(0)
	v_mfma_f32_16x16x32_bf16 v[60:63], v[128:131], v[192:195], v[60:63]
	v_mfma_f32_16x16x32_bf16 v[56:59], v[136:139], v[192:195], v[56:59]
	v_mfma_f32_16x16x32_bf16 v[44:47], v[128:131], v[200:203], v[44:47]
	v_mfma_f32_16x16x32_bf16 v[40:43], v[136:139], v[200:203], v[40:43]
	v_mfma_f32_16x16x32_bf16 v[28:31], v[128:131], v[208:211], v[28:31]
	v_mfma_f32_16x16x32_bf16 v[24:27], v[136:139], v[208:211], v[24:27]
	v_mfma_f32_16x16x32_bf16 v[12:15], v[128:131], v[216:219], v[12:15]
	v_mfma_f32_16x16x32_bf16 v[8:11], v[136:139], v[216:219], v[8:11]
	v_mfma_f32_16x16x32_bf16 v[60:63], v[132:135], v[196:199], v[60:63]
	v_mfma_f32_16x16x32_bf16 v[56:59], v[140:143], v[196:199], v[56:59]
	v_mfma_f32_16x16x32_bf16 v[44:47], v[132:135], v[204:207], v[44:47]
	v_mfma_f32_16x16x32_bf16 v[40:43], v[140:143], v[204:207], v[40:43]
	v_mfma_f32_16x16x32_bf16 v[28:31], v[132:135], v[212:215], v[28:31]
	v_mfma_f32_16x16x32_bf16 v[24:27], v[140:143], v[212:215], v[24:27]
	v_mfma_f32_16x16x32_bf16 v[12:15], v[132:135], v[222:225], v[12:15]
	v_mfma_f32_16x16x32_bf16 v[8:11], v[140:143], v[222:225], v[8:11]
	v_mfma_f32_16x16x32_bf16 v[52:55], v[164:167], v[192:195], v[52:55]
	v_mfma_f32_16x16x32_bf16 v[48:51], v[184:187], v[192:195], v[48:51]
	v_mfma_f32_16x16x32_bf16 v[36:39], v[164:167], v[200:203], v[36:39]
	v_mfma_f32_16x16x32_bf16 v[32:35], v[184:187], v[200:203], v[32:35]
	v_mfma_f32_16x16x32_bf16 v[20:23], v[164:167], v[208:211], v[20:23]
	v_mfma_f32_16x16x32_bf16 v[16:19], v[184:187], v[208:211], v[16:19]
	v_mfma_f32_16x16x32_bf16 v[4:7], v[164:167], v[216:219], v[4:7]
	v_mfma_f32_16x16x32_bf16 v[0:3], v[184:187], v[216:219], v[0:3]
	v_mfma_f32_16x16x32_bf16 v[52:55], v[180:183], v[196:199], v[52:55]
	v_mfma_f32_16x16x32_bf16 v[48:51], v[188:191], v[196:199], v[48:51]
	v_mfma_f32_16x16x32_bf16 v[36:39], v[180:183], v[204:207], v[36:39]
	v_mfma_f32_16x16x32_bf16 v[32:35], v[188:191], v[204:207], v[32:35]
	v_mfma_f32_16x16x32_bf16 v[20:23], v[180:183], v[212:215], v[20:23]
	v_mfma_f32_16x16x32_bf16 v[16:19], v[188:191], v[212:215], v[16:19]
	v_mfma_f32_16x16x32_bf16 v[4:7], v[180:183], v[222:225], v[4:7]
	v_mfma_f32_16x16x32_bf16 v[0:3], v[188:191], v[222:225], v[0:3]
	s_barrier
	s_add_i32 s62, s62, 2
	s_add_u32 s36, s36, 0x100
	s_addc_u32 s37, s37, 0
	s_add_u32 s60, s60, 0x100
	s_addc_u32 s61, s61, 0
	s_cmp_gt_u32 s62, 13
	s_cbranch_scc0 .LBB0_814
	s_and_b64 vcc, exec, s[18:19]
	s_cbranch_vccz .LBB0_817
	s_barrier

; #define PG8_STAGE(bufoff, gbase, voff) do { _Pragma("unroll") for (int _i = 0; _i < 2; ++_i) \
;         __builtin_amdgcn_global_load_lds((const unsigned*)((const char*)(gbase) + (voff)[_i]), (PG8_LAS unsigned*)(lds + (bufoff) + ldsw + _i * 8192), 16, 0, 0); } while (0)
; #define PG8_LDA(dst, b, h) do { _Pragma("unroll") for (int m = 0; m < 4; ++m) _Pragma("unroll") for (int k = 0; k < 2; ++k) dst[m][k] = *(const PG8_LAS bf16x8*)(lds + PG8_SA(b, h) + aoff + m * 2048 + k * 1024); } while (0)
; #define PG8_LDB(dst, b, h) do { _Pragma("unroll") for (int n = 0; n < 2; ++n) _Pragma("unroll") for (int k = 0; k < 2; ++k) dst[n][k] = *(const PG8_LAS bf16x8*)(lds + PG8_SB(b, h) + boff + n * 2048 + k * 1024); } while (0)
; #define PG8_MMA(ai, bj, At, Bt) do { __builtin_amdgcn_s_setprio(1); _Pragma("unroll") for (int m = 0; m < 4; ++m) _Pragma("unroll") for (int n = 0; n < 2; ++n) _Pragma("unroll") for (int k = 0; k < 2; ++k) \
;         acc[ai][bj][m][n] = __builtin_amdgcn_mfma_f32_16x16x32_bf16(Bt[n][k], At[m][k], acc[ai][bj][m][n], 0, 0, 0); __builtin_amdgcn_s_setprio(0); } while (0)
; #define PG8_WAIT_V(n) asm volatile("s_waitcnt vmcnt(" #n ")" ::: "memory")
; #define PG8_WAIT_L(n) asm volatile("s_waitcnt lgkmcnt(" #n ")" ::: "memory")
; #define PG8_BAR __builtin_amdgcn_s_barrier()
; #define PG8_SCHED __builtin_amdgcn_sched_barrier(0)
; template <class Epi, class Sched, bool ALIGN_EPI = false, bool SP2 = false>
; __device__ __forceinline__ void gemm_phase(PG8_LAS unsigned char* lds, const Gemm g, const Sched& S, const Epi& E) {
;     ...
;             PG8_LDB(B0, 0, 0); PG8_LDB(B1, 0, 1); PG8_SCHED; PG8_LDA(At, 0, 0); PG8_STAGE(PG8_SA(1, 1), a1 + hstep, voffA);
;             PG8_WAIT_V(8); PG8_WAIT_L(0); PG8_BAR; PG8_MMA(0, 0, At, B0); PG8_MMA(0, 1, At, B1); PG8_BAR; PG8_SCHED;
;             PG8_LDA(At, 0, 1); PG8_STAGE(PG8_SB(0, 0), b2, voffB); PG8_STAGE(PG8_SB(0, 1), b2 + hstep, voffB); PG8_STAGE(PG8_SA(0, 0), a2, voffA);
;             PG8_WAIT_V(8); PG8_WAIT_L(0); PG8_BAR; PG8_MMA(1, 0, At, B0); PG8_MMA(1, 1, At, B1); PG8_BAR; PG8_SCHED;
.LBB0_838:
	ds_read_b128 v[128:131], v170
	ds_read_b128 v[132:135], v170 offset:1024
	ds_read_b128 v[136:139], v170 offset:2048
	ds_read_b128 v[140:143], v170 offset:3072
	ds_read_b128 v[166:169], v171
	ds_read_b128 v[174:177], v171 offset:1024
	ds_read_b128 v[178:181], v171 offset:2048
	ds_read_b128 v[182:185], v171 offset:3072
	s_add_u32 s6, s30, 0xfffc0080
	s_addc_u32 s7, s31, -1
	s_cmp_eq_u32 s65, 12
	s_cselect_b32 s35, s21, s7
	s_cselect_b32 s34, s61, s6
	s_cselect_b32 s7, s19, s64
	s_cselect_b32 s6, s62, s63
	s_add_i32 m0, s46, 0xc000
	ds_read_b128 v[186:189], v173
	ds_read_b128 v[190:193], v173 offset:1024
	ds_read_b128 v[194:197], v173 offset:2048
	ds_read_b128 v[198:201], v173 offset:3072
	ds_read_b128 v[202:205], v173 offset:4096
	ds_read_b128 v[206:209], v173 offset:5120
	ds_read_b128 v[210:213], v173 offset:6144
	ds_read_b128 v[214:217], v173 offset:7168
	global_load_lds_dwordx4 v156, s[30:31]
	s_add_i32 m0, s46, 0xe000
	s_nop 0
	global_load_lds_dwordx4 v158, s[30:31]
	s_waitcnt vmcnt(8)
	s_waitcnt lgkmcnt(0)
	s_barrier
	s_waitcnt lgkmcnt(0)
	v_mfma_f32_16x16x32_bf16 v[124:127], v[128:131], v[186:189], v[124:127]
	v_mfma_f32_16x16x32_bf16 v[120:123], v[136:139], v[186:189], v[120:123]
	v_mfma_f32_16x16x32_bf16 v[108:111], v[128:131], v[194:197], v[108:111]
	v_mfma_f32_16x16x32_bf16 v[104:107], v[136:139], v[194:197], v[104:107]
	v_mfma_f32_16x16x32_bf16 v[92:95], v[128:131], v[202:205], v[92:95]
	v_mfma_f32_16x16x32_bf16 v[88:91], v[136:139], v[202:205], v[88:91]
	v_mfma_f32_16x16x32_bf16 v[76:79], v[128:131], v[210:213], v[76:79]
	v_mfma_f32_16x16x32_bf16 v[72:75], v[136:139], v[210:213], v[72:75]
	v_mfma_f32_16x16x32_bf16 v[124:127], v[132:135], v[190:193], v[124:127]
	v_mfma_f32_16x16x32_bf16 v[120:123], v[140:143], v[190:193], v[120:123]
	v_mfma_f32_16x16x32_bf16 v[108:111], v[132:135], v[198:201], v[108:111]
	v_mfma_f32_16x16x32_bf16 v[104:107], v[140:143], v[198:201], v[104:107]
	v_mfma_f32_16x16x32_bf16 v[92:95], v[132:135], v[206:209], v[92:95]
	v_mfma_f32_16x16x32_bf16 v[88:91], v[140:143], v[206:209], v[88:91]
	v_mfma_f32_16x16x32_bf16 v[76:79], v[132:135], v[214:217], v[76:79]
	v_mfma_f32_16x16x32_bf16 v[72:75], v[140:143], v[214:217], v[72:75]
	v_mfma_f32_16x16x32_bf16 v[116:119], v[166:169], v[186:189], v[116:119]
	v_mfma_f32_16x16x32_bf16 v[112:115], v[178:181], v[186:189], v[112:115]
	v_mfma_f32_16x16x32_bf16 v[100:103], v[166:169], v[194:197], v[100:103]
	v_mfma_f32_16x16x32_bf16 v[96:99], v[178:181], v[194:197], v[96:99]
	v_mfma_f32_16x16x32_bf16 v[84:87], v[166:169], v[202:205], v[84:87]
	v_mfma_f32_16x16x32_bf16 v[80:83], v[178:181], v[202:205], v[80:83]
	v_mfma_f32_16x16x32_bf16 v[68:71], v[166:169], v[210:213], v[68:71]
	v_mfma_f32_16x16x32_bf16 v[64:67], v[178:181], v[210:213], v[64:67]
	v_mfma_f32_16x16x32_bf16 v[116:119], v[174:177], v[190:193], v[116:119]
	v_mfma_f32_16x16x32_bf16 v[112:115], v[182:185], v[190:193], v[112:115]
	v_mfma_f32_16x16x32_bf16 v[100:103], v[174:177], v[198:201], v[100:103]
	v_mfma_f32_16x16x32_bf16 v[96:99], v[182:185], v[198:201], v[96:99]
	v_mfma_f32_16x16x32_bf16 v[84:87], v[174:177], v[206:209], v[84:87]
	v_mfma_f32_16x16x32_bf16 v[80:83], v[182:185], v[206:209], v[80:83]
	v_mfma_f32_16x16x32_bf16 v[68:71], v[174:177], v[214:217], v[68:71]
	v_mfma_f32_16x16x32_bf16 v[64:67], v[182:185], v[214:217], v[64:67]
	s_barrier
	s_add_i32 s66, s59, s37
	v_lshl_add_u64 v[218:219], s[6:7], 0, v[148:149]
	s_mov_b32 m0, s66
	ds_read_b128 v[186:189], v173 offset:16384
	ds_read_b128 v[190:193], v173 offset:17408
	ds_read_b128 v[194:197], v173 offset:18432
	ds_read_b128 v[198:201], v173 offset:19456
	ds_read_b128 v[202:205], v173 offset:20480
	ds_read_b128 v[206:209], v173 offset:21504
	ds_read_b128 v[210:213], v173 offset:22528
	ds_read_b128 v[214:217], v173 offset:23552
	global_load_lds_dwordx4 v[218:219], off
	s_add_i32 m0, s66, 0x2000
	s_add_u32 s66, s6, 0x40000
	v_lshl_add_u64 v[222:223], s[6:7], 0, v[152:153]
	s_addc_u32 s67, s7, 0
	s_add_i32 s76, s60, s37
	global_load_lds_dwordx4 v[222:223], off
	s_mov_b32 m0, s76
	v_lshl_add_u64 v[226:227], s[34:35], 0, v[150:151]
	global_load_lds_dwordx4 v148, s[66:67]
	s_add_i32 m0, s76, 0x2000
	s_nop 0
	global_load_lds_dwordx4 v152, s[66:67]
	v_lshl_add_u64 v[224:225], s[34:35], 0, v[146:147]
	s_mov_b32 m0, s46
	s_nop 0
	global_load_lds_dwordx4 v[224:225], off
	s_mov_b32 m0, s47
	s_nop 0
	global_load_lds_dwordx4 v[226:227], off
	s_waitcnt vmcnt(8)
	s_waitcnt lgkmcnt(0)
	s_barrier
	s_waitcnt lgkmcnt(0)
	v_mfma_f32_16x16x32_bf16 v[60:63], v[128:131], v[186:189], v[60:63]
	v_mfma_f32_16x16x32_bf16 v[56:59], v[136:139], v[186:189], v[56:59]
	v_mfma_f32_16x16x32_bf16 v[44:47], v[128:131], v[194:197], v[44:47]
	v_mfma_f32_16x16x32_bf16 v[40:43], v[136:139], v[194:197], v[40:43]
	v_mfma_f32_16x16x32_bf16 v[28:31], v[128:131], v[202:205], v[28:31]
	v_mfma_f32_16x16x32_bf16 v[24:27], v[136:139], v[202:205], v[24:27]
	v_mfma_f32_16x16x32_bf16 v[12:15], v[128:131], v[210:213], v[12:15]
	v_mfma_f32_16x16x32_bf16 v[8:11], v[136:139], v[210:213], v[8:11]
	v_mfma_f32_16x16x32_bf16 v[60:63], v[132:135], v[190:193], v[60:63]
	v_mfma_f32_16x16x32_bf16 v[56:59], v[140:143], v[190:193], v[56:59]
	v_mfma_f32_16x16x32_bf16 v[44:47], v[132:135], v[198:201], v[44:47]
	v_mfma_f32_16x16x32_bf16 v[40:43], v[140:143], v[198:201], v[40:43]
	v_mfma_f32_16x16x32_bf16 v[28:31], v[132:135], v[206:209], v[28:31]
	v_mfma_f32_16x16x32_bf16 v[24:27], v[140:143], v[206:209], v[24:27]
	v_mfma_f32_16x16x32_bf16 v[12:15], v[132:135], v[214:217], v[12:15]
	v_mfma_f32_16x16x32_bf16 v[8:11], v[140:143], v[214:217], v[8:11]
	v_mfma_f32_16x16x32_bf16 v[52:55], v[166:169], v[186:189], v[52:55]
	v_mfma_f32_16x16x32_bf16 v[48:51], v[178:181], v[186:189], v[48:51]
	v_mfma_f32_16x16x32_bf16 v[36:39], v[166:169], v[194:197], v[36:39]
	v_mfma_f32_16x16x32_bf16 v[32:35], v[178:181], v[194:197], v[32:35]
	v_mfma_f32_16x16x32_bf16 v[20:23], v[166:169], v[202:205], v[20:23]
	v_mfma_f32_16x16x32_bf16 v[16:19], v[178:181], v[202:205], v[16:19]
	v_mfma_f32_16x16x32_bf16 v[4:7], v[166:169], v[210:213], v[4:7]
	v_mfma_f32_16x16x32_bf16 v[0:3], v[178:181], v[210:213], v[0:3]
	v_mfma_f32_16x16x32_bf16 v[52:55], v[174:177], v[190:193], v[52:55]
	v_mfma_f32_16x16x32_bf16 v[48:51], v[182:185], v[190:193], v[48:51]
	v_mfma_f32_16x16x32_bf16 v[36:39], v[174:177], v[198:201], v[36:39]
	v_mfma_f32_16x16x32_bf16 v[32:35], v[182:185], v[198:201], v[32:35]
	v_mfma_f32_16x16x32_bf16 v[20:23], v[174:177], v[206:209], v[20:23]
	v_mfma_f32_16x16x32_bf16 v[16:19], v[182:185], v[206:209], v[16:19]
	v_mfma_f32_16x16x32_bf16 v[4:7], v[174:177], v[214:217], v[4:7]
	v_mfma_f32_16x16x32_bf16 v[0:3], v[182:185], v[214:217], v[0:3]
	s_barrier
; #define PG8_STAGE(bufoff, gbase, voff) do { _Pragma("unroll") for (int _i = 0; _i < 2; ++_i) \
;         __builtin_amdgcn_global_load_lds((const unsigned*)((const char*)(gbase) + (voff)[_i]), (PG8_LAS unsigned*)(lds + (bufoff) + ldsw + _i * 8192), 16, 0, 0); } while (0)
; #define PG8_LDA(dst, b, h) do { _Pragma("unroll") for (int m = 0; m < 4; ++m) _Pragma("unroll") for (int k = 0; k < 2; ++k) dst[m][k] = *(const PG8_LAS bf16x8*)(lds + PG8_SA(b, h) + aoff + m * 2048 + k * 1024); } while (0)
; #define PG8_LDB(dst, b, h) do { _Pragma("unroll") for (int n = 0; n < 2; ++n) _Pragma("unroll") for (int k = 0; k < 2; ++k) dst[n][k] = *(const PG8_LAS bf16x8*)(lds + PG8_SB(b, h) + boff + n * 2048 + k * 1024); } while (0)
; #define PG8_MMA(ai, bj, At, Bt) do { __builtin_amdgcn_s_setprio(1); _Pragma("unroll") for (int m = 0; m < 4; ++m) _Pragma("unroll") for (int n = 0; n < 2; ++n) _Pragma("unroll") for (int k = 0; k < 2; ++k) \
;         acc[ai][bj][m][n] = __builtin_amdgcn_mfma_f32_16x16x32_bf16(Bt[n][k], At[m][k], acc[ai][bj][m][n], 0, 0, 0); __builtin_amdgcn_s_setprio(0); } while (0)
; #define PG8_WAIT_V(n) asm volatile("s_waitcnt vmcnt(" #n ")" ::: "memory")
; #define PG8_WAIT_L(n) asm volatile("s_waitcnt lgkmcnt(" #n ")" ::: "memory")
; #define PG8_BAR __builtin_amdgcn_s_barrier()
; #define PG8_SCHED __builtin_amdgcn_sched_barrier(0)
; template <class Epi, class Sched, bool ALIGN_EPI = false, bool SP2 = false>
; __device__ __forceinline__ void gemm_phase(PG8_LAS unsigned char* lds, const Gemm g, const Sched& S, const Epi& E) {
;     ...
;             PG8_LDB(B0, 1, 0); PG8_LDB(B1, 1, 1); PG8_SCHED; PG8_LDA(At, 1, 0); PG8_STAGE(PG8_SA(0, 1), a2 + hstep, voffA);
;             PG8_WAIT_V(8); PG8_WAIT_L(0); PG8_BAR; PG8_MMA(0, 0, At, B0); PG8_MMA(0, 1, At, B1); PG8_BAR; PG8_SCHED;
;             PG8_LDA(At, 1, 1); PG8_STAGE(PG8_SB(1, 0), b3, voffB); PG8_STAGE(PG8_SB(1, 1), b3 + hstep, voffB); PG8_STAGE(PG8_SA(1, 0), a3, voffA);
;             PG8_WAIT_V(8); PG8_WAIT_L(0); PG8_BAR; PG8_MMA(1, 0, At, B0); PG8_MMA(1, 1, At, B1); PG8_BAR; PG8_SCHED;
;     ...
;         if constexpr (ALIGN_EPI) { if (wr == 0) PG8_BAR; }
	s_add_i32 s66, 0, 0x18000
	s_add_i32 s67, 0, 0x1c000
	v_add_u32_e32 v140, s66, v172
	v_add_u32_e32 v154, s67, v172
	ds_read_b128 v[128:131], v140
	ds_read_b128 v[132:135], v140 offset:1024
	ds_read_b128 v[136:139], v140 offset:2048
	ds_read_b128 v[140:143], v140 offset:3072
	ds_read_b128 v[166:169], v154
	ds_read_b128 v[174:177], v154 offset:1024
	ds_read_b128 v[178:181], v154 offset:2048
	ds_read_b128 v[182:185], v154 offset:3072
	s_add_u32 s34, s34, 0x40000
	s_addc_u32 s35, s35, 0
	s_mov_b32 m0, s48
	ds_read_b128 v[186:189], v173 offset:32768
	ds_read_b128 v[190:193], v173 offset:33792
	ds_read_b128 v[194:197], v173 offset:34816
	ds_read_b128 v[198:201], v173 offset:35840
	ds_read_b128 v[202:205], v173 offset:36864
	ds_read_b128 v[206:209], v173 offset:37888
	ds_read_b128 v[210:213], v173 offset:38912
	ds_read_b128 v[214:217], v173 offset:39936
	global_load_lds_dwordx4 v146, s[34:35]
	s_mov_b32 m0, s49
	s_nop 0
	global_load_lds_dwordx4 v150, s[34:35]
	s_waitcnt vmcnt(8)
	s_waitcnt lgkmcnt(0)
	s_barrier
	s_waitcnt lgkmcnt(0)
	v_mfma_f32_16x16x32_bf16 v[124:127], v[128:131], v[186:189], v[124:127]
	v_mfma_f32_16x16x32_bf16 v[120:123], v[136:139], v[186:189], v[120:123]
	v_mfma_f32_16x16x32_bf16 v[108:111], v[128:131], v[194:197], v[108:111]
	v_mfma_f32_16x16x32_bf16 v[104:107], v[136:139], v[194:197], v[104:107]
	v_mfma_f32_16x16x32_bf16 v[92:95], v[128:131], v[202:205], v[92:95]
	v_mfma_f32_16x16x32_bf16 v[88:91], v[136:139], v[202:205], v[88:91]
	v_mfma_f32_16x16x32_bf16 v[76:79], v[128:131], v[210:213], v[76:79]
	v_mfma_f32_16x16x32_bf16 v[72:75], v[136:139], v[210:213], v[72:75]
	v_mfma_f32_16x16x32_bf16 v[124:127], v[132:135], v[190:193], v[124:127]
	v_mfma_f32_16x16x32_bf16 v[120:123], v[140:143], v[190:193], v[120:123]
	v_mfma_f32_16x16x32_bf16 v[108:111], v[132:135], v[198:201], v[108:111]
	v_mfma_f32_16x16x32_bf16 v[104:107], v[140:143], v[198:201], v[104:107]
	v_mfma_f32_16x16x32_bf16 v[92:95], v[132:135], v[206:209], v[92:95]
	v_mfma_f32_16x16x32_bf16 v[88:91], v[140:143], v[206:209], v[88:91]
	v_mfma_f32_16x16x32_bf16 v[76:79], v[132:135], v[214:217], v[76:79]
	v_mfma_f32_16x16x32_bf16 v[72:75], v[140:143], v[214:217], v[72:75]
	v_mfma_f32_16x16x32_bf16 v[116:119], v[166:169], v[186:189], v[116:119]
	v_mfma_f32_16x16x32_bf16 v[112:115], v[178:181], v[186:189], v[112:115]
	v_mfma_f32_16x16x32_bf16 v[100:103], v[166:169], v[194:197], v[100:103]
	v_mfma_f32_16x16x32_bf16 v[96:99], v[178:181], v[194:197], v[96:99]
	v_mfma_f32_16x16x32_bf16 v[84:87], v[166:169], v[202:205], v[84:87]
	v_mfma_f32_16x16x32_bf16 v[80:83], v[178:181], v[202:205], v[80:83]
	v_mfma_f32_16x16x32_bf16 v[68:71], v[166:169], v[210:213], v[68:71]
	v_mfma_f32_16x16x32_bf16 v[64:67], v[178:181], v[210:213], v[64:67]
	v_mfma_f32_16x16x32_bf16 v[116:119], v[174:177], v[190:193], v[116:119]
	v_mfma_f32_16x16x32_bf16 v[112:115], v[182:185], v[190:193], v[112:115]
	v_mfma_f32_16x16x32_bf16 v[100:103], v[174:177], v[198:201], v[100:103]
	v_mfma_f32_16x16x32_bf16 v[96:99], v[182:185], v[198:201], v[96:99]
	v_mfma_f32_16x16x32_bf16 v[84:87], v[174:177], v[206:209], v[84:87]
	v_mfma_f32_16x16x32_bf16 v[80:83], v[182:185], v[206:209], v[80:83]
	v_mfma_f32_16x16x32_bf16 v[68:71], v[174:177], v[214:217], v[68:71]
	v_mfma_f32_16x16x32_bf16 v[64:67], v[182:185], v[214:217], v[64:67]
	s_barrier
	s_add_i32 s34, s66, s37
	v_lshl_add_u64 v[218:219], v[218:219], 0, s[14:15]
	s_mov_b32 m0, s34
	ds_read_b128 v[186:189], v173 offset:49152
	ds_read_b128 v[190:193], v173 offset:50176
	ds_read_b128 v[194:197], v173 offset:51200
	ds_read_b128 v[198:201], v173 offset:52224
	ds_read_b128 v[202:205], v173 offset:53248
	ds_read_b128 v[206:209], v173 offset:54272
	ds_read_b128 v[210:213], v173 offset:55296
	ds_read_b128 v[214:217], v173 offset:56320
	global_load_lds_dwordx4 v[218:219], off
	s_add_i32 m0, s34, 0x2000
	s_add_u32 s6, s6, 0x40080
	v_lshl_add_u64 v[218:219], v[222:223], 0, s[14:15]
	s_addc_u32 s7, s7, 0
	s_add_i32 s34, s67, s37
	global_load_lds_dwordx4 v[218:219], off
	s_mov_b32 m0, s34
	s_nop 0
	global_load_lds_dwordx4 v148, s[6:7]
	s_add_i32 m0, s34, 0x2000
	s_nop 0
	global_load_lds_dwordx4 v152, s[6:7]
	v_lshl_add_u64 v[218:219], v[224:225], 0, s[14:15]
	s_mov_b32 m0, s55
	s_nop 0
	global_load_lds_dwordx4 v[218:219], off
	v_lshl_add_u64 v[218:219], v[226:227], 0, s[14:15]
	s_mov_b32 m0, s56
	s_nop 0
	global_load_lds_dwordx4 v[218:219], off
	s_waitcnt vmcnt(8)
	s_waitcnt lgkmcnt(0)
	s_barrier
	s_waitcnt lgkmcnt(0)
	v_mfma_f32_16x16x32_bf16 v[60:63], v[128:131], v[186:189], v[60:63]
	v_mfma_f32_16x16x32_bf16 v[56:59], v[136:139], v[186:189], v[56:59]
	v_mfma_f32_16x16x32_bf16 v[44:47], v[128:131], v[194:197], v[44:47]
	v_mfma_f32_16x16x32_bf16 v[40:43], v[136:139], v[194:197], v[40:43]
	v_mfma_f32_16x16x32_bf16 v[28:31], v[128:131], v[202:205], v[28:31]
	v_mfma_f32_16x16x32_bf16 v[24:27], v[136:139], v[202:205], v[24:27]
	v_mfma_f32_16x16x32_bf16 v[12:15], v[128:131], v[210:213], v[12:15]
	v_mfma_f32_16x16x32_bf16 v[8:11], v[136:139], v[210:213], v[8:11]
	v_mfma_f32_16x16x32_bf16 v[60:63], v[132:135], v[190:193], v[60:63]
	v_mfma_f32_16x16x32_bf16 v[56:59], v[140:143], v[190:193], v[56:59]
	v_mfma_f32_16x16x32_bf16 v[44:47], v[132:135], v[198:201], v[44:47]
	v_mfma_f32_16x16x32_bf16 v[40:43], v[140:143], v[198:201], v[40:43]
	v_mfma_f32_16x16x32_bf16 v[28:31], v[132:135], v[206:209], v[28:31]
	v_mfma_f32_16x16x32_bf16 v[24:27], v[140:143], v[206:209], v[24:27]
	v_mfma_f32_16x16x32_bf16 v[12:15], v[132:135], v[214:217], v[12:15]
	v_mfma_f32_16x16x32_bf16 v[8:11], v[140:143], v[214:217], v[8:11]
	v_mfma_f32_16x16x32_bf16 v[52:55], v[166:169], v[186:189], v[52:55]
	v_mfma_f32_16x16x32_bf16 v[48:51], v[178:181], v[186:189], v[48:51]
	v_mfma_f32_16x16x32_bf16 v[36:39], v[166:169], v[194:197], v[36:39]
	v_mfma_f32_16x16x32_bf16 v[32:35], v[178:181], v[194:197], v[32:35]
	v_mfma_f32_16x16x32_bf16 v[20:23], v[166:169], v[202:205], v[20:23]
	v_mfma_f32_16x16x32_bf16 v[16:19], v[178:181], v[202:205], v[16:19]
	v_mfma_f32_16x16x32_bf16 v[4:7], v[166:169], v[210:213], v[4:7]
	v_mfma_f32_16x16x32_bf16 v[0:3], v[178:181], v[210:213], v[0:3]
	v_mfma_f32_16x16x32_bf16 v[52:55], v[174:177], v[190:193], v[52:55]
	v_mfma_f32_16x16x32_bf16 v[48:51], v[182:185], v[190:193], v[48:51]
	v_mfma_f32_16x16x32_bf16 v[36:39], v[174:177], v[198:201], v[36:39]
	v_mfma_f32_16x16x32_bf16 v[32:35], v[182:185], v[198:201], v[32:35]
	v_mfma_f32_16x16x32_bf16 v[20:23], v[174:177], v[206:209], v[20:23]
	v_mfma_f32_16x16x32_bf16 v[16:19], v[182:185], v[206:209], v[16:19]
	v_mfma_f32_16x16x32_bf16 v[4:7], v[174:177], v[214:217], v[4:7]
	v_mfma_f32_16x16x32_bf16 v[0:3], v[182:185], v[214:217], v[0:3]
	s_barrier
	s_add_i32 s65, s65, 2
	s_add_u32 s30, s30, 0x100
	s_addc_u32 s31, s31, 0
	s_add_u32 s63, s63, 0x100
	s_addc_u32 s64, s64, 0
	s_cmp_gt_u32 s65, 13
	s_cbranch_scc0 .LBB0_838
	s_and_b64 vcc, exec, s[16:17]
	s_cbranch_vccz .LBB0_841
	s_barrier

; #define PG8_STAGE(bufoff, gbase, voff) do { _Pragma("unroll") for (int _i = 0; _i < 2; ++_i) \
;         __builtin_amdgcn_global_load_lds((const unsigned*)((const char*)(gbase) + (voff)[_i]), (PG8_LAS unsigned*)(lds + (bufoff) + ldsw + _i * 8192), 16, 0, 0); } while (0)
; #define PG8_LDA(dst, b, h) do { _Pragma("unroll") for (int m = 0; m < 4; ++m) _Pragma("unroll") for (int k = 0; k < 2; ++k) dst[m][k] = *(const PG8_LAS bf16x8*)(lds + PG8_SA(b, h) + aoff + m * 2048 + k * 1024); } while (0)
; #define PG8_LDB(dst, b, h) do { _Pragma("unroll") for (int n = 0; n < 2; ++n) _Pragma("unroll") for (int k = 0; k < 2; ++k) dst[n][k] = *(const PG8_LAS bf16x8*)(lds + PG8_SB(b, h) + boff + n * 2048 + k * 1024); } while (0)
; #define PG8_MMA(ai, bj, At, Bt) do { __builtin_amdgcn_s_setprio(1); _Pragma("unroll") for (int m = 0; m < 4; ++m) _Pragma("unroll") for (int n = 0; n < 2; ++n) _Pragma("unroll") for (int k = 0; k < 2; ++k) \
;         acc[ai][bj][m][n] = __builtin_amdgcn_mfma_f32_16x16x32_bf16(Bt[n][k], At[m][k], acc[ai][bj][m][n], 0, 0, 0); __builtin_amdgcn_s_setprio(0); } while (0)
; #define PG8_WAIT_V(n) asm volatile("s_waitcnt vmcnt(" #n ")" ::: "memory")
; #define PG8_WAIT_L(n) asm volatile("s_waitcnt lgkmcnt(" #n ")" ::: "memory")
; #define PG8_BAR __builtin_amdgcn_s_barrier()
; #define PG8_SCHED __builtin_amdgcn_sched_barrier(0)
; template <class Epi, class Sched, bool ALIGN_EPI = false, bool SP2 = false>
; __device__ __forceinline__ void gemm_phase(PG8_LAS unsigned char* lds, const Gemm g, const Sched& S, const Epi& E) {
;     ...
;             PG8_LDB(B0, 0, 0); PG8_LDB(B1, 0, 1); PG8_SCHED; PG8_LDA(At, 0, 0); PG8_STAGE(PG8_SA(1, 1), a1 + hstep, voffA);
;             PG8_WAIT_V(8); PG8_WAIT_L(0); PG8_BAR; PG8_MMA(0, 0, At, B0); PG8_MMA(0, 1, At, B1); PG8_BAR; PG8_SCHED;
;             PG8_LDA(At, 0, 1); PG8_STAGE(PG8_SB(0, 0), b2, voffB); PG8_STAGE(PG8_SB(0, 1), b2 + hstep, voffB); PG8_STAGE(PG8_SA(0, 0), a2, voffA);
;             PG8_WAIT_V(8); PG8_WAIT_L(0); PG8_BAR; PG8_MMA(1, 0, At, B0); PG8_MMA(1, 1, At, B1); PG8_BAR; PG8_SCHED;
.LBB0_987:
	ds_read_b128 v[80:83], v205
	ds_read_b128 v[84:87], v205 offset:1024
	ds_read_b128 v[92:95], v205 offset:2048
	ds_read_b128 v[96:99], v205 offset:3072
	ds_read_b128 v[144:147], v206
	ds_read_b128 v[148:151], v206 offset:1024
	ds_read_b128 v[152:155], v206 offset:2048
	ds_read_b128 v[156:159], v206 offset:3072
	s_add_u32 s6, s8, 0xfffc0080
	s_addc_u32 s7, s9, -1
	s_cmp_eq_u32 s59, 12
	s_cselect_b32 s35, s25, s7
	s_cselect_b32 s34, s55, s6
	s_cselect_b32 s7, s23, s58
	s_cselect_b32 s6, s56, s57
	s_add_i32 m0, s31, 0xc000
	ds_read_b128 v[160:163], v207
	ds_read_b128 v[164:167], v207 offset:1024
	ds_read_b128 v[184:187], v207 offset:2048
	ds_read_b128 v[188:191], v207 offset:3072
	ds_read_b128 v[192:195], v207 offset:4096
	ds_read_b128 v[196:199], v207 offset:5120
	ds_read_b128 v[210:213], v207 offset:6144
	ds_read_b128 v[214:217], v207 offset:7168
	global_load_lds_dwordx4 v176, s[8:9]
	s_add_i32 m0, s31, 0xe000
	s_nop 0
	global_load_lds_dwordx4 v178, s[8:9]
	s_waitcnt vmcnt(8)
	s_waitcnt lgkmcnt(0)
	s_barrier
	s_waitcnt lgkmcnt(0)
	v_mfma_f32_16x16x32_bf16 v[140:143], v[80:83], v[160:163], v[140:143]
	v_mfma_f32_16x16x32_bf16 v[136:139], v[92:95], v[160:163], v[136:139]
	v_mfma_f32_16x16x32_bf16 v[124:127], v[80:83], v[184:187], v[124:127]
	v_mfma_f32_16x16x32_bf16 v[120:123], v[92:95], v[184:187], v[120:123]
	v_mfma_f32_16x16x32_bf16 v[108:111], v[80:83], v[192:195], v[108:111]
	v_mfma_f32_16x16x32_bf16 v[104:107], v[92:95], v[192:195], v[104:107]
	v_mfma_f32_16x16x32_bf16 v[76:79], v[80:83], v[210:213], v[76:79]
	v_mfma_f32_16x16x32_bf16 v[72:75], v[92:95], v[210:213], v[72:75]
	v_mfma_f32_16x16x32_bf16 v[140:143], v[84:87], v[164:167], v[140:143]
	v_mfma_f32_16x16x32_bf16 v[136:139], v[96:99], v[164:167], v[136:139]
	v_mfma_f32_16x16x32_bf16 v[124:127], v[84:87], v[188:191], v[124:127]
	v_mfma_f32_16x16x32_bf16 v[120:123], v[96:99], v[188:191], v[120:123]
	v_mfma_f32_16x16x32_bf16 v[108:111], v[84:87], v[196:199], v[108:111]
	v_mfma_f32_16x16x32_bf16 v[104:107], v[96:99], v[196:199], v[104:107]
	v_mfma_f32_16x16x32_bf16 v[76:79], v[84:87], v[214:217], v[76:79]
	v_mfma_f32_16x16x32_bf16 v[72:75], v[96:99], v[214:217], v[72:75]
	v_mfma_f32_16x16x32_bf16 v[132:135], v[144:147], v[160:163], v[132:135]
	v_mfma_f32_16x16x32_bf16 v[128:131], v[152:155], v[160:163], v[128:131]
	v_mfma_f32_16x16x32_bf16 v[116:119], v[144:147], v[184:187], v[116:119]
	v_mfma_f32_16x16x32_bf16 v[112:115], v[152:155], v[184:187], v[112:115]
	v_mfma_f32_16x16x32_bf16 v[100:103], v[144:147], v[192:195], v[100:103]
	v_mfma_f32_16x16x32_bf16 v[88:91], v[152:155], v[192:195], v[88:91]
	v_mfma_f32_16x16x32_bf16 v[68:71], v[144:147], v[210:213], v[68:71]
	v_mfma_f32_16x16x32_bf16 v[64:67], v[152:155], v[210:213], v[64:67]
	v_mfma_f32_16x16x32_bf16 v[132:135], v[148:151], v[164:167], v[132:135]
	v_mfma_f32_16x16x32_bf16 v[128:131], v[156:159], v[164:167], v[128:131]
	v_mfma_f32_16x16x32_bf16 v[116:119], v[148:151], v[188:191], v[116:119]
	v_mfma_f32_16x16x32_bf16 v[112:115], v[156:159], v[188:191], v[112:115]
	v_mfma_f32_16x16x32_bf16 v[100:103], v[148:151], v[196:199], v[100:103]
	v_mfma_f32_16x16x32_bf16 v[88:91], v[156:159], v[196:199], v[88:91]
	v_mfma_f32_16x16x32_bf16 v[68:71], v[148:151], v[214:217], v[68:71]
	v_mfma_f32_16x16x32_bf16 v[64:67], v[156:159], v[214:217], v[64:67]
	s_barrier
	s_add_i32 s60, s52, s3
	v_lshl_add_u64 v[200:201], s[6:7], 0, v[170:171]
	s_mov_b32 m0, s60
	ds_read_b128 v[160:163], v207 offset:16384
	ds_read_b128 v[164:167], v207 offset:17408
	ds_read_b128 v[184:187], v207 offset:18432
	ds_read_b128 v[188:191], v207 offset:19456
	ds_read_b128 v[192:195], v207 offset:20480
	ds_read_b128 v[196:199], v207 offset:21504
	ds_read_b128 v[210:213], v207 offset:22528
	ds_read_b128 v[214:217], v207 offset:23552
	global_load_lds_dwordx4 v[200:201], off
	s_add_i32 m0, s60, 0x2000
	s_add_u32 s60, s6, 0x40000
	v_lshl_add_u64 v[218:219], s[6:7], 0, v[174:175]
	s_addc_u32 s61, s7, 0
	s_add_i32 s62, s53, s3
	global_load_lds_dwordx4 v[218:219], off
	s_mov_b32 m0, s62
	v_lshl_add_u64 v[224:225], s[34:35], 0, v[172:173]
	global_load_lds_dwordx4 v170, s[60:61]
	s_add_i32 m0, s62, 0x2000
	s_nop 0
	global_load_lds_dwordx4 v174, s[60:61]
	v_lshl_add_u64 v[222:223], s[34:35], 0, v[168:169]
	s_mov_b32 m0, s31
	s_nop 0
	global_load_lds_dwordx4 v[222:223], off
	s_mov_b32 m0, s33
	s_nop 0
	global_load_lds_dwordx4 v[224:225], off
	s_waitcnt vmcnt(8)
	s_waitcnt lgkmcnt(0)
	s_barrier
	s_waitcnt lgkmcnt(0)
	v_mfma_f32_16x16x32_bf16 v[60:63], v[80:83], v[160:163], v[60:63]
	v_mfma_f32_16x16x32_bf16 v[56:59], v[92:95], v[160:163], v[56:59]
	v_mfma_f32_16x16x32_bf16 v[44:47], v[80:83], v[184:187], v[44:47]
	v_mfma_f32_16x16x32_bf16 v[40:43], v[92:95], v[184:187], v[40:43]
	v_mfma_f32_16x16x32_bf16 v[28:31], v[80:83], v[192:195], v[28:31]
	v_mfma_f32_16x16x32_bf16 v[24:27], v[92:95], v[192:195], v[24:27]
	v_mfma_f32_16x16x32_bf16 v[12:15], v[80:83], v[210:213], v[12:15]
	v_mfma_f32_16x16x32_bf16 v[8:11], v[92:95], v[210:213], v[8:11]
	v_mfma_f32_16x16x32_bf16 v[60:63], v[84:87], v[164:167], v[60:63]
	v_mfma_f32_16x16x32_bf16 v[56:59], v[96:99], v[164:167], v[56:59]
	v_mfma_f32_16x16x32_bf16 v[44:47], v[84:87], v[188:191], v[44:47]
	v_mfma_f32_16x16x32_bf16 v[40:43], v[96:99], v[188:191], v[40:43]
	v_mfma_f32_16x16x32_bf16 v[28:31], v[84:87], v[196:199], v[28:31]
	v_mfma_f32_16x16x32_bf16 v[24:27], v[96:99], v[196:199], v[24:27]
	v_mfma_f32_16x16x32_bf16 v[12:15], v[84:87], v[214:217], v[12:15]
	v_mfma_f32_16x16x32_bf16 v[8:11], v[96:99], v[214:217], v[8:11]
	v_mfma_f32_16x16x32_bf16 v[52:55], v[144:147], v[160:163], v[52:55]
	v_mfma_f32_16x16x32_bf16 v[48:51], v[152:155], v[160:163], v[48:51]
	v_mfma_f32_16x16x32_bf16 v[36:39], v[144:147], v[184:187], v[36:39]
	v_mfma_f32_16x16x32_bf16 v[32:35], v[152:155], v[184:187], v[32:35]
	v_mfma_f32_16x16x32_bf16 v[20:23], v[144:147], v[192:195], v[20:23]
	v_mfma_f32_16x16x32_bf16 v[16:19], v[152:155], v[192:195], v[16:19]
	v_mfma_f32_16x16x32_bf16 v[4:7], v[144:147], v[210:213], v[4:7]
	v_mfma_f32_16x16x32_bf16 v[0:3], v[152:155], v[210:213], v[0:3]
	v_mfma_f32_16x16x32_bf16 v[52:55], v[148:151], v[164:167], v[52:55]
	v_mfma_f32_16x16x32_bf16 v[48:51], v[156:159], v[164:167], v[48:51]
	v_mfma_f32_16x16x32_bf16 v[36:39], v[148:151], v[188:191], v[36:39]
	v_mfma_f32_16x16x32_bf16 v[32:35], v[156:159], v[188:191], v[32:35]
	v_mfma_f32_16x16x32_bf16 v[20:23], v[148:151], v[196:199], v[20:23]
	v_mfma_f32_16x16x32_bf16 v[16:19], v[156:159], v[196:199], v[16:19]
	v_mfma_f32_16x16x32_bf16 v[4:7], v[148:151], v[214:217], v[4:7]
	v_mfma_f32_16x16x32_bf16 v[0:3], v[156:159], v[214:217], v[0:3]
	s_barrier
; #define PG8_STAGE(bufoff, gbase, voff) do { _Pragma("unroll") for (int _i = 0; _i < 2; ++_i) \
;         __builtin_amdgcn_global_load_lds((const unsigned*)((const char*)(gbase) + (voff)[_i]), (PG8_LAS unsigned*)(lds + (bufoff) + ldsw + _i * 8192), 16, 0, 0); } while (0)
; #define PG8_LDA(dst, b, h) do { _Pragma("unroll") for (int m = 0; m < 4; ++m) _Pragma("unroll") for (int k = 0; k < 2; ++k) dst[m][k] = *(const PG8_LAS bf16x8*)(lds + PG8_SA(b, h) + aoff + m * 2048 + k * 1024); } while (0)
; #define PG8_LDB(dst, b, h) do { _Pragma("unroll") for (int n = 0; n < 2; ++n) _Pragma("unroll") for (int k = 0; k < 2; ++k) dst[n][k] = *(const PG8_LAS bf16x8*)(lds + PG8_SB(b, h) + boff + n * 2048 + k * 1024); } while (0)
; #define PG8_MMA(ai, bj, At, Bt) do { __builtin_amdgcn_s_setprio(1); _Pragma("unroll") for (int m = 0; m < 4; ++m) _Pragma("unroll") for (int n = 0; n < 2; ++n) _Pragma("unroll") for (int k = 0; k < 2; ++k) \
;         acc[ai][bj][m][n] = __builtin_amdgcn_mfma_f32_16x16x32_bf16(Bt[n][k], At[m][k], acc[ai][bj][m][n], 0, 0, 0); __builtin_amdgcn_s_setprio(0); } while (0)
; #define PG8_WAIT_V(n) asm volatile("s_waitcnt vmcnt(" #n ")" ::: "memory")
; #define PG8_WAIT_L(n) asm volatile("s_waitcnt lgkmcnt(" #n ")" ::: "memory")
; #define PG8_BAR __builtin_amdgcn_s_barrier()
; #define PG8_SCHED __builtin_amdgcn_sched_barrier(0)
; template <class Epi, class Sched, bool ALIGN_EPI = false, bool SP2 = false>
; __device__ __forceinline__ void gemm_phase(PG8_LAS unsigned char* lds, const Gemm g, const Sched& S, const Epi& E) {
;     ...
;             PG8_LDB(B0, 1, 0); PG8_LDB(B1, 1, 1); PG8_SCHED; PG8_LDA(At, 1, 0); PG8_STAGE(PG8_SA(0, 1), a2 + hstep, voffA);
;             PG8_WAIT_V(8); PG8_WAIT_L(0); PG8_BAR; PG8_MMA(0, 0, At, B0); PG8_MMA(0, 1, At, B1); PG8_BAR; PG8_SCHED;
;             PG8_LDA(At, 1, 1); PG8_STAGE(PG8_SB(1, 0), b3, voffB); PG8_STAGE(PG8_SB(1, 1), b3 + hstep, voffB); PG8_STAGE(PG8_SA(1, 0), a3, voffA);
;             PG8_WAIT_V(8); PG8_WAIT_L(0); PG8_BAR; PG8_MMA(1, 0, At, B0); PG8_MMA(1, 1, At, B1); PG8_BAR; PG8_SCHED;
;     ...
;         if constexpr (ALIGN_EPI) { if (wr == 0) PG8_BAR; }
	s_add_i32 s60, 0, 0x18000
	s_add_i32 s61, 0, 0x1c000
	v_add_u32_e32 v96, s60, v203
	v_add_u32_e32 v156, s61, v203
	ds_read_b128 v[80:83], v96
	ds_read_b128 v[84:87], v96 offset:1024
	ds_read_b128 v[92:95], v96 offset:2048
	ds_read_b128 v[96:99], v96 offset:3072
	ds_read_b128 v[144:147], v156
	ds_read_b128 v[148:151], v156 offset:1024
	ds_read_b128 v[152:155], v156 offset:2048
	ds_read_b128 v[156:159], v156 offset:3072
	s_add_u32 s34, s34, 0x40000
	s_addc_u32 s35, s35, 0
	s_mov_b32 m0, s36
	ds_read_b128 v[160:163], v207 offset:32768
	ds_read_b128 v[164:167], v207 offset:33792
	ds_read_b128 v[184:187], v207 offset:34816
	ds_read_b128 v[188:191], v207 offset:35840
	ds_read_b128 v[192:195], v207 offset:36864
	ds_read_b128 v[196:199], v207 offset:37888
	ds_read_b128 v[210:213], v207 offset:38912
	ds_read_b128 v[214:217], v207 offset:39936
	global_load_lds_dwordx4 v168, s[34:35]
	s_mov_b32 m0, s37
	s_nop 0
	global_load_lds_dwordx4 v172, s[34:35]
	s_waitcnt vmcnt(8)
	s_waitcnt lgkmcnt(0)
	s_barrier
	s_waitcnt lgkmcnt(0)
	v_mfma_f32_16x16x32_bf16 v[140:143], v[80:83], v[160:163], v[140:143]
	v_mfma_f32_16x16x32_bf16 v[136:139], v[92:95], v[160:163], v[136:139]
	v_mfma_f32_16x16x32_bf16 v[124:127], v[80:83], v[184:187], v[124:127]
	v_mfma_f32_16x16x32_bf16 v[120:123], v[92:95], v[184:187], v[120:123]
	v_mfma_f32_16x16x32_bf16 v[108:111], v[80:83], v[192:195], v[108:111]
	v_mfma_f32_16x16x32_bf16 v[104:107], v[92:95], v[192:195], v[104:107]
	v_mfma_f32_16x16x32_bf16 v[76:79], v[80:83], v[210:213], v[76:79]
	v_mfma_f32_16x16x32_bf16 v[72:75], v[92:95], v[210:213], v[72:75]
	v_mfma_f32_16x16x32_bf16 v[140:143], v[84:87], v[164:167], v[140:143]
	v_mfma_f32_16x16x32_bf16 v[136:139], v[96:99], v[164:167], v[136:139]
	v_mfma_f32_16x16x32_bf16 v[124:127], v[84:87], v[188:191], v[124:127]
	v_mfma_f32_16x16x32_bf16 v[120:123], v[96:99], v[188:191], v[120:123]
	v_mfma_f32_16x16x32_bf16 v[108:111], v[84:87], v[196:199], v[108:111]
	v_mfma_f32_16x16x32_bf16 v[104:107], v[96:99], v[196:199], v[104:107]
	v_mfma_f32_16x16x32_bf16 v[76:79], v[84:87], v[214:217], v[76:79]
	v_mfma_f32_16x16x32_bf16 v[72:75], v[96:99], v[214:217], v[72:75]
	v_mfma_f32_16x16x32_bf16 v[132:135], v[144:147], v[160:163], v[132:135]
	v_mfma_f32_16x16x32_bf16 v[128:131], v[152:155], v[160:163], v[128:131]
	v_mfma_f32_16x16x32_bf16 v[116:119], v[144:147], v[184:187], v[116:119]
	v_mfma_f32_16x16x32_bf16 v[112:115], v[152:155], v[184:187], v[112:115]
	v_mfma_f32_16x16x32_bf16 v[100:103], v[144:147], v[192:195], v[100:103]
	v_mfma_f32_16x16x32_bf16 v[88:91], v[152:155], v[192:195], v[88:91]
	v_mfma_f32_16x16x32_bf16 v[68:71], v[144:147], v[210:213], v[68:71]
	v_mfma_f32_16x16x32_bf16 v[64:67], v[152:155], v[210:213], v[64:67]
	v_mfma_f32_16x16x32_bf16 v[132:135], v[148:151], v[164:167], v[132:135]
	v_mfma_f32_16x16x32_bf16 v[128:131], v[156:159], v[164:167], v[128:131]
	v_mfma_f32_16x16x32_bf16 v[116:119], v[148:151], v[188:191], v[116:119]
	v_mfma_f32_16x16x32_bf16 v[112:115], v[156:159], v[188:191], v[112:115]
	v_mfma_f32_16x16x32_bf16 v[100:103], v[148:151], v[196:199], v[100:103]
	v_mfma_f32_16x16x32_bf16 v[88:91], v[156:159], v[196:199], v[88:91]
	v_mfma_f32_16x16x32_bf16 v[68:71], v[148:151], v[214:217], v[68:71]
	v_mfma_f32_16x16x32_bf16 v[64:67], v[156:159], v[214:217], v[64:67]
	s_barrier
	s_add_i32 s34, s60, s3
	v_lshl_add_u64 v[200:201], v[200:201], 0, s[16:17]
	s_mov_b32 m0, s34
	ds_read_b128 v[160:163], v207 offset:49152
	ds_read_b128 v[164:167], v207 offset:50176
	ds_read_b128 v[184:187], v207 offset:51200
	ds_read_b128 v[188:191], v207 offset:52224
	ds_read_b128 v[192:195], v207 offset:53248
	ds_read_b128 v[196:199], v207 offset:54272
	ds_read_b128 v[210:213], v207 offset:55296
	ds_read_b128 v[214:217], v207 offset:56320
	global_load_lds_dwordx4 v[200:201], off
	s_add_i32 m0, s34, 0x2000
	s_add_u32 s6, s6, 0x40080
	v_lshl_add_u64 v[200:201], v[218:219], 0, s[16:17]
	s_addc_u32 s7, s7, 0
	s_add_i32 s34, s61, s3
	global_load_lds_dwordx4 v[200:201], off
	s_mov_b32 m0, s34
	s_nop 0
	global_load_lds_dwordx4 v170, s[6:7]
	s_add_i32 m0, s34, 0x2000
	s_nop 0
	global_load_lds_dwordx4 v174, s[6:7]
	v_lshl_add_u64 v[200:201], v[222:223], 0, s[16:17]
	s_mov_b32 m0, s47
	s_nop 0
	global_load_lds_dwordx4 v[200:201], off
	v_lshl_add_u64 v[200:201], v[224:225], 0, s[16:17]
	s_mov_b32 m0, s48
	s_nop 0
	global_load_lds_dwordx4 v[200:201], off
	s_waitcnt vmcnt(8)
	s_waitcnt lgkmcnt(0)
	s_barrier
	s_waitcnt lgkmcnt(0)
	v_mfma_f32_16x16x32_bf16 v[60:63], v[80:83], v[160:163], v[60:63]
	v_mfma_f32_16x16x32_bf16 v[56:59], v[92:95], v[160:163], v[56:59]
	v_mfma_f32_16x16x32_bf16 v[44:47], v[80:83], v[184:187], v[44:47]
	v_mfma_f32_16x16x32_bf16 v[40:43], v[92:95], v[184:187], v[40:43]
	v_mfma_f32_16x16x32_bf16 v[28:31], v[80:83], v[192:195], v[28:31]
	v_mfma_f32_16x16x32_bf16 v[24:27], v[92:95], v[192:195], v[24:27]
	v_mfma_f32_16x16x32_bf16 v[12:15], v[80:83], v[210:213], v[12:15]
	v_mfma_f32_16x16x32_bf16 v[8:11], v[92:95], v[210:213], v[8:11]
	v_mfma_f32_16x16x32_bf16 v[60:63], v[84:87], v[164:167], v[60:63]
	v_mfma_f32_16x16x32_bf16 v[56:59], v[96:99], v[164:167], v[56:59]
	v_mfma_f32_16x16x32_bf16 v[44:47], v[84:87], v[188:191], v[44:47]
	v_mfma_f32_16x16x32_bf16 v[40:43], v[96:99], v[188:191], v[40:43]
	v_mfma_f32_16x16x32_bf16 v[28:31], v[84:87], v[196:199], v[28:31]
	v_mfma_f32_16x16x32_bf16 v[24:27], v[96:99], v[196:199], v[24:27]
	v_mfma_f32_16x16x32_bf16 v[12:15], v[84:87], v[214:217], v[12:15]
	v_mfma_f32_16x16x32_bf16 v[8:11], v[96:99], v[214:217], v[8:11]
	v_mfma_f32_16x16x32_bf16 v[52:55], v[144:147], v[160:163], v[52:55]
	v_mfma_f32_16x16x32_bf16 v[48:51], v[152:155], v[160:163], v[48:51]
	v_mfma_f32_16x16x32_bf16 v[36:39], v[144:147], v[184:187], v[36:39]
	v_mfma_f32_16x16x32_bf16 v[32:35], v[152:155], v[184:187], v[32:35]
	v_mfma_f32_16x16x32_bf16 v[20:23], v[144:147], v[192:195], v[20:23]
	v_mfma_f32_16x16x32_bf16 v[16:19], v[152:155], v[192:195], v[16:19]
	v_mfma_f32_16x16x32_bf16 v[4:7], v[144:147], v[210:213], v[4:7]
	v_mfma_f32_16x16x32_bf16 v[0:3], v[152:155], v[210:213], v[0:3]
	v_mfma_f32_16x16x32_bf16 v[52:55], v[148:151], v[164:167], v[52:55]
	v_mfma_f32_16x16x32_bf16 v[48:51], v[156:159], v[164:167], v[48:51]
	v_mfma_f32_16x16x32_bf16 v[36:39], v[148:151], v[188:191], v[36:39]
	v_mfma_f32_16x16x32_bf16 v[32:35], v[156:159], v[188:191], v[32:35]
	v_mfma_f32_16x16x32_bf16 v[20:23], v[148:151], v[196:199], v[20:23]
	v_mfma_f32_16x16x32_bf16 v[16:19], v[156:159], v[196:199], v[16:19]
	v_mfma_f32_16x16x32_bf16 v[4:7], v[148:151], v[214:217], v[4:7]
	v_mfma_f32_16x16x32_bf16 v[0:3], v[156:159], v[214:217], v[0:3]
	s_barrier
	s_add_i32 s59, s59, 2
	s_add_u32 s8, s8, 0x100
	s_addc_u32 s9, s9, 0
	s_add_u32 s57, s57, 0x100
	s_addc_u32 s58, s58, 0
	s_cmp_gt_u32 s59, 13
	s_cbranch_scc0 .LBB0_987
	s_and_b64 vcc, exec, s[18:19]
	s_cbranch_vccz .LBB0_990
	s_barrier

; #define PG8_STAGE(bufoff, gbase, voff) do { _Pragma("unroll") for (int _i = 0; _i < 2; ++_i) \
;         __builtin_amdgcn_global_load_lds((const unsigned*)((const char*)(gbase) + (voff)[_i]), (PG8_LAS unsigned*)(lds + (bufoff) + ldsw + _i * 8192), 16, 0, 0); } while (0)
; #define PG8_LDA(dst, b, h) do { _Pragma("unroll") for (int m = 0; m < 4; ++m) _Pragma("unroll") for (int k = 0; k < 2; ++k) dst[m][k] = *(const PG8_LAS bf16x8*)(lds + PG8_SA(b, h) + aoff + m * 2048 + k * 1024); } while (0)
; #define PG8_LDB(dst, b, h) do { _Pragma("unroll") for (int n = 0; n < 2; ++n) _Pragma("unroll") for (int k = 0; k < 2; ++k) dst[n][k] = *(const PG8_LAS bf16x8*)(lds + PG8_SB(b, h) + boff + n * 2048 + k * 1024); } while (0)
; #define PG8_MMA(ai, bj, At, Bt) do { __builtin_amdgcn_s_setprio(1); _Pragma("unroll") for (int m = 0; m < 4; ++m) _Pragma("unroll") for (int n = 0; n < 2; ++n) _Pragma("unroll") for (int k = 0; k < 2; ++k) \
;         acc[ai][bj][m][n] = __builtin_amdgcn_mfma_f32_16x16x32_bf16(Bt[n][k], At[m][k], acc[ai][bj][m][n], 0, 0, 0); __builtin_amdgcn_s_setprio(0); } while (0)
; #define PG8_WAIT_V(n) asm volatile("s_waitcnt vmcnt(" #n ")" ::: "memory")
; #define PG8_WAIT_L(n) asm volatile("s_waitcnt lgkmcnt(" #n ")" ::: "memory")
; #define PG8_BAR __builtin_amdgcn_s_barrier()
; #define PG8_SCHED __builtin_amdgcn_sched_barrier(0)
; template <class Epi, class Sched, bool ALIGN_EPI = false, bool SP2 = false>
; __device__ __forceinline__ void gemm_phase(PG8_LAS unsigned char* lds, const Gemm g, const Sched& S, const Epi& E) {
;     ...
;             PG8_LDB(B0, 0, 0); PG8_LDB(B1, 0, 1); PG8_SCHED; PG8_LDA(At, 0, 0); PG8_STAGE(PG8_SA(1, 1), a1 + hstep, voffA);
;             PG8_WAIT_V(8); PG8_WAIT_L(0); PG8_BAR; PG8_MMA(0, 0, At, B0); PG8_MMA(0, 1, At, B1); PG8_BAR; PG8_SCHED;
;             PG8_LDA(At, 0, 1); PG8_STAGE(PG8_SB(0, 0), b2, voffB); PG8_STAGE(PG8_SB(0, 1), b2 + hstep, voffB); PG8_STAGE(PG8_SA(0, 0), a2, voffA);
;             PG8_WAIT_V(8); PG8_WAIT_L(0); PG8_BAR; PG8_MMA(1, 0, At, B0); PG8_MMA(1, 1, At, B1); PG8_BAR; PG8_SCHED;
.LBB0_1082:
	ds_read_b128 v[154:157], v149
	ds_read_b128 v[158:161], v149 offset:1024
	ds_read_b128 v[162:165], v149 offset:2048
	ds_read_b128 v[166:169], v149 offset:3072
	ds_read_b128 v[170:173], v150
	ds_read_b128 v[174:177], v150 offset:1024
	ds_read_b128 v[178:181], v150 offset:2048
	ds_read_b128 v[182:185], v150 offset:3072
	s_add_u32 s6, s24, 0xfffc0080
	s_addc_u32 s7, s25, -1
	s_cmp_eq_u32 s55, 12
	s_cselect_b32 s27, s17, s7
	s_cselect_b32 s26, s51, s6
	s_cselect_b32 s7, s15, s54
	s_cselect_b32 s6, s52, s53
	s_add_i32 m0, s23, 0xc000
	ds_read_b128 v[186:189], v151
	ds_read_b128 v[190:193], v151 offset:1024
	ds_read_b128 v[194:197], v151 offset:2048
	ds_read_b128 v[198:201], v151 offset:3072
	ds_read_b128 v[202:205], v151 offset:4096
	ds_read_b128 v[206:209], v151 offset:5120
	ds_read_b128 v[210:213], v151 offset:6144
	ds_read_b128 v[214:217], v151 offset:7168
	global_load_lds_dwordx4 v136, s[24:25]
	s_add_i32 m0, s23, 0xe000
	s_nop 0
	global_load_lds_dwordx4 v138, s[24:25]
	s_waitcnt vmcnt(8)
	s_waitcnt lgkmcnt(0)
	s_barrier
	s_waitcnt lgkmcnt(0)
	v_mfma_f32_16x16x32_bf16 v[116:119], v[154:157], v[186:189], v[116:119]
	v_mfma_f32_16x16x32_bf16 v[112:115], v[162:165], v[186:189], v[112:115]
	v_mfma_f32_16x16x32_bf16 v[100:103], v[154:157], v[194:197], v[100:103]
	v_mfma_f32_16x16x32_bf16 v[96:99], v[162:165], v[194:197], v[96:99]
	v_mfma_f32_16x16x32_bf16 v[84:87], v[154:157], v[202:205], v[84:87]
	v_mfma_f32_16x16x32_bf16 v[80:83], v[162:165], v[202:205], v[80:83]
	v_mfma_f32_16x16x32_bf16 v[68:71], v[154:157], v[210:213], v[68:71]
	v_mfma_f32_16x16x32_bf16 v[64:67], v[162:165], v[210:213], v[64:67]
	v_mfma_f32_16x16x32_bf16 v[116:119], v[158:161], v[190:193], v[116:119]
	v_mfma_f32_16x16x32_bf16 v[112:115], v[166:169], v[190:193], v[112:115]
	v_mfma_f32_16x16x32_bf16 v[100:103], v[158:161], v[198:201], v[100:103]
	v_mfma_f32_16x16x32_bf16 v[96:99], v[166:169], v[198:201], v[96:99]
	v_mfma_f32_16x16x32_bf16 v[84:87], v[158:161], v[206:209], v[84:87]
	v_mfma_f32_16x16x32_bf16 v[80:83], v[166:169], v[206:209], v[80:83]
	v_mfma_f32_16x16x32_bf16 v[68:71], v[158:161], v[214:217], v[68:71]
	v_mfma_f32_16x16x32_bf16 v[64:67], v[166:169], v[214:217], v[64:67]
	v_mfma_f32_16x16x32_bf16 v[124:127], v[170:173], v[186:189], v[124:127]
	v_mfma_f32_16x16x32_bf16 v[120:123], v[178:181], v[186:189], v[120:123]
	v_mfma_f32_16x16x32_bf16 v[108:111], v[170:173], v[194:197], v[108:111]
	v_mfma_f32_16x16x32_bf16 v[104:107], v[178:181], v[194:197], v[104:107]
	v_mfma_f32_16x16x32_bf16 v[92:95], v[170:173], v[202:205], v[92:95]
	v_mfma_f32_16x16x32_bf16 v[88:91], v[178:181], v[202:205], v[88:91]
	v_mfma_f32_16x16x32_bf16 v[76:79], v[170:173], v[210:213], v[76:79]
	v_mfma_f32_16x16x32_bf16 v[72:75], v[178:181], v[210:213], v[72:75]
	v_mfma_f32_16x16x32_bf16 v[124:127], v[174:177], v[190:193], v[124:127]
	v_mfma_f32_16x16x32_bf16 v[120:123], v[182:185], v[190:193], v[120:123]
	v_mfma_f32_16x16x32_bf16 v[108:111], v[174:177], v[198:201], v[108:111]
	v_mfma_f32_16x16x32_bf16 v[104:107], v[182:185], v[198:201], v[104:107]
	v_mfma_f32_16x16x32_bf16 v[92:95], v[174:177], v[206:209], v[92:95]
	v_mfma_f32_16x16x32_bf16 v[88:91], v[182:185], v[206:209], v[88:91]
	v_mfma_f32_16x16x32_bf16 v[76:79], v[174:177], v[214:217], v[76:79]
	v_mfma_f32_16x16x32_bf16 v[72:75], v[182:185], v[214:217], v[72:75]
	s_barrier
	s_add_i32 s56, s47, s29
	v_lshl_add_u64 v[144:145], s[6:7], 0, v[132:133]
	s_mov_b32 m0, s56
	ds_read_b128 v[186:189], v151 offset:16384
	ds_read_b128 v[190:193], v151 offset:17408
	ds_read_b128 v[194:197], v151 offset:18432
	ds_read_b128 v[198:201], v151 offset:19456
	ds_read_b128 v[202:205], v151 offset:20480
	ds_read_b128 v[206:209], v151 offset:21504
	ds_read_b128 v[210:213], v151 offset:22528
	ds_read_b128 v[214:217], v151 offset:23552
	global_load_lds_dwordx4 v[144:145], off
	s_add_i32 m0, s56, 0x2000
	s_add_u32 s56, s6, 0x40000
	v_lshl_add_u64 v[218:219], s[6:7], 0, v[128:129]
	s_addc_u32 s57, s7, 0
	s_add_i32 s58, s48, s29
	global_load_lds_dwordx4 v[218:219], off
	s_mov_b32 m0, s58
	v_lshl_add_u64 v[224:225], s[26:27], 0, v[130:131]
	global_load_lds_dwordx4 v132, s[56:57]
	s_add_i32 m0, s58, 0x2000
	s_nop 0
	global_load_lds_dwordx4 v128, s[56:57]
	v_lshl_add_u64 v[222:223], s[26:27], 0, v[134:135]
	s_mov_b32 m0, s23
	s_nop 0
	global_load_lds_dwordx4 v[222:223], off
	s_mov_b32 m0, s33
	s_nop 0
	global_load_lds_dwordx4 v[224:225], off
	s_waitcnt vmcnt(8)
	s_waitcnt lgkmcnt(0)
	s_barrier
	s_waitcnt lgkmcnt(0)
	v_mfma_f32_16x16x32_bf16 v[52:55], v[154:157], v[186:189], v[52:55]
	v_mfma_f32_16x16x32_bf16 v[48:51], v[162:165], v[186:189], v[48:51]
	v_mfma_f32_16x16x32_bf16 v[36:39], v[154:157], v[194:197], v[36:39]
	v_mfma_f32_16x16x32_bf16 v[32:35], v[162:165], v[194:197], v[32:35]
	v_mfma_f32_16x16x32_bf16 v[20:23], v[154:157], v[202:205], v[20:23]
	v_mfma_f32_16x16x32_bf16 v[16:19], v[162:165], v[202:205], v[16:19]
	v_mfma_f32_16x16x32_bf16 v[4:7], v[154:157], v[210:213], v[4:7]
	v_mfma_f32_16x16x32_bf16 v[0:3], v[162:165], v[210:213], v[0:3]
	v_mfma_f32_16x16x32_bf16 v[52:55], v[158:161], v[190:193], v[52:55]
	v_mfma_f32_16x16x32_bf16 v[48:51], v[166:169], v[190:193], v[48:51]
	v_mfma_f32_16x16x32_bf16 v[36:39], v[158:161], v[198:201], v[36:39]
	v_mfma_f32_16x16x32_bf16 v[32:35], v[166:169], v[198:201], v[32:35]
	v_mfma_f32_16x16x32_bf16 v[20:23], v[158:161], v[206:209], v[20:23]
	v_mfma_f32_16x16x32_bf16 v[16:19], v[166:169], v[206:209], v[16:19]
	v_mfma_f32_16x16x32_bf16 v[4:7], v[158:161], v[214:217], v[4:7]
	v_mfma_f32_16x16x32_bf16 v[0:3], v[166:169], v[214:217], v[0:3]
	v_mfma_f32_16x16x32_bf16 v[60:63], v[170:173], v[186:189], v[60:63]
	v_mfma_f32_16x16x32_bf16 v[56:59], v[178:181], v[186:189], v[56:59]
	v_mfma_f32_16x16x32_bf16 v[44:47], v[170:173], v[194:197], v[44:47]
	v_mfma_f32_16x16x32_bf16 v[40:43], v[178:181], v[194:197], v[40:43]
	v_mfma_f32_16x16x32_bf16 v[28:31], v[170:173], v[202:205], v[28:31]
	v_mfma_f32_16x16x32_bf16 v[24:27], v[178:181], v[202:205], v[24:27]
	v_mfma_f32_16x16x32_bf16 v[12:15], v[170:173], v[210:213], v[12:15]
	v_mfma_f32_16x16x32_bf16 v[8:11], v[178:181], v[210:213], v[8:11]
	v_mfma_f32_16x16x32_bf16 v[60:63], v[174:177], v[190:193], v[60:63]
	v_mfma_f32_16x16x32_bf16 v[56:59], v[182:185], v[190:193], v[56:59]
	v_mfma_f32_16x16x32_bf16 v[44:47], v[174:177], v[198:201], v[44:47]
	v_mfma_f32_16x16x32_bf16 v[40:43], v[182:185], v[198:201], v[40:43]
	v_mfma_f32_16x16x32_bf16 v[28:31], v[174:177], v[206:209], v[28:31]
	v_mfma_f32_16x16x32_bf16 v[24:27], v[182:185], v[206:209], v[24:27]
	v_mfma_f32_16x16x32_bf16 v[12:15], v[174:177], v[214:217], v[12:15]
	v_mfma_f32_16x16x32_bf16 v[8:11], v[182:185], v[214:217], v[8:11]
	s_barrier
; #define PG8_STAGE(bufoff, gbase, voff) do { _Pragma("unroll") for (int _i = 0; _i < 2; ++_i) \
;         __builtin_amdgcn_global_load_lds((const unsigned*)((const char*)(gbase) + (voff)[_i]), (PG8_LAS unsigned*)(lds + (bufoff) + ldsw + _i * 8192), 16, 0, 0); } while (0)
; #define PG8_LDA(dst, b, h) do { _Pragma("unroll") for (int m = 0; m < 4; ++m) _Pragma("unroll") for (int k = 0; k < 2; ++k) dst[m][k] = *(const PG8_LAS bf16x8*)(lds + PG8_SA(b, h) + aoff + m * 2048 + k * 1024); } while (0)
; #define PG8_LDB(dst, b, h) do { _Pragma("unroll") for (int n = 0; n < 2; ++n) _Pragma("unroll") for (int k = 0; k < 2; ++k) dst[n][k] = *(const PG8_LAS bf16x8*)(lds + PG8_SB(b, h) + boff + n * 2048 + k * 1024); } while (0)
; #define PG8_MMA(ai, bj, At, Bt) do { __builtin_amdgcn_s_setprio(1); _Pragma("unroll") for (int m = 0; m < 4; ++m) _Pragma("unroll") for (int n = 0; n < 2; ++n) _Pragma("unroll") for (int k = 0; k < 2; ++k) \
;         acc[ai][bj][m][n] = __builtin_amdgcn_mfma_f32_16x16x32_bf16(Bt[n][k], At[m][k], acc[ai][bj][m][n], 0, 0, 0); __builtin_amdgcn_s_setprio(0); } while (0)
; #define PG8_WAIT_V(n) asm volatile("s_waitcnt vmcnt(" #n ")" ::: "memory")
; #define PG8_WAIT_L(n) asm volatile("s_waitcnt lgkmcnt(" #n ")" ::: "memory")
; #define PG8_BAR __builtin_amdgcn_s_barrier()
; #define PG8_SCHED __builtin_amdgcn_sched_barrier(0)
; template <class Epi, class Sched, bool ALIGN_EPI = false, bool SP2 = false>
; __device__ __forceinline__ void gemm_phase(PG8_LAS unsigned char* lds, const Gemm g, const Sched& S, const Epi& E) {
;     ...
;             PG8_LDB(B0, 1, 0); PG8_LDB(B1, 1, 1); PG8_SCHED; PG8_LDA(At, 1, 0); PG8_STAGE(PG8_SA(0, 1), a2 + hstep, voffA);
;             PG8_WAIT_V(8); PG8_WAIT_L(0); PG8_BAR; PG8_MMA(0, 0, At, B0); PG8_MMA(0, 1, At, B1); PG8_BAR; PG8_SCHED;
;             PG8_LDA(At, 1, 1); PG8_STAGE(PG8_SB(1, 0), b3, voffB); PG8_STAGE(PG8_SB(1, 1), b3 + hstep, voffB); PG8_STAGE(PG8_SA(1, 0), a3, voffA);
;             PG8_WAIT_V(8); PG8_WAIT_L(0); PG8_BAR; PG8_MMA(1, 0, At, B0); PG8_MMA(1, 1, At, B1); PG8_BAR; PG8_SCHED;
;     ...
;         if constexpr (ALIGN_EPI) { if (wr == 0) PG8_BAR; }
	s_add_i32 s56, 0, 0x18000
	v_add_u32_e32 v153, s56, v147
	s_add_i32 s57, 0, 0x1c000
	ds_read_b128 v[154:157], v153
	ds_read_b128 v[158:161], v153 offset:1024
	ds_read_b128 v[162:165], v153 offset:2048
	ds_read_b128 v[166:169], v153 offset:3072
	v_add_u32_e32 v153, s57, v147
	ds_read_b128 v[170:173], v153
	ds_read_b128 v[174:177], v153 offset:1024
	ds_read_b128 v[178:181], v153 offset:2048
	ds_read_b128 v[182:185], v153 offset:3072
	s_add_u32 s26, s26, 0x40000
	s_addc_u32 s27, s27, 0
	s_mov_b32 m0, s34
	ds_read_b128 v[186:189], v151 offset:32768
	ds_read_b128 v[190:193], v151 offset:33792
	ds_read_b128 v[194:197], v151 offset:34816
	ds_read_b128 v[198:201], v151 offset:35840
	ds_read_b128 v[202:205], v151 offset:36864
	ds_read_b128 v[206:209], v151 offset:37888
	ds_read_b128 v[210:213], v151 offset:38912
	ds_read_b128 v[214:217], v151 offset:39936
	global_load_lds_dwordx4 v134, s[26:27]
	s_mov_b32 m0, s35
	s_nop 0
	global_load_lds_dwordx4 v130, s[26:27]
	s_waitcnt vmcnt(8)
	s_waitcnt lgkmcnt(0)
	s_barrier
	s_waitcnt lgkmcnt(0)
	v_mfma_f32_16x16x32_bf16 v[116:119], v[154:157], v[186:189], v[116:119]
	v_mfma_f32_16x16x32_bf16 v[112:115], v[162:165], v[186:189], v[112:115]
	v_mfma_f32_16x16x32_bf16 v[100:103], v[154:157], v[194:197], v[100:103]
	v_mfma_f32_16x16x32_bf16 v[96:99], v[162:165], v[194:197], v[96:99]
	v_mfma_f32_16x16x32_bf16 v[84:87], v[154:157], v[202:205], v[84:87]
	v_mfma_f32_16x16x32_bf16 v[80:83], v[162:165], v[202:205], v[80:83]
	v_mfma_f32_16x16x32_bf16 v[68:71], v[154:157], v[210:213], v[68:71]
	v_mfma_f32_16x16x32_bf16 v[64:67], v[162:165], v[210:213], v[64:67]
	v_mfma_f32_16x16x32_bf16 v[116:119], v[158:161], v[190:193], v[116:119]
	v_mfma_f32_16x16x32_bf16 v[112:115], v[166:169], v[190:193], v[112:115]
	v_mfma_f32_16x16x32_bf16 v[100:103], v[158:161], v[198:201], v[100:103]
	v_mfma_f32_16x16x32_bf16 v[96:99], v[166:169], v[198:201], v[96:99]
	v_mfma_f32_16x16x32_bf16 v[84:87], v[158:161], v[206:209], v[84:87]
	v_mfma_f32_16x16x32_bf16 v[80:83], v[166:169], v[206:209], v[80:83]
	v_mfma_f32_16x16x32_bf16 v[68:71], v[158:161], v[214:217], v[68:71]
	v_mfma_f32_16x16x32_bf16 v[64:67], v[166:169], v[214:217], v[64:67]
	v_mfma_f32_16x16x32_bf16 v[124:127], v[170:173], v[186:189], v[124:127]
	v_mfma_f32_16x16x32_bf16 v[120:123], v[178:181], v[186:189], v[120:123]
	v_mfma_f32_16x16x32_bf16 v[108:111], v[170:173], v[194:197], v[108:111]
	v_mfma_f32_16x16x32_bf16 v[104:107], v[178:181], v[194:197], v[104:107]
	v_mfma_f32_16x16x32_bf16 v[92:95], v[170:173], v[202:205], v[92:95]
	v_mfma_f32_16x16x32_bf16 v[88:91], v[178:181], v[202:205], v[88:91]
	v_mfma_f32_16x16x32_bf16 v[76:79], v[170:173], v[210:213], v[76:79]
	v_mfma_f32_16x16x32_bf16 v[72:75], v[178:181], v[210:213], v[72:75]
	v_mfma_f32_16x16x32_bf16 v[124:127], v[174:177], v[190:193], v[124:127]
	v_mfma_f32_16x16x32_bf16 v[120:123], v[182:185], v[190:193], v[120:123]
	v_mfma_f32_16x16x32_bf16 v[108:111], v[174:177], v[198:201], v[108:111]
	v_mfma_f32_16x16x32_bf16 v[104:107], v[182:185], v[198:201], v[104:107]
	v_mfma_f32_16x16x32_bf16 v[92:95], v[174:177], v[206:209], v[92:95]
	v_mfma_f32_16x16x32_bf16 v[88:91], v[182:185], v[206:209], v[88:91]
	v_mfma_f32_16x16x32_bf16 v[76:79], v[174:177], v[214:217], v[76:79]
	v_mfma_f32_16x16x32_bf16 v[72:75], v[182:185], v[214:217], v[72:75]
	s_barrier
	s_add_i32 s26, s56, s29
	v_lshl_add_u64 v[144:145], v[144:145], 0, s[10:11]
	s_mov_b32 m0, s26
	ds_read_b128 v[186:189], v151 offset:49152
	ds_read_b128 v[190:193], v151 offset:50176
	ds_read_b128 v[194:197], v151 offset:51200
	ds_read_b128 v[198:201], v151 offset:52224
	ds_read_b128 v[202:205], v151 offset:53248
	ds_read_b128 v[206:209], v151 offset:54272
	ds_read_b128 v[210:213], v151 offset:55296
	ds_read_b128 v[214:217], v151 offset:56320
	global_load_lds_dwordx4 v[144:145], off
	s_add_i32 m0, s26, 0x2000
	s_add_u32 s6, s6, 0x40080
	v_lshl_add_u64 v[144:145], v[218:219], 0, s[10:11]
	s_addc_u32 s7, s7, 0
	s_add_i32 s26, s57, s29
	global_load_lds_dwordx4 v[144:145], off
	s_mov_b32 m0, s26
	s_nop 0
	global_load_lds_dwordx4 v132, s[6:7]
	s_add_i32 m0, s26, 0x2000
	s_nop 0
	global_load_lds_dwordx4 v128, s[6:7]
	v_lshl_add_u64 v[144:145], v[222:223], 0, s[10:11]
	s_mov_b32 m0, s37
	s_nop 0
	global_load_lds_dwordx4 v[144:145], off
	v_lshl_add_u64 v[144:145], v[224:225], 0, s[10:11]
	s_mov_b32 m0, s44
	s_nop 0
	global_load_lds_dwordx4 v[144:145], off
	s_waitcnt vmcnt(8)
	s_waitcnt lgkmcnt(0)
	s_barrier
	s_waitcnt lgkmcnt(0)
	v_mfma_f32_16x16x32_bf16 v[52:55], v[154:157], v[186:189], v[52:55]
	v_mfma_f32_16x16x32_bf16 v[48:51], v[162:165], v[186:189], v[48:51]
	v_mfma_f32_16x16x32_bf16 v[36:39], v[154:157], v[194:197], v[36:39]
	v_mfma_f32_16x16x32_bf16 v[32:35], v[162:165], v[194:197], v[32:35]
	v_mfma_f32_16x16x32_bf16 v[20:23], v[154:157], v[202:205], v[20:23]
	v_mfma_f32_16x16x32_bf16 v[16:19], v[162:165], v[202:205], v[16:19]
	v_mfma_f32_16x16x32_bf16 v[4:7], v[154:157], v[210:213], v[4:7]
	v_mfma_f32_16x16x32_bf16 v[0:3], v[162:165], v[210:213], v[0:3]
	v_mfma_f32_16x16x32_bf16 v[52:55], v[158:161], v[190:193], v[52:55]
	v_mfma_f32_16x16x32_bf16 v[48:51], v[166:169], v[190:193], v[48:51]
	v_mfma_f32_16x16x32_bf16 v[36:39], v[158:161], v[198:201], v[36:39]
	v_mfma_f32_16x16x32_bf16 v[32:35], v[166:169], v[198:201], v[32:35]
	v_mfma_f32_16x16x32_bf16 v[20:23], v[158:161], v[206:209], v[20:23]
	v_mfma_f32_16x16x32_bf16 v[16:19], v[166:169], v[206:209], v[16:19]
	v_mfma_f32_16x16x32_bf16 v[4:7], v[158:161], v[214:217], v[4:7]
	v_mfma_f32_16x16x32_bf16 v[0:3], v[166:169], v[214:217], v[0:3]
	v_mfma_f32_16x16x32_bf16 v[60:63], v[170:173], v[186:189], v[60:63]
	v_mfma_f32_16x16x32_bf16 v[56:59], v[178:181], v[186:189], v[56:59]
	v_mfma_f32_16x16x32_bf16 v[44:47], v[170:173], v[194:197], v[44:47]
	v_mfma_f32_16x16x32_bf16 v[40:43], v[178:181], v[194:197], v[40:43]
	v_mfma_f32_16x16x32_bf16 v[28:31], v[170:173], v[202:205], v[28:31]
	v_mfma_f32_16x16x32_bf16 v[24:27], v[178:181], v[202:205], v[24:27]
	v_mfma_f32_16x16x32_bf16 v[12:15], v[170:173], v[210:213], v[12:15]
	v_mfma_f32_16x16x32_bf16 v[8:11], v[178:181], v[210:213], v[8:11]
	v_mfma_f32_16x16x32_bf16 v[60:63], v[174:177], v[190:193], v[60:63]
	v_mfma_f32_16x16x32_bf16 v[56:59], v[182:185], v[190:193], v[56:59]
	v_mfma_f32_16x16x32_bf16 v[44:47], v[174:177], v[198:201], v[44:47]
	v_mfma_f32_16x16x32_bf16 v[40:43], v[182:185], v[198:201], v[40:43]
	v_mfma_f32_16x16x32_bf16 v[28:31], v[174:177], v[206:209], v[28:31]
	v_mfma_f32_16x16x32_bf16 v[24:27], v[182:185], v[206:209], v[24:27]
	v_mfma_f32_16x16x32_bf16 v[12:15], v[174:177], v[214:217], v[12:15]
	v_mfma_f32_16x16x32_bf16 v[8:11], v[182:185], v[214:217], v[8:11]
	s_barrier
	s_add_i32 s55, s55, 2
	s_add_u32 s24, s24, 0x100
	s_addc_u32 s25, s25, 0
	s_add_u32 s53, s53, 0x100
	s_addc_u32 s54, s54, 0
	s_cmp_gt_u32 s55, 13
	s_cbranch_scc0 .LBB0_1082
	s_and_b64 vcc, exec, s[12:13]
	s_cbranch_vccz .LBB0_1085
	s_barrier

; #define PG8_STAGE(bufoff, gbase, voff) do { _Pragma("unroll") for (int _i = 0; _i < 2; ++_i) \
;         __builtin_amdgcn_global_load_lds((const unsigned*)((const char*)(gbase) + (voff)[_i]), (PG8_LAS unsigned*)(lds + (bufoff) + ldsw + _i * 8192), 16, 0, 0); } while (0)
; #define PG8_LDA(dst, b, h) do { _Pragma("unroll") for (int m = 0; m < 4; ++m) _Pragma("unroll") for (int k = 0; k < 2; ++k) dst[m][k] = *(const PG8_LAS bf16x8*)(lds + PG8_SA(b, h) + aoff + m * 2048 + k * 1024); } while (0)
; #define PG8_LDB(dst, b, h) do { _Pragma("unroll") for (int n = 0; n < 2; ++n) _Pragma("unroll") for (int k = 0; k < 2; ++k) dst[n][k] = *(const PG8_LAS bf16x8*)(lds + PG8_SB(b, h) + boff + n * 2048 + k * 1024); } while (0)
; #define PG8_MMA(ai, bj, At, Bt) do { __builtin_amdgcn_s_setprio(1); _Pragma("unroll") for (int m = 0; m < 4; ++m) _Pragma("unroll") for (int n = 0; n < 2; ++n) _Pragma("unroll") for (int k = 0; k < 2; ++k) \
;         acc[ai][bj][m][n] = __builtin_amdgcn_mfma_f32_16x16x32_bf16(Bt[n][k], At[m][k], acc[ai][bj][m][n], 0, 0, 0); __builtin_amdgcn_s_setprio(0); } while (0)
; #define PG8_WAIT_V(n) asm volatile("s_waitcnt vmcnt(" #n ")" ::: "memory")
; #define PG8_WAIT_L(n) asm volatile("s_waitcnt lgkmcnt(" #n ")" ::: "memory")
; #define PG8_BAR __builtin_amdgcn_s_barrier()
; #define PG8_SCHED __builtin_amdgcn_sched_barrier(0)
; template <class Epi, class Sched, bool ALIGN_EPI = false, bool SP2 = false>
; __device__ __forceinline__ void gemm_phase(PG8_LAS unsigned char* lds, const Gemm g, const Sched& S, const Epi& E) {
;     ...
;             PG8_LDB(B0, 0, 0); PG8_LDB(B1, 0, 1); PG8_SCHED; PG8_LDA(At, 0, 0); PG8_STAGE(PG8_SA(1, 1), a1 + hstep, voffA);
;             PG8_WAIT_V(8); PG8_WAIT_L(0); PG8_BAR; PG8_MMA(0, 0, At, B0); PG8_MMA(0, 1, At, B1); PG8_BAR; PG8_SCHED;
;             PG8_LDA(At, 0, 1); PG8_STAGE(PG8_SB(0, 0), b2, voffB); PG8_STAGE(PG8_SB(0, 1), b2 + hstep, voffB); PG8_STAGE(PG8_SA(0, 0), a2, voffA);
;             PG8_WAIT_V(8); PG8_WAIT_L(0); PG8_BAR; PG8_MMA(1, 0, At, B0); PG8_MMA(1, 1, At, B1); PG8_BAR; PG8_SCHED;
.LBB0_1167:
	ds_read_b128 v[128:131], v189
	ds_read_b128 v[132:135], v189 offset:1024
	ds_read_b128 v[136:139], v189 offset:2048
	ds_read_b128 v[140:143], v189 offset:3072
	ds_read_b128 v[144:147], v190
	ds_read_b128 v[148:151], v190 offset:1024
	ds_read_b128 v[168:171], v190 offset:2048
	ds_read_b128 v[172:175], v190 offset:3072
	s_add_u32 s6, s22, 0xfff50080
	s_addc_u32 s7, s23, -1
	s_cmp_eq_u32 s53, 40
	s_cselect_b32 s25, s9, s7
	s_cselect_b32 s24, s8, s6
	s_cselect_b32 s7, s21, s52
	s_cselect_b32 s6, s20, s51
	s_add_i32 m0, s28, 0xc000
	ds_read_b128 v[176:179], v191
	ds_read_b128 v[180:183], v191 offset:1024
	ds_read_b128 v[194:197], v191 offset:2048
	ds_read_b128 v[198:201], v191 offset:3072
	ds_read_b128 v[202:205], v191 offset:4096
	ds_read_b128 v[206:209], v191 offset:5120
	ds_read_b128 v[210:213], v191 offset:6144
	ds_read_b128 v[214:217], v191 offset:7168
	global_load_lds_dwordx4 v160, s[22:23]
	s_add_i32 m0, s28, 0xe000
	s_nop 0
	global_load_lds_dwordx4 v162, s[22:23]
	s_waitcnt vmcnt(8)
	s_waitcnt lgkmcnt(0)
	s_barrier
	s_waitcnt lgkmcnt(0)
	v_mfma_f32_16x16x32_bf16 v[124:127], v[128:131], v[176:179], v[124:127]
	v_mfma_f32_16x16x32_bf16 v[120:123], v[136:139], v[176:179], v[120:123]
	v_mfma_f32_16x16x32_bf16 v[108:111], v[128:131], v[194:197], v[108:111]
	v_mfma_f32_16x16x32_bf16 v[104:107], v[136:139], v[194:197], v[104:107]
	v_mfma_f32_16x16x32_bf16 v[92:95], v[128:131], v[202:205], v[92:95]
	v_mfma_f32_16x16x32_bf16 v[88:91], v[136:139], v[202:205], v[88:91]
	v_mfma_f32_16x16x32_bf16 v[76:79], v[128:131], v[210:213], v[76:79]
	v_mfma_f32_16x16x32_bf16 v[72:75], v[136:139], v[210:213], v[72:75]
	v_mfma_f32_16x16x32_bf16 v[124:127], v[132:135], v[180:183], v[124:127]
	v_mfma_f32_16x16x32_bf16 v[120:123], v[140:143], v[180:183], v[120:123]
	v_mfma_f32_16x16x32_bf16 v[108:111], v[132:135], v[198:201], v[108:111]
	v_mfma_f32_16x16x32_bf16 v[104:107], v[140:143], v[198:201], v[104:107]
	v_mfma_f32_16x16x32_bf16 v[92:95], v[132:135], v[206:209], v[92:95]
	v_mfma_f32_16x16x32_bf16 v[88:91], v[140:143], v[206:209], v[88:91]
	v_mfma_f32_16x16x32_bf16 v[76:79], v[132:135], v[214:217], v[76:79]
	v_mfma_f32_16x16x32_bf16 v[72:75], v[140:143], v[214:217], v[72:75]
	v_mfma_f32_16x16x32_bf16 v[116:119], v[144:147], v[176:179], v[116:119]
	v_mfma_f32_16x16x32_bf16 v[112:115], v[168:171], v[176:179], v[112:115]
	v_mfma_f32_16x16x32_bf16 v[100:103], v[144:147], v[194:197], v[100:103]
	v_mfma_f32_16x16x32_bf16 v[96:99], v[168:171], v[194:197], v[96:99]
	v_mfma_f32_16x16x32_bf16 v[84:87], v[144:147], v[202:205], v[84:87]
	v_mfma_f32_16x16x32_bf16 v[80:83], v[168:171], v[202:205], v[80:83]
	v_mfma_f32_16x16x32_bf16 v[68:71], v[144:147], v[210:213], v[68:71]
	v_mfma_f32_16x16x32_bf16 v[64:67], v[168:171], v[210:213], v[64:67]
	v_mfma_f32_16x16x32_bf16 v[116:119], v[148:151], v[180:183], v[116:119]
	v_mfma_f32_16x16x32_bf16 v[112:115], v[172:175], v[180:183], v[112:115]
	v_mfma_f32_16x16x32_bf16 v[100:103], v[148:151], v[198:201], v[100:103]
	v_mfma_f32_16x16x32_bf16 v[96:99], v[172:175], v[198:201], v[96:99]
	v_mfma_f32_16x16x32_bf16 v[84:87], v[148:151], v[206:209], v[84:87]
	v_mfma_f32_16x16x32_bf16 v[80:83], v[172:175], v[206:209], v[80:83]
	v_mfma_f32_16x16x32_bf16 v[68:71], v[148:151], v[214:217], v[68:71]
	v_mfma_f32_16x16x32_bf16 v[64:67], v[172:175], v[214:217], v[64:67]
	s_barrier
	s_add_i32 s54, s45, s27
	v_lshl_add_u64 v[184:185], s[6:7], 0, v[154:155]
	s_mov_b32 m0, s54
	ds_read_b128 v[176:179], v191 offset:16384
	ds_read_b128 v[180:183], v191 offset:17408
	ds_read_b128 v[194:197], v191 offset:18432
	ds_read_b128 v[198:201], v191 offset:19456
	ds_read_b128 v[202:205], v191 offset:20480
	ds_read_b128 v[206:209], v191 offset:21504
	ds_read_b128 v[210:213], v191 offset:22528
	ds_read_b128 v[214:217], v191 offset:23552
	global_load_lds_dwordx4 v[184:185], off
	s_add_i32 m0, s54, 0x2000
	s_add_u32 s54, s6, 0xb0000
	v_lshl_add_u64 v[218:219], s[6:7], 0, v[158:159]
	s_addc_u32 s55, s7, 0
	s_add_i32 s56, s46, s27
	global_load_lds_dwordx4 v[218:219], off
	s_mov_b32 m0, s56
	v_lshl_add_u64 v[224:225], s[24:25], 0, v[156:157]
	global_load_lds_dwordx4 v154, s[54:55]
	s_add_i32 m0, s56, 0x2000
	s_nop 0
	global_load_lds_dwordx4 v158, s[54:55]
	v_lshl_add_u64 v[222:223], s[24:25], 0, v[152:153]
	s_mov_b32 m0, s28
	s_nop 0
	global_load_lds_dwordx4 v[222:223], off
	s_mov_b32 m0, s29
	s_nop 0
	global_load_lds_dwordx4 v[224:225], off
	s_waitcnt vmcnt(8)
	s_waitcnt lgkmcnt(0)
	s_barrier
	s_waitcnt lgkmcnt(0)
	v_mfma_f32_16x16x32_bf16 v[60:63], v[128:131], v[176:179], v[60:63]
	v_mfma_f32_16x16x32_bf16 v[56:59], v[136:139], v[176:179], v[56:59]
	v_mfma_f32_16x16x32_bf16 v[44:47], v[128:131], v[194:197], v[44:47]
	v_mfma_f32_16x16x32_bf16 v[40:43], v[136:139], v[194:197], v[40:43]
	v_mfma_f32_16x16x32_bf16 v[28:31], v[128:131], v[202:205], v[28:31]
	v_mfma_f32_16x16x32_bf16 v[24:27], v[136:139], v[202:205], v[24:27]
	v_mfma_f32_16x16x32_bf16 v[12:15], v[128:131], v[210:213], v[12:15]
	v_mfma_f32_16x16x32_bf16 v[8:11], v[136:139], v[210:213], v[8:11]
	v_mfma_f32_16x16x32_bf16 v[60:63], v[132:135], v[180:183], v[60:63]
	v_mfma_f32_16x16x32_bf16 v[56:59], v[140:143], v[180:183], v[56:59]
	v_mfma_f32_16x16x32_bf16 v[44:47], v[132:135], v[198:201], v[44:47]
	v_mfma_f32_16x16x32_bf16 v[40:43], v[140:143], v[198:201], v[40:43]
	v_mfma_f32_16x16x32_bf16 v[28:31], v[132:135], v[206:209], v[28:31]
	v_mfma_f32_16x16x32_bf16 v[24:27], v[140:143], v[206:209], v[24:27]
	v_mfma_f32_16x16x32_bf16 v[12:15], v[132:135], v[214:217], v[12:15]
	v_mfma_f32_16x16x32_bf16 v[8:11], v[140:143], v[214:217], v[8:11]
	v_mfma_f32_16x16x32_bf16 v[52:55], v[144:147], v[176:179], v[52:55]
	v_mfma_f32_16x16x32_bf16 v[48:51], v[168:171], v[176:179], v[48:51]
	v_mfma_f32_16x16x32_bf16 v[36:39], v[144:147], v[194:197], v[36:39]
	v_mfma_f32_16x16x32_bf16 v[32:35], v[168:171], v[194:197], v[32:35]
	v_mfma_f32_16x16x32_bf16 v[20:23], v[144:147], v[202:205], v[20:23]
	v_mfma_f32_16x16x32_bf16 v[16:19], v[168:171], v[202:205], v[16:19]
	v_mfma_f32_16x16x32_bf16 v[4:7], v[144:147], v[210:213], v[4:7]
	v_mfma_f32_16x16x32_bf16 v[0:3], v[168:171], v[210:213], v[0:3]
	v_mfma_f32_16x16x32_bf16 v[52:55], v[148:151], v[180:183], v[52:55]
	v_mfma_f32_16x16x32_bf16 v[48:51], v[172:175], v[180:183], v[48:51]
	v_mfma_f32_16x16x32_bf16 v[36:39], v[148:151], v[198:201], v[36:39]
	v_mfma_f32_16x16x32_bf16 v[32:35], v[172:175], v[198:201], v[32:35]
	v_mfma_f32_16x16x32_bf16 v[20:23], v[148:151], v[206:209], v[20:23]
	v_mfma_f32_16x16x32_bf16 v[16:19], v[172:175], v[206:209], v[16:19]
	v_mfma_f32_16x16x32_bf16 v[4:7], v[148:151], v[214:217], v[4:7]
	v_mfma_f32_16x16x32_bf16 v[0:3], v[172:175], v[214:217], v[0:3]
	s_barrier
; #define PG8_STAGE(bufoff, gbase, voff) do { _Pragma("unroll") for (int _i = 0; _i < 2; ++_i) \
;         __builtin_amdgcn_global_load_lds((const unsigned*)((const char*)(gbase) + (voff)[_i]), (PG8_LAS unsigned*)(lds + (bufoff) + ldsw + _i * 8192), 16, 0, 0); } while (0)
; #define PG8_LDA(dst, b, h) do { _Pragma("unroll") for (int m = 0; m < 4; ++m) _Pragma("unroll") for (int k = 0; k < 2; ++k) dst[m][k] = *(const PG8_LAS bf16x8*)(lds + PG8_SA(b, h) + aoff + m * 2048 + k * 1024); } while (0)
; #define PG8_LDB(dst, b, h) do { _Pragma("unroll") for (int n = 0; n < 2; ++n) _Pragma("unroll") for (int k = 0; k < 2; ++k) dst[n][k] = *(const PG8_LAS bf16x8*)(lds + PG8_SB(b, h) + boff + n * 2048 + k * 1024); } while (0)
; #define PG8_MMA(ai, bj, At, Bt) do { __builtin_amdgcn_s_setprio(1); _Pragma("unroll") for (int m = 0; m < 4; ++m) _Pragma("unroll") for (int n = 0; n < 2; ++n) _Pragma("unroll") for (int k = 0; k < 2; ++k) \
;         acc[ai][bj][m][n] = __builtin_amdgcn_mfma_f32_16x16x32_bf16(Bt[n][k], At[m][k], acc[ai][bj][m][n], 0, 0, 0); __builtin_amdgcn_s_setprio(0); } while (0)
; #define PG8_WAIT_V(n) asm volatile("s_waitcnt vmcnt(" #n ")" ::: "memory")
; #define PG8_WAIT_L(n) asm volatile("s_waitcnt lgkmcnt(" #n ")" ::: "memory")
; #define PG8_BAR __builtin_amdgcn_s_barrier()
; #define PG8_SCHED __builtin_amdgcn_sched_barrier(0)
; template <class Epi, class Sched, bool ALIGN_EPI = false, bool SP2 = false>
; __device__ __forceinline__ void gemm_phase(PG8_LAS unsigned char* lds, const Gemm g, const Sched& S, const Epi& E) {
;     ...
;             PG8_LDB(B0, 1, 0); PG8_LDB(B1, 1, 1); PG8_SCHED; PG8_LDA(At, 1, 0); PG8_STAGE(PG8_SA(0, 1), a2 + hstep, voffA);
;             PG8_WAIT_V(8); PG8_WAIT_L(0); PG8_BAR; PG8_MMA(0, 0, At, B0); PG8_MMA(0, 1, At, B1); PG8_BAR; PG8_SCHED;
;             PG8_LDA(At, 1, 1); PG8_STAGE(PG8_SB(1, 0), b3, voffB); PG8_STAGE(PG8_SB(1, 1), b3 + hstep, voffB); PG8_STAGE(PG8_SA(1, 0), a3, voffA);
;             PG8_WAIT_V(8); PG8_WAIT_L(0); PG8_BAR; PG8_MMA(1, 0, At, B0); PG8_MMA(1, 1, At, B1); PG8_BAR; PG8_SCHED;
;     ...
;         if constexpr (ALIGN_EPI) { if (wr == 0) PG8_BAR; }
	s_add_i32 s54, 0, 0x18000
	s_add_i32 s55, 0, 0x1c000
	v_add_u32_e32 v140, s54, v187
	v_add_u32_e32 v172, s55, v187
	ds_read_b128 v[128:131], v140
	ds_read_b128 v[132:135], v140 offset:1024
	ds_read_b128 v[136:139], v140 offset:2048
	ds_read_b128 v[140:143], v140 offset:3072
	ds_read_b128 v[144:147], v172
	ds_read_b128 v[148:151], v172 offset:1024
	ds_read_b128 v[168:171], v172 offset:2048
	ds_read_b128 v[172:175], v172 offset:3072
	s_add_u32 s24, s24, 0xb0000
	s_addc_u32 s25, s25, 0
	s_mov_b32 m0, s30
	ds_read_b128 v[176:179], v191 offset:32768
	ds_read_b128 v[180:183], v191 offset:33792
	ds_read_b128 v[194:197], v191 offset:34816
	ds_read_b128 v[198:201], v191 offset:35840
	ds_read_b128 v[202:205], v191 offset:36864
	ds_read_b128 v[206:209], v191 offset:37888
	ds_read_b128 v[210:213], v191 offset:38912
	ds_read_b128 v[214:217], v191 offset:39936
	global_load_lds_dwordx4 v152, s[24:25]
	s_mov_b32 m0, s31
	s_nop 0
	global_load_lds_dwordx4 v156, s[24:25]
	s_waitcnt vmcnt(8)
	s_waitcnt lgkmcnt(0)
	s_barrier
	s_waitcnt lgkmcnt(0)
	v_mfma_f32_16x16x32_bf16 v[124:127], v[128:131], v[176:179], v[124:127]
	v_mfma_f32_16x16x32_bf16 v[120:123], v[136:139], v[176:179], v[120:123]
	v_mfma_f32_16x16x32_bf16 v[108:111], v[128:131], v[194:197], v[108:111]
	v_mfma_f32_16x16x32_bf16 v[104:107], v[136:139], v[194:197], v[104:107]
	v_mfma_f32_16x16x32_bf16 v[92:95], v[128:131], v[202:205], v[92:95]
	v_mfma_f32_16x16x32_bf16 v[88:91], v[136:139], v[202:205], v[88:91]
	v_mfma_f32_16x16x32_bf16 v[76:79], v[128:131], v[210:213], v[76:79]
	v_mfma_f32_16x16x32_bf16 v[72:75], v[136:139], v[210:213], v[72:75]
	v_mfma_f32_16x16x32_bf16 v[124:127], v[132:135], v[180:183], v[124:127]
	v_mfma_f32_16x16x32_bf16 v[120:123], v[140:143], v[180:183], v[120:123]
	v_mfma_f32_16x16x32_bf16 v[108:111], v[132:135], v[198:201], v[108:111]
	v_mfma_f32_16x16x32_bf16 v[104:107], v[140:143], v[198:201], v[104:107]
	v_mfma_f32_16x16x32_bf16 v[92:95], v[132:135], v[206:209], v[92:95]
	v_mfma_f32_16x16x32_bf16 v[88:91], v[140:143], v[206:209], v[88:91]
	v_mfma_f32_16x16x32_bf16 v[76:79], v[132:135], v[214:217], v[76:79]
	v_mfma_f32_16x16x32_bf16 v[72:75], v[140:143], v[214:217], v[72:75]
	v_mfma_f32_16x16x32_bf16 v[116:119], v[144:147], v[176:179], v[116:119]
	v_mfma_f32_16x16x32_bf16 v[112:115], v[168:171], v[176:179], v[112:115]
	v_mfma_f32_16x16x32_bf16 v[100:103], v[144:147], v[194:197], v[100:103]
	v_mfma_f32_16x16x32_bf16 v[96:99], v[168:171], v[194:197], v[96:99]
	v_mfma_f32_16x16x32_bf16 v[84:87], v[144:147], v[202:205], v[84:87]
	v_mfma_f32_16x16x32_bf16 v[80:83], v[168:171], v[202:205], v[80:83]
	v_mfma_f32_16x16x32_bf16 v[68:71], v[144:147], v[210:213], v[68:71]
	v_mfma_f32_16x16x32_bf16 v[64:67], v[168:171], v[210:213], v[64:67]
	v_mfma_f32_16x16x32_bf16 v[116:119], v[148:151], v[180:183], v[116:119]
	v_mfma_f32_16x16x32_bf16 v[112:115], v[172:175], v[180:183], v[112:115]
	v_mfma_f32_16x16x32_bf16 v[100:103], v[148:151], v[198:201], v[100:103]
	v_mfma_f32_16x16x32_bf16 v[96:99], v[172:175], v[198:201], v[96:99]
	v_mfma_f32_16x16x32_bf16 v[84:87], v[148:151], v[206:209], v[84:87]
	v_mfma_f32_16x16x32_bf16 v[80:83], v[172:175], v[206:209], v[80:83]
	v_mfma_f32_16x16x32_bf16 v[68:71], v[148:151], v[214:217], v[68:71]
	v_mfma_f32_16x16x32_bf16 v[64:67], v[172:175], v[214:217], v[64:67]
	s_barrier
	s_add_i32 s24, s54, s27
	v_lshl_add_u64 v[184:185], v[184:185], 0, s[16:17]
	s_mov_b32 m0, s24
	ds_read_b128 v[176:179], v191 offset:49152
	ds_read_b128 v[180:183], v191 offset:50176
	ds_read_b128 v[194:197], v191 offset:51200
	ds_read_b128 v[198:201], v191 offset:52224
	ds_read_b128 v[202:205], v191 offset:53248
	ds_read_b128 v[206:209], v191 offset:54272
	ds_read_b128 v[210:213], v191 offset:55296
	ds_read_b128 v[214:217], v191 offset:56320
	global_load_lds_dwordx4 v[184:185], off
	s_add_i32 m0, s24, 0x2000
	s_add_u32 s6, s6, 0xb0080
	v_lshl_add_u64 v[184:185], v[218:219], 0, s[16:17]
	s_addc_u32 s7, s7, 0
	s_add_i32 s24, s55, s27
	global_load_lds_dwordx4 v[184:185], off
	s_mov_b32 m0, s24
	s_nop 0
	global_load_lds_dwordx4 v154, s[6:7]
	s_add_i32 m0, s24, 0x2000
	s_nop 0
	global_load_lds_dwordx4 v158, s[6:7]
	v_lshl_add_u64 v[184:185], v[222:223], 0, s[16:17]
	s_mov_b32 m0, s34
	s_nop 0
	global_load_lds_dwordx4 v[184:185], off
	v_lshl_add_u64 v[184:185], v[224:225], 0, s[16:17]
	s_mov_b32 m0, s35
	s_nop 0
	global_load_lds_dwordx4 v[184:185], off
	s_waitcnt vmcnt(8)
	s_waitcnt lgkmcnt(0)
	s_barrier
	s_waitcnt lgkmcnt(0)
	v_mfma_f32_16x16x32_bf16 v[60:63], v[128:131], v[176:179], v[60:63]
	v_mfma_f32_16x16x32_bf16 v[56:59], v[136:139], v[176:179], v[56:59]
	v_mfma_f32_16x16x32_bf16 v[44:47], v[128:131], v[194:197], v[44:47]
	v_mfma_f32_16x16x32_bf16 v[40:43], v[136:139], v[194:197], v[40:43]
	v_mfma_f32_16x16x32_bf16 v[28:31], v[128:131], v[202:205], v[28:31]
	v_mfma_f32_16x16x32_bf16 v[24:27], v[136:139], v[202:205], v[24:27]
	v_mfma_f32_16x16x32_bf16 v[12:15], v[128:131], v[210:213], v[12:15]
	v_mfma_f32_16x16x32_bf16 v[8:11], v[136:139], v[210:213], v[8:11]
	v_mfma_f32_16x16x32_bf16 v[60:63], v[132:135], v[180:183], v[60:63]
	v_mfma_f32_16x16x32_bf16 v[56:59], v[140:143], v[180:183], v[56:59]
	v_mfma_f32_16x16x32_bf16 v[44:47], v[132:135], v[198:201], v[44:47]
	v_mfma_f32_16x16x32_bf16 v[40:43], v[140:143], v[198:201], v[40:43]
	v_mfma_f32_16x16x32_bf16 v[28:31], v[132:135], v[206:209], v[28:31]
	v_mfma_f32_16x16x32_bf16 v[24:27], v[140:143], v[206:209], v[24:27]
	v_mfma_f32_16x16x32_bf16 v[12:15], v[132:135], v[214:217], v[12:15]
	v_mfma_f32_16x16x32_bf16 v[8:11], v[140:143], v[214:217], v[8:11]
	v_mfma_f32_16x16x32_bf16 v[52:55], v[144:147], v[176:179], v[52:55]
	v_mfma_f32_16x16x32_bf16 v[48:51], v[168:171], v[176:179], v[48:51]
	v_mfma_f32_16x16x32_bf16 v[36:39], v[144:147], v[194:197], v[36:39]
	v_mfma_f32_16x16x32_bf16 v[32:35], v[168:171], v[194:197], v[32:35]
	v_mfma_f32_16x16x32_bf16 v[20:23], v[144:147], v[202:205], v[20:23]
	v_mfma_f32_16x16x32_bf16 v[16:19], v[168:171], v[202:205], v[16:19]
	v_mfma_f32_16x16x32_bf16 v[4:7], v[144:147], v[210:213], v[4:7]
	v_mfma_f32_16x16x32_bf16 v[0:3], v[168:171], v[210:213], v[0:3]
	v_mfma_f32_16x16x32_bf16 v[52:55], v[148:151], v[180:183], v[52:55]
	v_mfma_f32_16x16x32_bf16 v[48:51], v[172:175], v[180:183], v[48:51]
	v_mfma_f32_16x16x32_bf16 v[36:39], v[148:151], v[198:201], v[36:39]
	v_mfma_f32_16x16x32_bf16 v[32:35], v[172:175], v[198:201], v[32:35]
	v_mfma_f32_16x16x32_bf16 v[20:23], v[148:151], v[206:209], v[20:23]
	v_mfma_f32_16x16x32_bf16 v[16:19], v[172:175], v[206:209], v[16:19]
	v_mfma_f32_16x16x32_bf16 v[4:7], v[148:151], v[214:217], v[4:7]
	v_mfma_f32_16x16x32_bf16 v[0:3], v[172:175], v[214:217], v[0:3]
	s_barrier
	s_add_i32 s53, s53, 2
	s_add_u32 s22, s22, 0x100
	s_addc_u32 s23, s23, 0
	s_add_u32 s51, s51, 0x100
	s_addc_u32 s52, s52, 0
	s_cmp_gt_u32 s53, 41
	s_cbranch_scc0 .LBB0_1167
	s_and_b64 vcc, exec, s[18:19]
	s_cbranch_vccz .LBB0_1170
	s_barrier
